# LayerNorm row statistics: ds_bpermute cross-lane sums replaced by v_permlane16_swap/v_permlane32_swap + add (96 steps in the three fused LN epilogues)
# speedup vs baseline: 1.0074x; 1.0023x over previous
;     __device__ __forceinline__ void fused(f32x4 (&acc)[2][2][4][2], const Unit& u, int wr, int wc, int fr, int fq, PG8_LAS unsigned char* lds, int wid, int lane) const {
;     ...
;         const int col0 = u.pn * BM + wc * 32 + 8 * fq;
; #pragma unroll
;         for (int ai = 0; ai < 2; ++ai)
; #pragma unroll
;             for (int m = 0; m < 4; ++m) { const size_t off = (size_t)(u.pm * BM + ai * HALF + wr * 64 + m * 16 + fr) * ldc + col0;
; #pragma unroll
;                 for (int bj = 0; bj < 2; ++bj) { f32x4 b0, b1;
;                     if (base) { b0 = *(const f32x4*)(base + off + bj * HALF); b1 = *(const f32x4*)(base + off + bj * HALF + 4); }
;                     else { const u32x4 w = *(const u32x4*)(baseb + off + bj * HALF);
;                         b0 = (f32x4){__uint_as_float(w.x << 16), __uint_as_float(w.x & 0xffff0000u), __uint_as_float(w.y << 16), __uint_as_float(w.y & 0xffff0000u)};
;                         b1 = (f32x4){__uint_as_float(w.z << 16), __uint_as_float(w.z & 0xffff0000u), __uint_as_float(w.w << 16), __uint_as_float(w.w & 0xffff0000u)}; }
;                     acc[ai][bj][m][0] = acc[ai][bj][m][0] * s + b0 * alpha; acc[ai][bj][m][1] = acc[ai][bj][m][1] * s + b1 * alpha; }
;                 asm volatile("" : "+v"(acc[ai][0][m][0]), "+v"(acc[ai][0][m][1]), "+v"(acc[ai][1][m][0]), "+v"(acc[ai][1][m][1]));
;                 if (m == 3) asm volatile("" ::: "memory"); }
.LBB0_194:
	s_lshl_b32 s0, s27, 5
	s_lshl_b32 s1, s60, 8
	v_lshrrev_b32_e32 v132, 1, v2
	s_or_b32 s0, s1, s0
	s_lshl_b32 s16, s25, 8
	v_and_or_b32 v164, v132, 24, s0
	s_add_i32 s0, s16, s36
	v_or_b32_e32 v134, s0, v152
	v_readlane_b32 s0, v245, 5
	v_readlane_b32 s4, v245, 9
	v_readlane_b32 s5, v245, 10
	v_readlane_b32 s6, v245, 11
	v_readlane_b32 s7, v245, 12
	v_readlane_b32 s8, v245, 13
	v_readlane_b32 s9, v245, 14
	v_readlane_b32 s10, v245, 15
	v_readlane_b32 s11, v245, 16
	v_readlane_b32 s12, v245, 17
	v_readlane_b32 s13, v245, 18
	v_readlane_b32 s14, v245, 19
	v_readlane_b32 s15, v245, 20
	v_ashrrev_i32_e32 v135, 31, v134
	v_readlane_b32 s1, v245, 6
	v_readlane_b32 s2, v245, 7
	v_readlane_b32 s3, v245, 8
	s_mov_b64 s[14:15], s[10:11]
	v_ashrrev_i32_e32 v165, 31, v164
	v_lshlrev_b64 v[132:133], 12, v[134:135]
	s_mov_b64 s[12:13], s[8:9]
	s_mov_b64 s[10:11], s[6:7]
	s_mov_b64 s[8:9], s[4:5]
	s_mov_b64 s[6:7], s[2:3]
	s_mov_b64 s[4:5], s[0:1]
	v_lshl_add_u64 v[136:137], s[4:5], 0, v[132:133]
	v_lshlrev_b64 v[132:133], 2, v[164:165]
	v_lshl_add_u64 v[148:149], v[136:137], 0, v[132:133]
	s_barrier
	s_nop 1
	v_subrev_u32_e32 v242, s4, v148
	global_load_dwordx4 v[176:179], v242, s[4:5]
	global_load_dwordx4 v[180:183], v242, s[4:5] offset:16
	global_load_dwordx4 v[184:187], v242, s[4:5] offset:512
	global_load_dwordx4 v[188:191], v242, s[4:5] offset:528
	s_add_u32 s100, s4, 0x10000
	s_addc_u32 s101, s5, 0
	global_load_dwordx4 v[192:195], v242, s[100:101]
	global_load_dwordx4 v[198:201], v242, s[100:101] offset:16
	global_load_dwordx4 v[202:205], v242, s[100:101] offset:512
	global_load_dwordx4 v[206:209], v242, s[100:101] offset:528
	s_add_u32 s98, s4, 0x20000
	s_addc_u32 s99, s5, 0
	global_load_dwordx4 v[210:213], v242, s[98:99]
	global_load_dwordx4 v[214:217], v242, s[98:99] offset:16
	global_load_dwordx4 v[218:221], v242, s[98:99] offset:512
	global_load_dwordx4 v[222:225], v242, s[98:99] offset:528
	s_add_u32 s100, s4, 0x30000
	s_addc_u32 s101, s5, 0
	global_load_dwordx4 v[226:229], v242, s[100:101]
	global_load_dwordx4 v[230:233], v242, s[100:101] offset:16
	global_load_dwordx4 v[246:249], v242, s[100:101] offset:512
	global_load_dwordx4 v[250:253], v242, s[100:101] offset:528
	s_nop 0
	v_or_b32_e32 v154, 16, v134
	v_ashrrev_i32_e32 v155, 31, v154
	s_mov_b32 s0, 0x3f9837f0
	v_lshlrev_b64 v[154:155], 12, v[154:155]
	v_lshl_add_u64 v[154:155], s[4:5], 0, v[154:155]
	v_lshl_add_u64 v[154:155], v[154:155], 0, v[132:133]
	v_mbcnt_lo_u32_b32 v135, -1, 0
	v_mbcnt_hi_u32_b32 v153, -1, v135
	v_and_b32_e32 v135, 64, v153
	v_add_u32_e32 v174, 64, v135
	s_waitcnt vmcnt(12)
	v_pk_mul_f32 v[138:139], v[178:179], s[0:1] op_sel_hi:[1,0]
	v_pk_mul_f32 v[136:137], v[176:177], s[0:1] op_sel_hi:[1,0]
	v_pk_mul_f32 v[142:143], v[182:183], s[0:1] op_sel_hi:[1,0]
	v_pk_mul_f32 v[140:141], v[180:181], s[0:1] op_sel_hi:[1,0]
	v_pk_mul_f32 v[146:147], v[186:187], s[0:1] op_sel_hi:[1,0]
	v_pk_mul_f32 v[144:145], v[184:185], s[0:1] op_sel_hi:[1,0]
	v_pk_mul_f32 v[150:151], v[190:191], s[0:1] op_sel_hi:[1,0]
	v_pk_mul_f32 v[148:149], v[188:189], s[0:1] op_sel_hi:[1,0]
	v_pk_fma_f32 v[114:115], v[114:115], 0.5, v[138:139] op_sel_hi:[1,0,1]
	v_pk_fma_f32 v[112:113], v[112:113], 0.5, v[136:137] op_sel_hi:[1,0,1]
	v_pk_fma_f32 v[126:127], v[126:127], 0.5, v[142:143] op_sel_hi:[1,0,1]
	v_pk_fma_f32 v[124:125], v[124:125], 0.5, v[140:141] op_sel_hi:[1,0,1]
	v_pk_fma_f32 v[110:111], v[110:111], 0.5, v[146:147] op_sel_hi:[1,0,1]
	v_pk_fma_f32 v[108:109], v[108:109], 0.5, v[144:145] op_sel_hi:[1,0,1]
	v_pk_fma_f32 v[94:95], v[94:95], 0.5, v[150:151] op_sel_hi:[1,0,1]
	v_pk_fma_f32 v[92:93], v[92:93], 0.5, v[148:149] op_sel_hi:[1,0,1]
	s_nop 0
	s_add_u32 s98, s4, 0x80000
	s_addc_u32 s99, s5, 0
	global_load_dwordx4 v[176:179], v242, s[98:99]
	global_load_dwordx4 v[180:183], v242, s[98:99] offset:16
	global_load_dwordx4 v[184:187], v242, s[98:99] offset:512
	global_load_dwordx4 v[188:191], v242, s[98:99] offset:528
	v_or_b32_e32 v154, 32, v134
	v_ashrrev_i32_e32 v155, 31, v154
	v_lshlrev_b64 v[154:155], 12, v[154:155]
	v_lshl_add_u64 v[154:155], s[4:5], 0, v[154:155]
	v_lshl_add_u64 v[154:155], v[154:155], 0, v[132:133]
	v_mov_b32_e32 v158, v113
	v_mov_b32_e32 v159, v114
	v_mov_b32_e32 v160, v112
	v_mov_b32_e32 v161, v115
	v_pk_add_f32 v[158:159], v[158:159], v[160:161]
	v_add_f32_e32 v163, v108, v109
	v_add_f32_e32 v167, v110, v111
	v_mov_b32_e32 v162, v92
	v_mov_b32_e32 v166, v93
	v_mov_b32_e32 v172, v95
	s_waitcnt vmcnt(15)
	v_pk_mul_f32 v[138:139], v[194:195], s[0:1] op_sel_hi:[1,0]
	v_pk_mul_f32 v[136:137], v[192:193], s[0:1] op_sel_hi:[1,0]
	s_waitcnt vmcnt(14)
	v_pk_mul_f32 v[142:143], v[200:201], s[0:1] op_sel_hi:[1,0]
	v_pk_mul_f32 v[140:141], v[198:199], s[0:1] op_sel_hi:[1,0]
	s_waitcnt vmcnt(13)
	v_pk_mul_f32 v[146:147], v[204:205], s[0:1] op_sel_hi:[1,0]
	v_pk_mul_f32 v[144:145], v[202:203], s[0:1] op_sel_hi:[1,0]
	s_waitcnt vmcnt(12)
	v_pk_mul_f32 v[150:151], v[208:209], s[0:1] op_sel_hi:[1,0]
	v_pk_mul_f32 v[148:149], v[206:207], s[0:1] op_sel_hi:[1,0]
	v_pk_fma_f32 v[98:99], v[98:99], 0.5, v[138:139] op_sel_hi:[1,0,1]
	v_pk_fma_f32 v[96:97], v[96:97], 0.5, v[136:137] op_sel_hi:[1,0,1]
	v_pk_fma_f32 v[130:131], v[130:131], 0.5, v[142:143] op_sel_hi:[1,0,1]
	v_pk_fma_f32 v[128:129], v[128:129], 0.5, v[140:141] op_sel_hi:[1,0,1]
	v_pk_fma_f32 v[82:83], v[82:83], 0.5, v[146:147] op_sel_hi:[1,0,1]
	v_pk_fma_f32 v[80:81], v[80:81], 0.5, v[144:145] op_sel_hi:[1,0,1]
	v_pk_fma_f32 v[70:71], v[70:71], 0.5, v[150:151] op_sel_hi:[1,0,1]
	v_pk_fma_f32 v[68:69], v[68:69], 0.5, v[148:149] op_sel_hi:[1,0,1]
	s_nop 0
	s_add_u32 s100, s4, 0x90000
	s_addc_u32 s101, s5, 0
	global_load_dwordx4 v[192:195], v242, s[100:101]
	global_load_dwordx4 v[198:201], v242, s[100:101] offset:16
	global_load_dwordx4 v[202:205], v242, s[100:101] offset:512
	global_load_dwordx4 v[206:209], v242, s[100:101] offset:528
	v_or_b32_e32 v154, 48, v134
	v_ashrrev_i32_e32 v155, 31, v154
	v_lshlrev_b64 v[154:155], 12, v[154:155]
	v_lshl_add_u64 v[154:155], s[4:5], 0, v[154:155]
	v_lshl_add_u64 v[154:155], v[154:155], 0, v[132:133]
	s_waitcnt vmcnt(15)
;     __device__ __forceinline__ void fused(f32x4 (&acc)[2][2][4][2], const Unit& u, int wr, int wc, int fr, int fq, PG8_LAS unsigned char* lds, int wid, int lane) const {
;     ...
;             for (int m = 0; m < 4; ++m) { const size_t off = (size_t)(u.pm * BM + ai * HALF + wr * 64 + m * 16 + fr) * ldc + col0;
; #pragma unroll
;                 for (int bj = 0; bj < 2; ++bj) { f32x4 b0, b1;
;                     if (base) { b0 = *(const f32x4*)(base + off + bj * HALF); b1 = *(const f32x4*)(base + off + bj * HALF + 4); }
;                     else { const u32x4 w = *(const u32x4*)(baseb + off + bj * HALF);
;                         b0 = (f32x4){__uint_as_float(w.x << 16), __uint_as_float(w.x & 0xffff0000u), __uint_as_float(w.y << 16), __uint_as_float(w.y & 0xffff0000u)};
;                         b1 = (f32x4){__uint_as_float(w.z << 16), __uint_as_float(w.z & 0xffff0000u), __uint_as_float(w.w << 16), __uint_as_float(w.w & 0xffff0000u)}; }
;                     acc[ai][bj][m][0] = acc[ai][bj][m][0] * s + b0 * alpha; acc[ai][bj][m][1] = acc[ai][bj][m][1] * s + b1 * alpha; }
;                 asm volatile("" : "+v"(acc[ai][0][m][0]), "+v"(acc[ai][0][m][1]), "+v"(acc[ai][1][m][0]), "+v"(acc[ai][1][m][1]));
;                 if (m == 3) asm volatile("" ::: "memory"); }
	v_pk_mul_f32 v[138:139], v[212:213], s[0:1] op_sel_hi:[1,0]
	v_pk_mul_f32 v[136:137], v[210:211], s[0:1] op_sel_hi:[1,0]
	s_waitcnt vmcnt(14)
	v_pk_mul_f32 v[142:143], v[216:217], s[0:1] op_sel_hi:[1,0]
	v_pk_mul_f32 v[140:141], v[214:215], s[0:1] op_sel_hi:[1,0]
	s_waitcnt vmcnt(13)
	v_pk_mul_f32 v[146:147], v[220:221], s[0:1] op_sel_hi:[1,0]
	v_pk_mul_f32 v[144:145], v[218:219], s[0:1] op_sel_hi:[1,0]
	s_waitcnt vmcnt(12)
	v_pk_mul_f32 v[150:151], v[224:225], s[0:1] op_sel_hi:[1,0]
	v_pk_mul_f32 v[148:149], v[222:223], s[0:1] op_sel_hi:[1,0]
	v_pk_fma_f32 v[102:103], v[102:103], 0.5, v[138:139] op_sel_hi:[1,0,1]
	v_pk_fma_f32 v[100:101], v[100:101], 0.5, v[136:137] op_sel_hi:[1,0,1]
	v_pk_fma_f32 v[118:119], v[118:119], 0.5, v[142:143] op_sel_hi:[1,0,1]
	v_pk_fma_f32 v[116:117], v[116:117], 0.5, v[140:141] op_sel_hi:[1,0,1]
	v_pk_fma_f32 v[86:87], v[86:87], 0.5, v[146:147] op_sel_hi:[1,0,1]
	v_pk_fma_f32 v[84:85], v[84:85], 0.5, v[144:145] op_sel_hi:[1,0,1]
	v_pk_fma_f32 v[74:75], v[74:75], 0.5, v[150:151] op_sel_hi:[1,0,1]
	v_pk_fma_f32 v[72:73], v[72:73], 0.5, v[148:149] op_sel_hi:[1,0,1]
	s_nop 0
	s_add_u32 s98, s4, 0xa0000
	s_addc_u32 s99, s5, 0
	global_load_dwordx4 v[210:213], v242, s[98:99]
	global_load_dwordx4 v[214:217], v242, s[98:99] offset:16
	global_load_dwordx4 v[218:221], v242, s[98:99] offset:512
	global_load_dwordx4 v[222:225], v242, s[98:99] offset:528
	v_add_u32_e32 v154, 0x80, v134
	v_ashrrev_i32_e32 v155, 31, v154
	v_lshlrev_b64 v[154:155], 12, v[154:155]
	v_lshl_add_u64 v[154:155], s[4:5], 0, v[154:155]
	v_lshl_add_u64 v[154:155], v[154:155], 0, v[132:133]
	s_waitcnt vmcnt(15)
	v_pk_mul_f32 v[138:139], v[228:229], s[0:1] op_sel_hi:[1,0]
	v_pk_mul_f32 v[136:137], v[226:227], s[0:1] op_sel_hi:[1,0]
	s_waitcnt vmcnt(14)
	v_pk_mul_f32 v[142:143], v[232:233], s[0:1] op_sel_hi:[1,0]
	v_pk_mul_f32 v[140:141], v[230:231], s[0:1] op_sel_hi:[1,0]
	s_waitcnt vmcnt(13)
	v_pk_mul_f32 v[146:147], v[248:249], s[0:1] op_sel_hi:[1,0]
	v_pk_mul_f32 v[144:145], v[246:247], s[0:1] op_sel_hi:[1,0]
	s_waitcnt vmcnt(12)
	v_pk_mul_f32 v[150:151], v[252:253], s[0:1] op_sel_hi:[1,0]
	v_pk_mul_f32 v[148:149], v[250:251], s[0:1] op_sel_hi:[1,0]
	v_pk_fma_f32 v[106:107], v[106:107], 0.5, v[138:139] op_sel_hi:[1,0,1]
	v_pk_fma_f32 v[104:105], v[104:105], 0.5, v[136:137] op_sel_hi:[1,0,1]
	v_pk_fma_f32 v[122:123], v[122:123], 0.5, v[142:143] op_sel_hi:[1,0,1]
	v_pk_fma_f32 v[120:121], v[120:121], 0.5, v[140:141] op_sel_hi:[1,0,1]
	v_pk_fma_f32 v[90:91], v[90:91], 0.5, v[146:147] op_sel_hi:[1,0,1]
	v_pk_fma_f32 v[88:89], v[88:89], 0.5, v[144:145] op_sel_hi:[1,0,1]
	v_pk_fma_f32 v[78:79], v[78:79], 0.5, v[150:151] op_sel_hi:[1,0,1]
	v_pk_fma_f32 v[76:77], v[76:77], 0.5, v[148:149] op_sel_hi:[1,0,1]
	s_nop 0
	s_add_u32 s100, s4, 0xb0000
	s_addc_u32 s101, s5, 0
	global_load_dwordx4 v[226:229], v242, s[100:101] offset:16
	global_load_dwordx4 v[230:233], v242, s[100:101]
	global_load_dwordx4 v[246:249], v242, s[100:101] offset:528
	global_load_dwordx4 v[250:253], v242, s[100:101] offset:512
	v_add_u32_e32 v154, 0x90, v134
	v_ashrrev_i32_e32 v155, 31, v154
	v_lshlrev_b64 v[154:155], 12, v[154:155]
	v_lshl_add_u64 v[154:155], s[4:5], 0, v[154:155]
	v_lshl_add_u64 v[154:155], v[154:155], 0, v[132:133]
	s_waitcnt vmcnt(15)
	v_pk_mul_f32 v[138:139], v[178:179], s[0:1] op_sel_hi:[1,0]
	v_pk_mul_f32 v[136:137], v[176:177], s[0:1] op_sel_hi:[1,0]
	s_waitcnt vmcnt(14)
	v_pk_mul_f32 v[142:143], v[182:183], s[0:1] op_sel_hi:[1,0]
	v_pk_mul_f32 v[140:141], v[180:181], s[0:1] op_sel_hi:[1,0]
	s_waitcnt vmcnt(13)
	v_pk_mul_f32 v[146:147], v[186:187], s[0:1] op_sel_hi:[1,0]
	v_pk_mul_f32 v[144:145], v[184:185], s[0:1] op_sel_hi:[1,0]
	s_waitcnt vmcnt(12)
	v_pk_mul_f32 v[150:151], v[190:191], s[0:1] op_sel_hi:[1,0]
	v_pk_mul_f32 v[148:149], v[188:189], s[0:1] op_sel_hi:[1,0]
	v_pk_fma_f32 v[66:67], v[66:67], 0.5, v[138:139] op_sel_hi:[1,0,1]
	v_pk_fma_f32 v[64:65], v[64:65], 0.5, v[136:137] op_sel_hi:[1,0,1]
	v_pk_fma_f32 v[62:63], v[62:63], 0.5, v[142:143] op_sel_hi:[1,0,1]
	v_pk_fma_f32 v[60:61], v[60:61], 0.5, v[140:141] op_sel_hi:[1,0,1]
	v_pk_fma_f32 v[58:59], v[58:59], 0.5, v[146:147] op_sel_hi:[1,0,1]
	v_pk_fma_f32 v[56:57], v[56:57], 0.5, v[144:145] op_sel_hi:[1,0,1]
	v_pk_fma_f32 v[54:55], v[54:55], 0.5, v[150:151] op_sel_hi:[1,0,1]
	v_pk_fma_f32 v[52:53], v[52:53], 0.5, v[148:149] op_sel_hi:[1,0,1]
	s_nop 0
	v_add_u32_e32 v154, 0xa0, v134
	v_ashrrev_i32_e32 v155, 31, v154
	v_lshlrev_b64 v[154:155], 12, v[154:155]
	v_lshl_add_u64 v[154:155], s[4:5], 0, v[154:155]
	v_lshl_add_u64 v[154:155], v[154:155], 0, v[132:133]
	v_add_u32_e32 v134, 0xb0, v134
	v_ashrrev_i32_e32 v135, 31, v134
	s_waitcnt vmcnt(11)
	v_pk_mul_f32 v[138:139], v[194:195], s[0:1] op_sel_hi:[1,0]
	v_pk_mul_f32 v[136:137], v[192:193], s[0:1] op_sel_hi:[1,0]
	s_waitcnt vmcnt(10)
	v_pk_mul_f32 v[142:143], v[200:201], s[0:1] op_sel_hi:[1,0]
	v_pk_mul_f32 v[140:141], v[198:199], s[0:1] op_sel_hi:[1,0]
	s_waitcnt vmcnt(9)
	v_pk_mul_f32 v[146:147], v[204:205], s[0:1] op_sel_hi:[1,0]
	v_pk_mul_f32 v[144:145], v[202:203], s[0:1] op_sel_hi:[1,0]
	s_waitcnt vmcnt(8)
	v_pk_mul_f32 v[150:151], v[208:209], s[0:1] op_sel_hi:[1,0]
	v_pk_mul_f32 v[148:149], v[206:207], s[0:1] op_sel_hi:[1,0]
	v_pk_fma_f32 v[50:51], v[50:51], 0.5, v[138:139] op_sel_hi:[1,0,1]
	v_pk_fma_f32 v[48:49], v[48:49], 0.5, v[136:137] op_sel_hi:[1,0,1]
	v_pk_fma_f32 v[46:47], v[46:47], 0.5, v[142:143] op_sel_hi:[1,0,1]
	v_pk_fma_f32 v[44:45], v[44:45], 0.5, v[140:141] op_sel_hi:[1,0,1]
	v_pk_fma_f32 v[42:43], v[42:43], 0.5, v[146:147] op_sel_hi:[1,0,1]
	v_pk_fma_f32 v[40:41], v[40:41], 0.5, v[144:145] op_sel_hi:[1,0,1]
	v_pk_fma_f32 v[38:39], v[38:39], 0.5, v[150:151] op_sel_hi:[1,0,1]
	v_pk_fma_f32 v[36:37], v[36:37], 0.5, v[148:149] op_sel_hi:[1,0,1]
	s_nop 0
	v_xor_b32_e32 v154, 16, v153
	v_cmp_lt_i32_e32 vcc, v154, v174
	s_waitcnt vmcnt(7)
;     __device__ __forceinline__ bool run(const f32x4 (&v)[2][2][4][2], const Unit& u, int wr, int wc, int fr, int fq, PG8_LAS unsigned char* lds, int wid, int lane) const {
;     ...
;                 float s = 0.f;
; #pragma unroll
;                 for (int bj = 0; bj < 2; ++bj)
; #pragma unroll
;                     for (int n = 0; n < 2; ++n) { const f32x4 x = v[ai][bj][m][n]; s += (x[0] + x[1]) + (x[2] + x[3]); }
;                 s += __shfl_xor(s, 16); s += __shfl_xor(s, 32);
;                 const float mw = s * (1.0f / 64.0f); float q = 0.f;
; #pragma unroll
;                 for (int bj = 0; bj < 2; ++bj)
; #pragma unroll
;                     for (int n = 0; n < 2; ++n) { const f32x4 d = v[ai][bj][m][n] - mw; q += (d[0] * d[0] + d[1] * d[1]) + (d[2] * d[2] + d[3] * d[3]); }
;                 q += __shfl_xor(q, 16); q += __shfl_xor(q, 32);
;                 if (fq == 0) P[(ai * HALF + wr * 64 + m * 16 + fr) * 4 + wc] = (f32x2v){mw, q};
	v_pk_mul_f32 v[138:139], v[212:213], s[0:1] op_sel_hi:[1,0]
	v_cndmask_b32_e32 v156, v153, v154, vcc
	v_lshlrev_b64 v[154:155], 12, v[134:135]
	v_lshl_add_u64 v[154:155], s[4:5], 0, v[154:155]
	v_pk_mul_f32 v[136:137], v[210:211], s[0:1] op_sel_hi:[1,0]
	s_waitcnt vmcnt(6)
	v_pk_mul_f32 v[142:143], v[216:217], s[0:1] op_sel_hi:[1,0]
	v_pk_mul_f32 v[140:141], v[214:215], s[0:1] op_sel_hi:[1,0]
	s_waitcnt vmcnt(5)
	v_pk_mul_f32 v[146:147], v[220:221], s[0:1] op_sel_hi:[1,0]
	v_pk_mul_f32 v[144:145], v[218:219], s[0:1] op_sel_hi:[1,0]
	s_waitcnt vmcnt(4)
	v_pk_mul_f32 v[150:151], v[224:225], s[0:1] op_sel_hi:[1,0]
	v_pk_mul_f32 v[148:149], v[222:223], s[0:1] op_sel_hi:[1,0]
	v_lshl_add_u64 v[154:155], v[154:155], 0, v[132:133]
	v_pk_fma_f32 v[34:35], v[34:35], 0.5, v[138:139] op_sel_hi:[1,0,1]
	v_pk_fma_f32 v[32:33], v[32:33], 0.5, v[136:137] op_sel_hi:[1,0,1]
	v_pk_fma_f32 v[30:31], v[30:31], 0.5, v[142:143] op_sel_hi:[1,0,1]
	v_pk_fma_f32 v[28:29], v[28:29], 0.5, v[140:141] op_sel_hi:[1,0,1]
	v_pk_fma_f32 v[26:27], v[26:27], 0.5, v[146:147] op_sel_hi:[1,0,1]
	v_pk_fma_f32 v[24:25], v[24:25], 0.5, v[144:145] op_sel_hi:[1,0,1]
	v_pk_fma_f32 v[22:23], v[22:23], 0.5, v[150:151] op_sel_hi:[1,0,1]
	v_pk_fma_f32 v[20:21], v[20:21], 0.5, v[148:149] op_sel_hi:[1,0,1]
	v_lshlrev_b32_e32 v134, 2, v156
	s_nop 0
	v_mov_b32_e32 v136, v125
	v_mov_b32_e32 v137, v126
	v_mov_b32_e32 v138, v124
	v_mov_b32_e32 v139, v127
	v_pk_add_f32 v[136:137], v[136:137], v[138:139]
	v_add_f32_e32 v135, v158, v159
	v_pk_add_f32 v[136:137], v[136:137], v[136:137] op_sel_hi:[0,1]
	v_add_f32_e32 v173, 0, v135
	v_mov_b32_e32 v136, v94
	v_pk_add_f32 v[138:139], v[162:163], v[166:167]
	v_pk_add_f32 v[136:137], v[136:137], v[172:173]
	v_xor_b32_e32 v135, 32, v153
	v_pk_add_f32 v[136:137], v[138:139], v[136:137]
	v_cmp_lt_i32_e32 vcc, v135, v174
	v_add_f32_e32 v136, v136, v137
	v_mov_b32_e32 v137, v136
	s_nop 1
	v_permlane16_swap_b32 v136, v137
	v_cndmask_b32_e32 v135, v153, v135, vcc
	v_lshlrev_b32_e32 v135, 2, v135
	s_waitcnt lgkmcnt(0)
	v_add_f32_e32 v136, v136, v137
	v_mov_b32_e32 v137, v136
	s_nop 1
	v_permlane32_swap_b32 v136, v137
	s_waitcnt lgkmcnt(0)
	v_add_f32_e32 v137, v136, v137
	v_fmamk_f32 v138, v137, 0xbc800000, v115
	v_fmamk_f32 v153, v137, 0xbc800000, v113
	v_fmamk_f32 v159, v137, 0xbc800000, v127
	v_fmamk_f32 v161, v137, 0xbc800000, v125
	v_fmamk_f32 v136, v137, 0xbc800000, v114
	v_fmamk_f32 v139, v137, 0xbc800000, v112
	v_fmamk_f32 v158, v137, 0xbc800000, v126
	v_fmamk_f32 v160, v137, 0xbc800000, v124
	v_fmamk_f32 v163, v137, 0xbc800000, v111
	v_fmamk_f32 v167, v137, 0xbc800000, v109
	v_mul_f32_e32 v153, v153, v153
	v_mul_f32_e32 v138, v138, v138
	v_mul_f32_e32 v161, v161, v161
	v_mul_f32_e32 v159, v159, v159
	v_fmamk_f32 v162, v137, 0xbc800000, v110
	v_fmamk_f32 v166, v137, 0xbc800000, v108
	v_fmamk_f32 v173, v137, 0xbc800000, v95
	v_fmamk_f32 v175, v137, 0xbc800000, v93
	v_mul_f32_e32 v167, v167, v167
	v_mul_f32_e32 v163, v163, v163
	v_fmac_f32_e32 v153, v139, v139
	v_fmac_f32_e32 v138, v136, v136
	v_fmac_f32_e32 v161, v160, v160
	v_fmac_f32_e32 v159, v158, v158
	v_fmamk_f32 v172, v137, 0xbc800000, v94
	v_fmamk_f32 v174, v137, 0xbc800000, v92
	v_mul_f32_e32 v175, v175, v175
	v_mul_f32_e32 v173, v173, v173
	v_fmac_f32_e32 v167, v166, v166
	v_fmac_f32_e32 v163, v162, v162
	v_add_f32_e32 v136, v153, v138
	v_add_f32_e32 v138, v161, v159
	v_fmac_f32_e32 v175, v174, v174
	v_fmac_f32_e32 v173, v172, v172
	v_add_f32_e32 v139, v167, v163
	v_add_f32_e32 v136, v136, v138
	v_add_f32_e32 v153, v175, v173
	v_add_f32_e32 v136, v139, v136
	v_add_f32_e32 v138, v153, v136
	v_mov_b32_e32 v139, v138
	s_nop 1
	v_permlane16_swap_b32 v138, v139
	v_and_b32_e32 v136, 63, v2
	v_cmp_gt_u32_e32 vcc, 16, v136
	s_waitcnt lgkmcnt(0)
	v_add_f32_e32 v138, v138, v139
	v_mov_b32_e32 v139, v138
	s_nop 1
	v_permlane32_swap_b32 v138, v139
	s_waitcnt vmcnt(3)
	v_pk_mul_f32 v[142:143], v[228:229], s[0:1] op_sel_hi:[1,0]
	s_waitcnt vmcnt(2)
	v_pk_mul_f32 v[146:147], v[232:233], s[0:1] op_sel_hi:[1,0]
	v_pk_mul_f32 v[144:145], v[230:231], s[0:1] op_sel_hi:[1,0]
	v_pk_mul_f32 v[140:141], v[226:227], s[0:1] op_sel_hi:[1,0]
	s_waitcnt vmcnt(0)
	v_pk_mul_f32 v[156:157], v[252:253], s[0:1] op_sel_hi:[1,0]
	v_pk_mul_f32 v[154:155], v[250:251], s[0:1] op_sel_hi:[1,0]
	v_pk_mul_f32 v[150:151], v[248:249], s[0:1] op_sel_hi:[1,0]
	v_pk_mul_f32 v[148:149], v[246:247], s[0:1] op_sel_hi:[1,0]
	v_pk_fma_f32 v[18:19], v[18:19], 0.5, v[146:147] op_sel_hi:[1,0,1]
	v_pk_fma_f32 v[16:17], v[16:17], 0.5, v[144:145] op_sel_hi:[1,0,1]
	v_pk_fma_f32 v[14:15], v[14:15], 0.5, v[142:143] op_sel_hi:[1,0,1]
	v_pk_fma_f32 v[12:13], v[12:13], 0.5, v[140:141] op_sel_hi:[1,0,1]
	v_pk_fma_f32 v[10:11], v[10:11], 0.5, v[156:157] op_sel_hi:[1,0,1]
	v_pk_fma_f32 v[8:9], v[8:9], 0.5, v[154:155] op_sel_hi:[1,0,1]
	v_pk_fma_f32 v[6:7], v[6:7], 0.5, v[150:151] op_sel_hi:[1,0,1]
	v_pk_fma_f32 v[4:5], v[4:5], 0.5, v[148:149] op_sel_hi:[1,0,1]
	s_lshl_b32 s0, s27, 3
	s_add_i32 s2, s0, 0
	s_and_saveexec_b64 s[0:1], vcc
	s_cbranch_execz .LBB0_196
	s_lshl_b32 s3, s26, 11
	s_add_i32 s3, s2, s3
	v_mul_f32_e32 v140, 0x3c800000, v137
	v_lshl_add_u32 v137, v152, 5, s3
	s_waitcnt lgkmcnt(0)
	v_add_f32_e32 v141, v138, v139
	ds_write_b64 v137, v[140:141]
;     __device__ __forceinline__ bool run(const f32x4 (&v)[2][2][4][2], const Unit& u, int wr, int wc, int fr, int fq, PG8_LAS unsigned char* lds, int wid, int lane) const {
;     ...
;                 float s = 0.f;
; #pragma unroll
;                 for (int bj = 0; bj < 2; ++bj)
; #pragma unroll
;                     for (int n = 0; n < 2; ++n) { const f32x4 x = v[ai][bj][m][n]; s += (x[0] + x[1]) + (x[2] + x[3]); }
;                 s += __shfl_xor(s, 16); s += __shfl_xor(s, 32);
;                 const float mw = s * (1.0f / 64.0f); float q = 0.f;
; #pragma unroll
;                 for (int bj = 0; bj < 2; ++bj)
; #pragma unroll
;                     for (int n = 0; n < 2; ++n) { const f32x4 d = v[ai][bj][m][n] - mw; q += (d[0] * d[0] + d[1] * d[1]) + (d[2] * d[2] + d[3] * d[3]); }
;                 q += __shfl_xor(q, 16); q += __shfl_xor(q, 32);
;                 if (fq == 0) P[(ai * HALF + wr * 64 + m * 16 + fr) * 4 + wc] = (f32x2v){mw, q};
.LBB0_196:
	s_or_b64 exec, exec, s[0:1]
	v_mov_b32_e32 v138, v97
	s_waitcnt lgkmcnt(0)
	v_mov_b32_e32 v139, v98
	v_mov_b32_e32 v140, v96
	v_mov_b32_e32 v141, v99
	v_pk_add_f32 v[138:139], v[138:139], v[140:141]
	v_mov_b32_e32 v140, v129
	v_mov_b32_e32 v141, v130
	v_mov_b32_e32 v142, v128
	v_mov_b32_e32 v143, v131
	v_pk_add_f32 v[140:141], v[140:141], v[142:143]
	v_add_f32_e32 v137, v138, v139
	v_pk_add_f32 v[140:141], v[140:141], v[140:141] op_sel_hi:[0,1]
	v_add_f32_e32 v139, 0, v137
	v_add_f32_e32 v143, v80, v81
	v_add_f32_e32 v145, v82, v83
	v_mov_b32_e32 v142, v68
	v_mov_b32_e32 v144, v69
	v_mov_b32_e32 v140, v70
	v_mov_b32_e32 v138, v71
	v_pk_add_f32 v[142:143], v[142:143], v[144:145]
	v_pk_add_f32 v[138:139], v[140:141], v[138:139]
	s_nop 0
	v_pk_add_f32 v[138:139], v[142:143], v[138:139]
	s_nop 0
	v_add_f32_e32 v137, v138, v139
	v_mov_b32_e32 v138, v137
	s_nop 1
	v_permlane16_swap_b32 v137, v138
	s_waitcnt lgkmcnt(0)
	v_add_f32_e32 v137, v137, v138
	v_mov_b32_e32 v138, v137
	s_nop 1
	v_permlane32_swap_b32 v137, v138
	s_waitcnt lgkmcnt(0)
	v_add_f32_e32 v137, v137, v138
	v_fmamk_f32 v139, v137, 0xbc800000, v99
	v_fmamk_f32 v141, v137, 0xbc800000, v97
	v_fmamk_f32 v138, v137, 0xbc800000, v98
	v_fmamk_f32 v140, v137, 0xbc800000, v96
	v_mul_f32_e32 v141, v141, v141
	v_mul_f32_e32 v139, v139, v139
	v_fmac_f32_e32 v141, v140, v140
	v_fmac_f32_e32 v139, v138, v138
	v_fmamk_f32 v140, v137, 0xbc800000, v131
	v_fmamk_f32 v142, v137, 0xbc800000, v129
	v_add_f32_e32 v138, v141, v139
	v_fmamk_f32 v139, v137, 0xbc800000, v130
	v_fmamk_f32 v141, v137, 0xbc800000, v128
	v_mul_f32_e32 v142, v142, v142
	v_mul_f32_e32 v140, v140, v140
	v_fmac_f32_e32 v142, v141, v141
	v_fmac_f32_e32 v140, v139, v139
	v_add_f32_e32 v139, v142, v140
	v_fmamk_f32 v140, v137, 0xbc800000, v83
	v_fmamk_f32 v142, v137, 0xbc800000, v81
	v_add_f32_e32 v138, v138, v139
	v_fmamk_f32 v139, v137, 0xbc800000, v82
	v_fmamk_f32 v141, v137, 0xbc800000, v80
	v_mul_f32_e32 v142, v142, v142
	v_mul_f32_e32 v140, v140, v140
	v_fmac_f32_e32 v142, v141, v141
	v_fmac_f32_e32 v140, v139, v139
	v_add_f32_e32 v139, v142, v140
	v_fmamk_f32 v140, v137, 0xbc800000, v71
	v_fmamk_f32 v142, v137, 0xbc800000, v69
	v_add_f32_e32 v138, v139, v138
	v_fmamk_f32 v139, v137, 0xbc800000, v70
	v_fmamk_f32 v141, v137, 0xbc800000, v68
	v_mul_f32_e32 v142, v142, v142
	v_mul_f32_e32 v140, v140, v140
	v_fmac_f32_e32 v142, v141, v141
	v_fmac_f32_e32 v140, v139, v139
	v_add_f32_e32 v139, v142, v140
	v_add_f32_e32 v138, v139, v138
	v_mov_b32_e32 v139, v138
	s_nop 1
	v_permlane16_swap_b32 v138, v139
	s_waitcnt lgkmcnt(0)
	v_add_f32_e32 v138, v138, v139
	v_mov_b32_e32 v139, v138
	s_nop 1
	v_permlane32_swap_b32 v138, v139
	s_and_saveexec_b64 s[0:1], vcc
	s_cbranch_execz .LBB0_198
	s_lshl_b32 s3, s26, 11
	s_add_i32 s3, s2, s3
	v_mul_f32_e32 v140, 0x3c800000, v137
	v_lshl_add_u32 v137, v152, 5, s3
	s_waitcnt lgkmcnt(0)
	v_add_f32_e32 v141, v138, v139
	ds_write_b64 v137, v[140:141] offset:512
.LBB0_198:
	s_or_b64 exec, exec, s[0:1]
	v_mov_b32_e32 v138, v101
	s_waitcnt lgkmcnt(0)
	v_mov_b32_e32 v139, v102
	v_mov_b32_e32 v140, v100
	v_mov_b32_e32 v141, v103
	v_pk_add_f32 v[138:139], v[138:139], v[140:141]
	v_mov_b32_e32 v140, v117
	v_mov_b32_e32 v141, v118
	v_mov_b32_e32 v142, v116
	v_mov_b32_e32 v143, v119
	v_pk_add_f32 v[140:141], v[140:141], v[142:143]
	v_add_f32_e32 v137, v138, v139
	v_pk_add_f32 v[140:141], v[140:141], v[140:141] op_sel_hi:[0,1]
	v_add_f32_e32 v139, 0, v137
	v_add_f32_e32 v143, v84, v85
	v_add_f32_e32 v145, v86, v87
	v_mov_b32_e32 v142, v72
	v_mov_b32_e32 v144, v73
	v_mov_b32_e32 v140, v74
	v_mov_b32_e32 v138, v75
	v_pk_add_f32 v[142:143], v[142:143], v[144:145]
	v_pk_add_f32 v[138:139], v[140:141], v[138:139]
	s_nop 0
	v_pk_add_f32 v[138:139], v[142:143], v[138:139]
	s_nop 0
	v_add_f32_e32 v137, v138, v139
	v_mov_b32_e32 v138, v137
	s_nop 1
	v_permlane16_swap_b32 v137, v138
	s_waitcnt lgkmcnt(0)
	v_add_f32_e32 v137, v137, v138
	v_mov_b32_e32 v138, v137
	s_nop 1
	v_permlane32_swap_b32 v137, v138
	s_waitcnt lgkmcnt(0)
	v_add_f32_e32 v137, v137, v138
	v_fmamk_f32 v139, v137, 0xbc800000, v103
	v_fmamk_f32 v141, v137, 0xbc800000, v101
	v_fmamk_f32 v138, v137, 0xbc800000, v102
	v_fmamk_f32 v140, v137, 0xbc800000, v100
	v_mul_f32_e32 v141, v141, v141
	v_mul_f32_e32 v139, v139, v139
	v_fmac_f32_e32 v141, v140, v140
	v_fmac_f32_e32 v139, v138, v138
	v_fmamk_f32 v140, v137, 0xbc800000, v119
	v_fmamk_f32 v142, v137, 0xbc800000, v117
	v_add_f32_e32 v138, v141, v139
	v_fmamk_f32 v139, v137, 0xbc800000, v118
	v_fmamk_f32 v141, v137, 0xbc800000, v116
	v_mul_f32_e32 v142, v142, v142
	v_mul_f32_e32 v140, v140, v140
	v_fmac_f32_e32 v142, v141, v141
	v_fmac_f32_e32 v140, v139, v139
	v_add_f32_e32 v139, v142, v140
	v_fmamk_f32 v140, v137, 0xbc800000, v87
	v_fmamk_f32 v142, v137, 0xbc800000, v85
	v_add_f32_e32 v138, v138, v139
	v_fmamk_f32 v139, v137, 0xbc800000, v86
	v_fmamk_f32 v141, v137, 0xbc800000, v84
	v_mul_f32_e32 v142, v142, v142
	v_mul_f32_e32 v140, v140, v140
	v_fmac_f32_e32 v142, v141, v141
	v_fmac_f32_e32 v140, v139, v139
	v_add_f32_e32 v139, v142, v140
	v_fmamk_f32 v140, v137, 0xbc800000, v75
	v_fmamk_f32 v142, v137, 0xbc800000, v73
	v_add_f32_e32 v138, v139, v138
	v_fmamk_f32 v139, v137, 0xbc800000, v74
	v_fmamk_f32 v141, v137, 0xbc800000, v72
	v_mul_f32_e32 v142, v142, v142
	v_mul_f32_e32 v140, v140, v140
	v_fmac_f32_e32 v142, v141, v141
	v_fmac_f32_e32 v140, v139, v139
	v_add_f32_e32 v139, v142, v140
	v_add_f32_e32 v138, v139, v138
	v_mov_b32_e32 v139, v138
	s_nop 1
	v_permlane16_swap_b32 v138, v139
	s_waitcnt lgkmcnt(0)
	v_add_f32_e32 v138, v138, v139
	v_mov_b32_e32 v139, v138
	s_nop 1
	v_permlane32_swap_b32 v138, v139
	s_and_saveexec_b64 s[0:1], vcc
	s_cbranch_execz .LBB0_200
	s_lshl_b32 s3, s26, 11
	s_add_i32 s3, s2, s3
	v_mul_f32_e32 v140, 0x3c800000, v137
	v_lshl_add_u32 v137, v152, 5, s3
	s_waitcnt lgkmcnt(0)
	v_add_f32_e32 v141, v138, v139
	ds_write_b64 v137, v[140:141] offset:1024
;     __device__ __forceinline__ bool run(const f32x4 (&v)[2][2][4][2], const Unit& u, int wr, int wc, int fr, int fq, PG8_LAS unsigned char* lds, int wid, int lane) const {
;     ...
;                 float s = 0.f;
; #pragma unroll
;                 for (int bj = 0; bj < 2; ++bj)
; #pragma unroll
;                     for (int n = 0; n < 2; ++n) { const f32x4 x = v[ai][bj][m][n]; s += (x[0] + x[1]) + (x[2] + x[3]); }
;                 s += __shfl_xor(s, 16); s += __shfl_xor(s, 32);
;                 const float mw = s * (1.0f / 64.0f); float q = 0.f;
; #pragma unroll
;                 for (int bj = 0; bj < 2; ++bj)
; #pragma unroll
;                     for (int n = 0; n < 2; ++n) { const f32x4 d = v[ai][bj][m][n] - mw; q += (d[0] * d[0] + d[1] * d[1]) + (d[2] * d[2] + d[3] * d[3]); }
;                 q += __shfl_xor(q, 16); q += __shfl_xor(q, 32);
;                 if (fq == 0) P[(ai * HALF + wr * 64 + m * 16 + fr) * 4 + wc] = (f32x2v){mw, q};
.LBB0_200:
	s_or_b64 exec, exec, s[0:1]
	v_mov_b32_e32 v138, v105
	s_waitcnt lgkmcnt(0)
	v_mov_b32_e32 v139, v106
	v_mov_b32_e32 v140, v104
	v_mov_b32_e32 v141, v107
	v_pk_add_f32 v[138:139], v[138:139], v[140:141]
	v_mov_b32_e32 v140, v121
	v_mov_b32_e32 v141, v122
	v_mov_b32_e32 v142, v120
	v_mov_b32_e32 v143, v123
	v_pk_add_f32 v[140:141], v[140:141], v[142:143]
	v_add_f32_e32 v137, v138, v139
	v_pk_add_f32 v[140:141], v[140:141], v[140:141] op_sel_hi:[0,1]
	v_add_f32_e32 v139, 0, v137
	v_add_f32_e32 v143, v88, v89
	v_add_f32_e32 v145, v90, v91
	v_mov_b32_e32 v142, v76
	v_mov_b32_e32 v144, v77
	v_mov_b32_e32 v140, v78
	v_mov_b32_e32 v138, v79
	v_pk_add_f32 v[142:143], v[142:143], v[144:145]
	v_pk_add_f32 v[138:139], v[140:141], v[138:139]
	s_nop 0
	v_pk_add_f32 v[138:139], v[142:143], v[138:139]
	s_nop 0
	v_add_f32_e32 v137, v138, v139
	v_mov_b32_e32 v138, v137
	s_nop 1
	v_permlane16_swap_b32 v137, v138
	s_waitcnt lgkmcnt(0)
	v_add_f32_e32 v137, v137, v138
	v_mov_b32_e32 v138, v137
	s_nop 1
	v_permlane32_swap_b32 v137, v138
	s_waitcnt lgkmcnt(0)
	v_add_f32_e32 v137, v137, v138
	v_fmamk_f32 v139, v137, 0xbc800000, v107
	v_fmamk_f32 v141, v137, 0xbc800000, v105
	v_fmamk_f32 v138, v137, 0xbc800000, v106
	v_fmamk_f32 v140, v137, 0xbc800000, v104
	v_mul_f32_e32 v141, v141, v141
	v_mul_f32_e32 v139, v139, v139
	v_fmac_f32_e32 v141, v140, v140
	v_fmac_f32_e32 v139, v138, v138
	v_fmamk_f32 v140, v137, 0xbc800000, v123
	v_fmamk_f32 v142, v137, 0xbc800000, v121
	v_add_f32_e32 v138, v141, v139
	v_fmamk_f32 v139, v137, 0xbc800000, v122
	v_fmamk_f32 v141, v137, 0xbc800000, v120
	v_mul_f32_e32 v142, v142, v142
	v_mul_f32_e32 v140, v140, v140
	v_fmac_f32_e32 v142, v141, v141
	v_fmac_f32_e32 v140, v139, v139
	v_add_f32_e32 v139, v142, v140
	v_fmamk_f32 v140, v137, 0xbc800000, v91
	v_fmamk_f32 v142, v137, 0xbc800000, v89
	v_add_f32_e32 v138, v138, v139
	v_fmamk_f32 v139, v137, 0xbc800000, v90
	v_fmamk_f32 v141, v137, 0xbc800000, v88
	v_mul_f32_e32 v142, v142, v142
	v_mul_f32_e32 v140, v140, v140
	v_fmac_f32_e32 v142, v141, v141
	v_fmac_f32_e32 v140, v139, v139
	v_add_f32_e32 v139, v142, v140
	v_fmamk_f32 v140, v137, 0xbc800000, v79
	v_fmamk_f32 v142, v137, 0xbc800000, v77
	v_add_f32_e32 v138, v139, v138
	v_fmamk_f32 v139, v137, 0xbc800000, v78
	v_fmamk_f32 v141, v137, 0xbc800000, v76
	v_mul_f32_e32 v142, v142, v142
	v_mul_f32_e32 v140, v140, v140
	v_fmac_f32_e32 v142, v141, v141
	v_fmac_f32_e32 v140, v139, v139
	v_add_f32_e32 v139, v142, v140
	v_add_f32_e32 v138, v139, v138
	v_mov_b32_e32 v139, v138
	s_nop 1
	v_permlane16_swap_b32 v138, v139
	s_waitcnt lgkmcnt(0)
	v_add_f32_e32 v138, v138, v139
	v_mov_b32_e32 v139, v138
	s_nop 1
	v_permlane32_swap_b32 v138, v139
	s_and_saveexec_b64 s[0:1], vcc
	s_cbranch_execz .LBB0_202
	s_lshl_b32 s3, s26, 11
	s_add_i32 s3, s2, s3
	v_mul_f32_e32 v140, 0x3c800000, v137
	v_lshl_add_u32 v137, v152, 5, s3
	s_waitcnt lgkmcnt(0)
	v_add_f32_e32 v141, v138, v139
	ds_write_b64 v137, v[140:141] offset:1536
.LBB0_202:
	s_or_b64 exec, exec, s[0:1]
	v_mov_b32_e32 v138, v65
	s_waitcnt lgkmcnt(0)
	v_mov_b32_e32 v139, v66
	v_mov_b32_e32 v140, v64
	v_mov_b32_e32 v141, v67
	v_pk_add_f32 v[138:139], v[138:139], v[140:141]
	v_mov_b32_e32 v140, v61
	v_mov_b32_e32 v141, v62
	v_mov_b32_e32 v142, v60
	v_mov_b32_e32 v143, v63
	v_pk_add_f32 v[140:141], v[140:141], v[142:143]
	v_add_f32_e32 v137, v138, v139
	v_pk_add_f32 v[140:141], v[140:141], v[140:141] op_sel_hi:[0,1]
	v_add_f32_e32 v139, 0, v137
	v_add_f32_e32 v143, v56, v57
	v_add_f32_e32 v145, v58, v59
	v_mov_b32_e32 v142, v52
	v_mov_b32_e32 v144, v53
	v_mov_b32_e32 v140, v54
	v_mov_b32_e32 v138, v55
	v_pk_add_f32 v[142:143], v[142:143], v[144:145]
	v_pk_add_f32 v[138:139], v[140:141], v[138:139]
	s_nop 0
	v_pk_add_f32 v[138:139], v[142:143], v[138:139]
	s_nop 0
	v_add_f32_e32 v137, v138, v139
	v_mov_b32_e32 v138, v137
	s_nop 1
	v_permlane16_swap_b32 v137, v138
	s_waitcnt lgkmcnt(0)
	v_add_f32_e32 v137, v137, v138
	v_mov_b32_e32 v138, v137
	s_nop 1
	v_permlane32_swap_b32 v137, v138
	s_waitcnt lgkmcnt(0)
	v_add_f32_e32 v137, v137, v138
	v_fmamk_f32 v139, v137, 0xbc800000, v67
	v_fmamk_f32 v141, v137, 0xbc800000, v65
	v_fmamk_f32 v138, v137, 0xbc800000, v66
	v_fmamk_f32 v140, v137, 0xbc800000, v64
	v_mul_f32_e32 v141, v141, v141
	v_mul_f32_e32 v139, v139, v139
	v_fmac_f32_e32 v141, v140, v140
	v_fmac_f32_e32 v139, v138, v138
	v_fmamk_f32 v140, v137, 0xbc800000, v63
	v_fmamk_f32 v142, v137, 0xbc800000, v61
	v_add_f32_e32 v138, v141, v139
	v_fmamk_f32 v139, v137, 0xbc800000, v62
	v_fmamk_f32 v141, v137, 0xbc800000, v60
	v_mul_f32_e32 v142, v142, v142
	v_mul_f32_e32 v140, v140, v140
	v_fmac_f32_e32 v142, v141, v141
	v_fmac_f32_e32 v140, v139, v139
	v_add_f32_e32 v139, v142, v140
	v_fmamk_f32 v140, v137, 0xbc800000, v59
	v_fmamk_f32 v142, v137, 0xbc800000, v57
	v_add_f32_e32 v138, v138, v139
	v_fmamk_f32 v139, v137, 0xbc800000, v58
	v_fmamk_f32 v141, v137, 0xbc800000, v56
	v_mul_f32_e32 v142, v142, v142
	v_mul_f32_e32 v140, v140, v140
	v_fmac_f32_e32 v142, v141, v141
	v_fmac_f32_e32 v140, v139, v139
	v_add_f32_e32 v139, v142, v140
	v_fmamk_f32 v140, v137, 0xbc800000, v55
	v_fmamk_f32 v142, v137, 0xbc800000, v53
	v_add_f32_e32 v138, v139, v138
	v_fmamk_f32 v139, v137, 0xbc800000, v54
	v_fmamk_f32 v141, v137, 0xbc800000, v52
	v_mul_f32_e32 v142, v142, v142
	v_mul_f32_e32 v140, v140, v140
	v_fmac_f32_e32 v142, v141, v141
	v_fmac_f32_e32 v140, v139, v139
	v_add_f32_e32 v139, v142, v140
	v_add_f32_e32 v138, v139, v138
	v_mov_b32_e32 v139, v138
	s_nop 1
	v_permlane16_swap_b32 v138, v139
	s_waitcnt lgkmcnt(0)
	v_add_f32_e32 v138, v138, v139
	v_mov_b32_e32 v139, v138
	s_nop 1
	v_permlane32_swap_b32 v138, v139
	s_and_saveexec_b64 s[0:1], vcc
	s_cbranch_execz .LBB0_204
	s_lshl_b32 s3, s26, 11
	s_add_i32 s3, s2, s3
	v_mul_f32_e32 v140, 0x3c800000, v137
	v_lshl_add_u32 v137, v152, 5, s3
	s_waitcnt lgkmcnt(0)
	v_add_f32_e32 v141, v138, v139
	ds_write_b64 v137, v[140:141] offset:4096
;     __device__ __forceinline__ bool run(const f32x4 (&v)[2][2][4][2], const Unit& u, int wr, int wc, int fr, int fq, PG8_LAS unsigned char* lds, int wid, int lane) const {
;     ...
;                 float s = 0.f;
; #pragma unroll
;                 for (int bj = 0; bj < 2; ++bj)
; #pragma unroll
;                     for (int n = 0; n < 2; ++n) { const f32x4 x = v[ai][bj][m][n]; s += (x[0] + x[1]) + (x[2] + x[3]); }
;                 s += __shfl_xor(s, 16); s += __shfl_xor(s, 32);
;                 const float mw = s * (1.0f / 64.0f); float q = 0.f;
; #pragma unroll
;                 for (int bj = 0; bj < 2; ++bj)
; #pragma unroll
;                     for (int n = 0; n < 2; ++n) { const f32x4 d = v[ai][bj][m][n] - mw; q += (d[0] * d[0] + d[1] * d[1]) + (d[2] * d[2] + d[3] * d[3]); }
;                 q += __shfl_xor(q, 16); q += __shfl_xor(q, 32);
;                 if (fq == 0) P[(ai * HALF + wr * 64 + m * 16 + fr) * 4 + wc] = (f32x2v){mw, q};
.LBB0_204:
	s_or_b64 exec, exec, s[0:1]
	v_mov_b32_e32 v138, v49
	s_waitcnt lgkmcnt(0)
	v_mov_b32_e32 v139, v50
	v_mov_b32_e32 v140, v48
	v_mov_b32_e32 v141, v51
	v_pk_add_f32 v[138:139], v[138:139], v[140:141]
	v_mov_b32_e32 v140, v45
	v_mov_b32_e32 v141, v46
	v_mov_b32_e32 v142, v44
	v_mov_b32_e32 v143, v47
	v_pk_add_f32 v[140:141], v[140:141], v[142:143]
	v_add_f32_e32 v137, v138, v139
	v_pk_add_f32 v[140:141], v[140:141], v[140:141] op_sel_hi:[0,1]
	v_add_f32_e32 v139, 0, v137
	v_add_f32_e32 v143, v40, v41
	v_add_f32_e32 v145, v42, v43
	v_mov_b32_e32 v142, v36
	v_mov_b32_e32 v144, v37
	v_mov_b32_e32 v140, v38
	v_mov_b32_e32 v138, v39
	v_pk_add_f32 v[142:143], v[142:143], v[144:145]
	v_pk_add_f32 v[138:139], v[140:141], v[138:139]
	s_nop 0
	v_pk_add_f32 v[138:139], v[142:143], v[138:139]
	s_nop 0
	v_add_f32_e32 v137, v138, v139
	v_mov_b32_e32 v138, v137
	s_nop 1
	v_permlane16_swap_b32 v137, v138
	s_waitcnt lgkmcnt(0)
	v_add_f32_e32 v137, v137, v138
	v_mov_b32_e32 v138, v137
	s_nop 1
	v_permlane32_swap_b32 v137, v138
	s_waitcnt lgkmcnt(0)
	v_add_f32_e32 v137, v137, v138
	v_fmamk_f32 v139, v137, 0xbc800000, v51
	v_fmamk_f32 v141, v137, 0xbc800000, v49
	v_fmamk_f32 v138, v137, 0xbc800000, v50
	v_fmamk_f32 v140, v137, 0xbc800000, v48
	v_mul_f32_e32 v141, v141, v141
	v_mul_f32_e32 v139, v139, v139
	v_fmac_f32_e32 v141, v140, v140
	v_fmac_f32_e32 v139, v138, v138
	v_fmamk_f32 v140, v137, 0xbc800000, v47
	v_fmamk_f32 v142, v137, 0xbc800000, v45
	v_add_f32_e32 v138, v141, v139
	v_fmamk_f32 v139, v137, 0xbc800000, v46
	v_fmamk_f32 v141, v137, 0xbc800000, v44
	v_mul_f32_e32 v142, v142, v142
	v_mul_f32_e32 v140, v140, v140
	v_fmac_f32_e32 v142, v141, v141
	v_fmac_f32_e32 v140, v139, v139
	v_add_f32_e32 v139, v142, v140
	v_fmamk_f32 v140, v137, 0xbc800000, v43
	v_fmamk_f32 v142, v137, 0xbc800000, v41
	v_add_f32_e32 v138, v138, v139
	v_fmamk_f32 v139, v137, 0xbc800000, v42
	v_fmamk_f32 v141, v137, 0xbc800000, v40
	v_mul_f32_e32 v142, v142, v142
	v_mul_f32_e32 v140, v140, v140
	v_fmac_f32_e32 v142, v141, v141
	v_fmac_f32_e32 v140, v139, v139
	v_add_f32_e32 v139, v142, v140
	v_fmamk_f32 v140, v137, 0xbc800000, v39
	v_fmamk_f32 v142, v137, 0xbc800000, v37
	v_add_f32_e32 v138, v139, v138
	v_fmamk_f32 v139, v137, 0xbc800000, v38
	v_fmamk_f32 v141, v137, 0xbc800000, v36
	v_mul_f32_e32 v142, v142, v142
	v_mul_f32_e32 v140, v140, v140
	v_fmac_f32_e32 v142, v141, v141
	v_fmac_f32_e32 v140, v139, v139
	v_add_f32_e32 v139, v142, v140
	v_add_f32_e32 v138, v139, v138
	v_mov_b32_e32 v139, v138
	s_nop 1
	v_permlane16_swap_b32 v138, v139
	s_waitcnt lgkmcnt(0)
	v_add_f32_e32 v138, v138, v139
	v_mov_b32_e32 v139, v138
	s_nop 1
	v_permlane32_swap_b32 v138, v139
	s_and_saveexec_b64 s[0:1], vcc
	s_cbranch_execz .LBB0_206
	s_lshl_b32 s3, s26, 11
	s_add_i32 s3, s2, s3
	v_mul_f32_e32 v140, 0x3c800000, v137
	v_lshl_add_u32 v137, v152, 5, s3
	s_waitcnt lgkmcnt(0)
	v_add_f32_e32 v141, v138, v139
	ds_write_b64 v137, v[140:141] offset:4608
;     __device__ __forceinline__ bool run(const f32x4 (&v)[2][2][4][2], const Unit& u, int wr, int wc, int fr, int fq, PG8_LAS unsigned char* lds, int wid, int lane) const {
;     ...
;                 float s = 0.f;
; #pragma unroll
;                 for (int bj = 0; bj < 2; ++bj)
; #pragma unroll
;                     for (int n = 0; n < 2; ++n) { const f32x4 x = v[ai][bj][m][n]; s += (x[0] + x[1]) + (x[2] + x[3]); }
;                 s += __shfl_xor(s, 16); s += __shfl_xor(s, 32);
;                 const float mw = s * (1.0f / 64.0f); float q = 0.f;
; #pragma unroll
;                 for (int bj = 0; bj < 2; ++bj)
; #pragma unroll
;                     for (int n = 0; n < 2; ++n) { const f32x4 d = v[ai][bj][m][n] - mw; q += (d[0] * d[0] + d[1] * d[1]) + (d[2] * d[2] + d[3] * d[3]); }
;                 q += __shfl_xor(q, 16); q += __shfl_xor(q, 32);
;                 if (fq == 0) P[(ai * HALF + wr * 64 + m * 16 + fr) * 4 + wc] = (f32x2v){mw, q};
.LBB0_206:
	s_or_b64 exec, exec, s[0:1]
	v_mov_b32_e32 v138, v33
	s_waitcnt lgkmcnt(0)
	v_mov_b32_e32 v139, v34
	v_mov_b32_e32 v140, v32
	v_mov_b32_e32 v141, v35
	v_pk_add_f32 v[138:139], v[138:139], v[140:141]
	v_mov_b32_e32 v140, v29
	v_mov_b32_e32 v141, v30
	v_mov_b32_e32 v142, v28
	v_mov_b32_e32 v143, v31
	v_pk_add_f32 v[140:141], v[140:141], v[142:143]
	v_add_f32_e32 v137, v138, v139
	v_pk_add_f32 v[140:141], v[140:141], v[140:141] op_sel_hi:[0,1]
	v_add_f32_e32 v139, 0, v137
	v_add_f32_e32 v143, v24, v25
	v_add_f32_e32 v145, v26, v27
	v_mov_b32_e32 v142, v20
	v_mov_b32_e32 v144, v21
	v_mov_b32_e32 v140, v22
	v_mov_b32_e32 v138, v23
	v_pk_add_f32 v[142:143], v[142:143], v[144:145]
	v_pk_add_f32 v[138:139], v[140:141], v[138:139]
	s_nop 0
	v_pk_add_f32 v[138:139], v[142:143], v[138:139]
	s_nop 0
	v_add_f32_e32 v137, v138, v139
	v_mov_b32_e32 v138, v137
	s_nop 1
	v_permlane16_swap_b32 v137, v138
	s_waitcnt lgkmcnt(0)
	v_add_f32_e32 v137, v137, v138
	v_mov_b32_e32 v138, v137
	s_nop 1
	v_permlane32_swap_b32 v137, v138
	s_waitcnt lgkmcnt(0)
	v_add_f32_e32 v137, v137, v138
	v_fmamk_f32 v139, v137, 0xbc800000, v35
	v_fmamk_f32 v141, v137, 0xbc800000, v33
	v_fmamk_f32 v138, v137, 0xbc800000, v34
	v_fmamk_f32 v140, v137, 0xbc800000, v32
	v_mul_f32_e32 v141, v141, v141
	v_mul_f32_e32 v139, v139, v139
	v_fmac_f32_e32 v141, v140, v140
	v_fmac_f32_e32 v139, v138, v138
	v_fmamk_f32 v140, v137, 0xbc800000, v31
	v_fmamk_f32 v142, v137, 0xbc800000, v29
	v_add_f32_e32 v138, v141, v139
	v_fmamk_f32 v139, v137, 0xbc800000, v30
	v_fmamk_f32 v141, v137, 0xbc800000, v28
	v_mul_f32_e32 v142, v142, v142
	v_mul_f32_e32 v140, v140, v140
	v_fmac_f32_e32 v142, v141, v141
	v_fmac_f32_e32 v140, v139, v139
	v_add_f32_e32 v139, v142, v140
	v_fmamk_f32 v140, v137, 0xbc800000, v27
	v_fmamk_f32 v142, v137, 0xbc800000, v25
	v_add_f32_e32 v138, v138, v139
	v_fmamk_f32 v139, v137, 0xbc800000, v26
	v_fmamk_f32 v141, v137, 0xbc800000, v24
	v_mul_f32_e32 v142, v142, v142
	v_mul_f32_e32 v140, v140, v140
	v_fmac_f32_e32 v142, v141, v141
	v_fmac_f32_e32 v140, v139, v139
	v_add_f32_e32 v139, v142, v140
	v_fmamk_f32 v140, v137, 0xbc800000, v23
	v_fmamk_f32 v142, v137, 0xbc800000, v21
	v_add_f32_e32 v138, v139, v138
	v_fmamk_f32 v139, v137, 0xbc800000, v22
	v_fmamk_f32 v141, v137, 0xbc800000, v20
	v_mul_f32_e32 v142, v142, v142
	v_mul_f32_e32 v140, v140, v140
	v_fmac_f32_e32 v142, v141, v141
	v_fmac_f32_e32 v140, v139, v139
	v_add_f32_e32 v139, v142, v140
	v_add_f32_e32 v138, v139, v138
	v_mov_b32_e32 v139, v138
	s_nop 1
	v_permlane16_swap_b32 v138, v139
	s_waitcnt lgkmcnt(0)
	v_add_f32_e32 v138, v138, v139
	v_mov_b32_e32 v139, v138
	s_nop 1
	v_permlane32_swap_b32 v138, v139
	s_and_saveexec_b64 s[0:1], vcc
	s_cbranch_execz .LBB0_208
	s_lshl_b32 s3, s26, 11
	s_add_i32 s3, s2, s3
	v_mul_f32_e32 v140, 0x3c800000, v137
	v_lshl_add_u32 v137, v152, 5, s3
	s_waitcnt lgkmcnt(0)
	v_add_f32_e32 v141, v138, v139
	ds_write_b64 v137, v[140:141] offset:5120
.LBB0_208:
	s_or_b64 exec, exec, s[0:1]
	v_mov_b32_e32 v138, v17
	s_waitcnt lgkmcnt(0)
	v_mov_b32_e32 v139, v18
	v_mov_b32_e32 v140, v16
	v_mov_b32_e32 v141, v19
	v_pk_add_f32 v[138:139], v[138:139], v[140:141]
	v_mov_b32_e32 v140, v13
	v_mov_b32_e32 v141, v14
	v_mov_b32_e32 v142, v12
	v_mov_b32_e32 v143, v15
	v_pk_add_f32 v[140:141], v[140:141], v[142:143]
	v_add_f32_e32 v137, v138, v139
	v_pk_add_f32 v[140:141], v[140:141], v[140:141] op_sel_hi:[0,1]
	v_add_f32_e32 v139, 0, v137
	v_add_f32_e32 v143, v8, v9
	v_add_f32_e32 v145, v10, v11
	v_mov_b32_e32 v142, v4
	v_mov_b32_e32 v144, v5
	v_mov_b32_e32 v140, v6
	v_mov_b32_e32 v138, v7
	v_pk_add_f32 v[142:143], v[142:143], v[144:145]
	v_pk_add_f32 v[138:139], v[140:141], v[138:139]
	s_nop 0
	v_pk_add_f32 v[138:139], v[142:143], v[138:139]
	s_nop 0
	v_add_f32_e32 v137, v138, v139
	v_mov_b32_e32 v138, v137
	s_nop 1
	v_permlane16_swap_b32 v137, v138
	s_waitcnt lgkmcnt(0)
	v_add_f32_e32 v137, v137, v138
	v_mov_b32_e32 v138, v137
	s_nop 1
	v_permlane32_swap_b32 v137, v138
	s_waitcnt lgkmcnt(0)
	v_add_f32_e32 v137, v137, v138
	v_fmamk_f32 v139, v137, 0xbc800000, v19
	v_fmamk_f32 v141, v137, 0xbc800000, v17
	v_fmamk_f32 v138, v137, 0xbc800000, v18
	v_fmamk_f32 v140, v137, 0xbc800000, v16
	v_mul_f32_e32 v141, v141, v141
	v_mul_f32_e32 v139, v139, v139
	v_fmac_f32_e32 v141, v140, v140
	v_fmac_f32_e32 v139, v138, v138
	v_fmamk_f32 v140, v137, 0xbc800000, v15
	v_fmamk_f32 v142, v137, 0xbc800000, v13
	v_add_f32_e32 v138, v141, v139
	v_fmamk_f32 v139, v137, 0xbc800000, v14
	v_fmamk_f32 v141, v137, 0xbc800000, v12
	v_mul_f32_e32 v142, v142, v142
	v_mul_f32_e32 v140, v140, v140
	v_fmac_f32_e32 v142, v141, v141
	v_fmac_f32_e32 v140, v139, v139
	v_add_f32_e32 v139, v142, v140
	v_fmamk_f32 v140, v137, 0xbc800000, v11
	v_fmamk_f32 v142, v137, 0xbc800000, v9
	v_add_f32_e32 v138, v138, v139
	v_fmamk_f32 v139, v137, 0xbc800000, v10
	v_fmamk_f32 v141, v137, 0xbc800000, v8
	v_mul_f32_e32 v142, v142, v142
	v_mul_f32_e32 v140, v140, v140
	v_fmac_f32_e32 v142, v141, v141
	v_fmac_f32_e32 v140, v139, v139
	v_add_f32_e32 v139, v142, v140
	v_fmamk_f32 v140, v137, 0xbc800000, v7
	v_fmamk_f32 v142, v137, 0xbc800000, v5
	v_add_f32_e32 v138, v139, v138
	v_fmamk_f32 v139, v137, 0xbc800000, v6
	v_fmamk_f32 v141, v137, 0xbc800000, v4
	v_mul_f32_e32 v142, v142, v142
	v_mul_f32_e32 v140, v140, v140
	v_fmac_f32_e32 v142, v141, v141
	v_fmac_f32_e32 v140, v139, v139
	v_add_f32_e32 v139, v142, v140
	v_add_f32_e32 v138, v139, v138
	v_mov_b32_e32 v134, v138
	s_nop 1
	v_permlane16_swap_b32 v138, v134
	s_waitcnt lgkmcnt(0)
	v_add_f32_e32 v134, v138, v134
	v_mov_b32_e32 v135, v134
	s_nop 1
	v_permlane32_swap_b32 v134, v135
	s_and_saveexec_b64 s[0:1], vcc
	s_cbranch_execz .LBB0_210
	s_lshl_b32 s3, s26, 11
	s_add_i32 s2, s2, s3
	v_mul_f32_e32 v138, 0x3c800000, v137
	v_lshl_add_u32 v137, v152, 5, s2
	s_waitcnt lgkmcnt(0)
	v_add_f32_e32 v139, v134, v135
	ds_write_b64 v137, v[138:139] offset:5632

;     __device__ __forceinline__ void fused(f32x4 (&acc)[2][2][4][2], const Unit& u, int wr, int wc, int fr, int fq, PG8_LAS unsigned char* lds, int wid, int lane) const {
;     ...
;             for (int m = 0; m < 4; ++m) { const size_t off = (size_t)(u.pm * BM + ai * HALF + wr * 64 + m * 16 + fr) * ldc + col0;
; #pragma unroll
;                 for (int bj = 0; bj < 2; ++bj) { f32x4 b0, b1;
;                     if (base) { b0 = *(const f32x4*)(base + off + bj * HALF); b1 = *(const f32x4*)(base + off + bj * HALF + 4); }
;                     else { const u32x4 w = *(const u32x4*)(baseb + off + bj * HALF);
;                         b0 = (f32x4){__uint_as_float(w.x << 16), __uint_as_float(w.x & 0xffff0000u), __uint_as_float(w.y << 16), __uint_as_float(w.y & 0xffff0000u)};
;                         b1 = (f32x4){__uint_as_float(w.z << 16), __uint_as_float(w.z & 0xffff0000u), __uint_as_float(w.w << 16), __uint_as_float(w.w & 0xffff0000u)}; }
;                     acc[ai][bj][m][0] = acc[ai][bj][m][0] * s + b0 * alpha; acc[ai][bj][m][1] = acc[ai][bj][m][1] * s + b1 * alpha; }
.LBB0_1496:
	s_lshl_b32 s0, s13, 5
	s_lshl_b32 s1, s20, 8
	v_lshrrev_b32_e32 v130, 1, v150
	s_or_b32 s0, s1, s0
	s_lshl_b32 s22, s12, 8
	v_and_or_b32 v130, v130, 24, s0
	s_add_i32 s0, s22, s35
	v_or_b32_e32 v132, s0, v151
	v_ashrrev_i32_e32 v133, 31, v132
	v_readlane_b32 s2, v245, 57
	v_ashrrev_i32_e32 v131, 31, v130
	v_lshlrev_b64 v[134:135], 11, v[132:133]
	v_readlane_b32 s3, v245, 58
	v_lshlrev_b64 v[162:163], 1, v[130:131]
	s_barrier
	v_lshl_add_u64 v[134:135], s[2:3], 0, v[134:135]
	v_lshl_add_u64 v[138:139], v[134:135], 0, v[162:163]
	s_nop 1
	v_subrev_u32_e32 v175, s2, v138
	global_load_dwordx4 v[176:179], v175, s[2:3]
	global_load_dwordx4 v[180:183], v175, s[2:3] offset:256
	s_add_u32 s100, s2, 0x8000
	s_addc_u32 s101, s3, 0
	global_load_dwordx4 v[184:187], v175, s[100:101]
	global_load_dwordx4 v[188:191], v175, s[100:101] offset:256
	s_add_u32 s98, s2, 0x10000
	s_addc_u32 s99, s3, 0
	global_load_dwordx4 v[192:195], v175, s[98:99]
	global_load_dwordx4 v[196:199], v175, s[98:99] offset:256
	s_add_u32 s100, s2, 0x18000
	s_addc_u32 s101, s3, 0
	global_load_dwordx4 v[200:203], v175, s[100:101]
	global_load_dwordx4 v[204:207], v175, s[100:101] offset:256
	s_add_u32 s98, s2, 0x40000
	s_addc_u32 s99, s3, 0
	global_load_dwordx4 v[208:211], v175, s[98:99]
	global_load_dwordx4 v[212:215], v175, s[98:99] offset:256
	s_add_u32 s100, s2, 0x48000
	s_addc_u32 s101, s3, 0
	global_load_dwordx4 v[216:219], v175, s[100:101]
	global_load_dwordx4 v[220:223], v175, s[100:101] offset:256
	s_add_u32 s98, s2, 0x50000
	s_addc_u32 s99, s3, 0
	global_load_dwordx4 v[224:227], v175, s[98:99]
	global_load_dwordx4 v[228:231], v175, s[98:99] offset:256
	s_add_u32 s100, s2, 0x58000
	s_addc_u32 s101, s3, 0
	global_load_dwordx4 v[232:235], v175, s[100:101]
	global_load_dwordx4 v[236:239], v175, s[100:101] offset:256
	s_nop 0
	v_or_b32_e32 v142, 16, v132
	v_ashrrev_i32_e32 v143, 31, v142
	v_lshlrev_b64 v[142:143], 11, v[142:143]
	s_mov_b32 s0, 0x3f9837f0
	v_lshl_add_u64 v[142:143], s[2:3], 0, v[142:143]
	v_lshl_add_u64 v[142:143], v[142:143], 0, v[162:163]
	v_mbcnt_hi_u32_b32 v133, -1, v1
	s_waitcnt vmcnt(14)
	v_lshlrev_b32_e32 v144, 16, v176
	v_and_b32_e32 v145, 0xffff0000, v176
	v_lshlrev_b32_e32 v134, 16, v177
	v_and_b32_e32 v135, 0xffff0000, v177
	v_lshlrev_b32_e32 v146, 16, v178
	v_and_b32_e32 v147, 0xffff0000, v178
	v_lshlrev_b32_e32 v136, 16, v179
	v_and_b32_e32 v137, 0xffff0000, v179
	v_lshlrev_b32_e32 v148, 16, v180
	v_and_b32_e32 v149, 0xffff0000, v180
	v_lshlrev_b32_e32 v138, 16, v181
	v_and_b32_e32 v139, 0xffff0000, v181
	v_lshlrev_b32_e32 v152, 16, v182
	v_and_b32_e32 v153, 0xffff0000, v182
	v_lshlrev_b32_e32 v140, 16, v183
	v_and_b32_e32 v141, 0xffff0000, v183
	v_pk_fma_f32 v[96:97], v[134:135], s[0:1], v[96:97] op_sel_hi:[1,0,1]
	v_pk_fma_f32 v[94:95], v[144:145], s[0:1], v[94:95] op_sel_hi:[1,0,1]
	v_pk_fma_f32 v[104:105], v[136:137], s[0:1], v[104:105] op_sel_hi:[1,0,1]
	v_pk_fma_f32 v[102:103], v[146:147], s[0:1], v[102:103] op_sel_hi:[1,0,1]
	v_pk_fma_f32 v[92:93], v[138:139], s[0:1], v[92:93] op_sel_hi:[1,0,1]
	v_pk_fma_f32 v[90:91], v[148:149], s[0:1], v[90:91] op_sel_hi:[1,0,1]
	v_pk_fma_f32 v[76:77], v[140:141], s[0:1], v[76:77] op_sel_hi:[1,0,1]
	v_pk_fma_f32 v[74:75], v[152:153], s[0:1], v[74:75] op_sel_hi:[1,0,1]
	s_nop 0
	v_or_b32_e32 v142, 32, v132
	v_ashrrev_i32_e32 v143, 31, v142
	v_lshlrev_b64 v[142:143], 11, v[142:143]
	v_lshl_add_u64 v[142:143], s[2:3], 0, v[142:143]
	v_lshl_add_u64 v[142:143], v[142:143], 0, v[162:163]
	s_waitcnt vmcnt(13)
	v_lshlrev_b32_e32 v144, 16, v184
	v_and_b32_e32 v145, 0xffff0000, v184
	v_lshlrev_b32_e32 v134, 16, v185
	v_and_b32_e32 v135, 0xffff0000, v185
	v_lshlrev_b32_e32 v146, 16, v186
	v_and_b32_e32 v147, 0xffff0000, v186
	v_lshlrev_b32_e32 v136, 16, v187
	v_and_b32_e32 v137, 0xffff0000, v187
	s_waitcnt vmcnt(12)
	v_lshlrev_b32_e32 v148, 16, v188
	v_and_b32_e32 v149, 0xffff0000, v188
	v_lshlrev_b32_e32 v138, 16, v189
	v_and_b32_e32 v139, 0xffff0000, v189
	v_lshlrev_b32_e32 v152, 16, v190
	v_and_b32_e32 v153, 0xffff0000, v190
	v_lshlrev_b32_e32 v140, 16, v191
	v_and_b32_e32 v141, 0xffff0000, v191
	v_pk_fma_f32 v[108:109], v[134:135], s[0:1], v[108:109] op_sel_hi:[1,0,1]
	v_pk_fma_f32 v[106:107], v[144:145], s[0:1], v[106:107] op_sel_hi:[1,0,1]
	v_pk_fma_f32 v[112:113], v[136:137], s[0:1], v[112:113] op_sel_hi:[1,0,1]
	v_pk_fma_f32 v[110:111], v[146:147], s[0:1], v[110:111] op_sel_hi:[1,0,1]
	v_pk_fma_f32 v[80:81], v[138:139], s[0:1], v[80:81] op_sel_hi:[1,0,1]
	v_pk_fma_f32 v[78:79], v[148:149], s[0:1], v[78:79] op_sel_hi:[1,0,1]
	v_pk_fma_f32 v[68:69], v[140:141], s[0:1], v[68:69] op_sel_hi:[1,0,1]
	v_pk_fma_f32 v[66:67], v[152:153], s[0:1], v[66:67] op_sel_hi:[1,0,1]
	s_nop 0
	v_or_b32_e32 v142, 48, v132
	v_ashrrev_i32_e32 v143, 31, v142
	v_lshlrev_b64 v[142:143], 11, v[142:143]
	v_lshl_add_u64 v[142:143], s[2:3], 0, v[142:143]
	v_lshl_add_u64 v[142:143], v[142:143], 0, v[162:163]
	s_waitcnt vmcnt(11)
	v_lshlrev_b32_e32 v144, 16, v192
	v_and_b32_e32 v145, 0xffff0000, v192
	v_lshlrev_b32_e32 v134, 16, v193
	v_and_b32_e32 v135, 0xffff0000, v193
	v_lshlrev_b32_e32 v146, 16, v194
	v_and_b32_e32 v147, 0xffff0000, v194
	v_lshlrev_b32_e32 v136, 16, v195
	v_and_b32_e32 v137, 0xffff0000, v195
	s_waitcnt vmcnt(10)
;     __device__ __forceinline__ void fused(f32x4 (&acc)[2][2][4][2], const Unit& u, int wr, int wc, int fr, int fq, PG8_LAS unsigned char* lds, int wid, int lane) const {
;     ...
;             for (int m = 0; m < 4; ++m) { const size_t off = (size_t)(u.pm * BM + ai * HALF + wr * 64 + m * 16 + fr) * ldc + col0;
; #pragma unroll
;                 for (int bj = 0; bj < 2; ++bj) { f32x4 b0, b1;
;                     if (base) { b0 = *(const f32x4*)(base + off + bj * HALF); b1 = *(const f32x4*)(base + off + bj * HALF + 4); }
;                     else { const u32x4 w = *(const u32x4*)(baseb + off + bj * HALF);
;                         b0 = (f32x4){__uint_as_float(w.x << 16), __uint_as_float(w.x & 0xffff0000u), __uint_as_float(w.y << 16), __uint_as_float(w.y & 0xffff0000u)};
;                         b1 = (f32x4){__uint_as_float(w.z << 16), __uint_as_float(w.z & 0xffff0000u), __uint_as_float(w.w << 16), __uint_as_float(w.w & 0xffff0000u)}; }
;                     acc[ai][bj][m][0] = acc[ai][bj][m][0] * s + b0 * alpha; acc[ai][bj][m][1] = acc[ai][bj][m][1] * s + b1 * alpha; }
	v_lshlrev_b32_e32 v148, 16, v196
	v_and_b32_e32 v149, 0xffff0000, v196
	v_lshlrev_b32_e32 v138, 16, v197
	v_and_b32_e32 v139, 0xffff0000, v197
	v_lshlrev_b32_e32 v152, 16, v198
	v_and_b32_e32 v153, 0xffff0000, v198
	v_lshlrev_b32_e32 v140, 16, v199
	v_and_b32_e32 v141, 0xffff0000, v199
	v_pk_fma_f32 v[116:117], v[134:135], s[0:1], v[116:117] op_sel_hi:[1,0,1]
	v_pk_fma_f32 v[114:115], v[144:145], s[0:1], v[114:115] op_sel_hi:[1,0,1]
	v_pk_fma_f32 v[124:125], v[136:137], s[0:1], v[124:125] op_sel_hi:[1,0,1]
	v_pk_fma_f32 v[122:123], v[146:147], s[0:1], v[122:123] op_sel_hi:[1,0,1]
	v_pk_fma_f32 v[100:101], v[138:139], s[0:1], v[100:101] op_sel_hi:[1,0,1]
	v_pk_fma_f32 v[98:99], v[148:149], s[0:1], v[98:99] op_sel_hi:[1,0,1]
	v_pk_fma_f32 v[88:89], v[140:141], s[0:1], v[88:89] op_sel_hi:[1,0,1]
	v_pk_fma_f32 v[86:87], v[152:153], s[0:1], v[86:87] op_sel_hi:[1,0,1]
	s_nop 0
	v_add_u32_e32 v142, 0x80, v132
	v_ashrrev_i32_e32 v143, 31, v142
	v_lshlrev_b64 v[142:143], 11, v[142:143]
	v_lshl_add_u64 v[142:143], s[2:3], 0, v[142:143]
	v_lshl_add_u64 v[142:143], v[142:143], 0, v[162:163]
	s_waitcnt vmcnt(9)
	v_lshlrev_b32_e32 v144, 16, v200
	v_and_b32_e32 v145, 0xffff0000, v200
	v_lshlrev_b32_e32 v134, 16, v201
	v_and_b32_e32 v135, 0xffff0000, v201
	v_lshlrev_b32_e32 v146, 16, v202
	v_and_b32_e32 v147, 0xffff0000, v202
	v_lshlrev_b32_e32 v136, 16, v203
	v_and_b32_e32 v137, 0xffff0000, v203
	s_waitcnt vmcnt(8)
	v_lshlrev_b32_e32 v148, 16, v204
	v_and_b32_e32 v149, 0xffff0000, v204
	v_lshlrev_b32_e32 v138, 16, v205
	v_and_b32_e32 v139, 0xffff0000, v205
	v_lshlrev_b32_e32 v152, 16, v206
	v_and_b32_e32 v153, 0xffff0000, v206
	v_lshlrev_b32_e32 v140, 16, v207
	v_and_b32_e32 v141, 0xffff0000, v207
	v_pk_fma_f32 v[128:129], v[134:135], s[0:1], v[128:129] op_sel_hi:[1,0,1]
	v_pk_fma_f32 v[126:127], v[144:145], s[0:1], v[126:127] op_sel_hi:[1,0,1]
	v_pk_fma_f32 v[120:121], v[136:137], s[0:1], v[120:121] op_sel_hi:[1,0,1]
	v_pk_fma_f32 v[118:119], v[146:147], s[0:1], v[118:119] op_sel_hi:[1,0,1]
	v_pk_fma_f32 v[84:85], v[138:139], s[0:1], v[84:85] op_sel_hi:[1,0,1]
	v_pk_fma_f32 v[82:83], v[148:149], s[0:1], v[82:83] op_sel_hi:[1,0,1]
	v_pk_fma_f32 v[72:73], v[140:141], s[0:1], v[72:73] op_sel_hi:[1,0,1]
	v_pk_fma_f32 v[70:71], v[152:153], s[0:1], v[70:71] op_sel_hi:[1,0,1]
	s_nop 0
	v_add_u32_e32 v142, 0x90, v132
	v_ashrrev_i32_e32 v143, 31, v142
	v_lshlrev_b64 v[142:143], 11, v[142:143]
	v_lshl_add_u64 v[142:143], s[2:3], 0, v[142:143]
	v_lshl_add_u64 v[142:143], v[142:143], 0, v[162:163]
	s_waitcnt vmcnt(7)
	v_lshlrev_b32_e32 v144, 16, v208
	v_and_b32_e32 v145, 0xffff0000, v208
	v_lshlrev_b32_e32 v134, 16, v209
	v_and_b32_e32 v135, 0xffff0000, v209
	v_lshlrev_b32_e32 v146, 16, v210
	v_and_b32_e32 v147, 0xffff0000, v210
	v_lshlrev_b32_e32 v136, 16, v211
	v_and_b32_e32 v137, 0xffff0000, v211
	s_waitcnt vmcnt(6)
	v_lshlrev_b32_e32 v148, 16, v212
	v_and_b32_e32 v149, 0xffff0000, v212
	v_lshlrev_b32_e32 v138, 16, v213
	v_and_b32_e32 v139, 0xffff0000, v213
	v_lshlrev_b32_e32 v152, 16, v214
	v_and_b32_e32 v153, 0xffff0000, v214
	v_lshlrev_b32_e32 v140, 16, v215
	v_and_b32_e32 v141, 0xffff0000, v215
	v_pk_fma_f32 v[64:65], v[134:135], s[0:1], v[64:65] op_sel_hi:[1,0,1]
	v_pk_fma_f32 v[62:63], v[144:145], s[0:1], v[62:63] op_sel_hi:[1,0,1]
	v_pk_fma_f32 v[60:61], v[136:137], s[0:1], v[60:61] op_sel_hi:[1,0,1]
	v_pk_fma_f32 v[58:59], v[146:147], s[0:1], v[58:59] op_sel_hi:[1,0,1]
	v_pk_fma_f32 v[56:57], v[138:139], s[0:1], v[56:57] op_sel_hi:[1,0,1]
	v_pk_fma_f32 v[54:55], v[148:149], s[0:1], v[54:55] op_sel_hi:[1,0,1]
	v_pk_fma_f32 v[52:53], v[140:141], s[0:1], v[52:53] op_sel_hi:[1,0,1]
	v_pk_fma_f32 v[50:51], v[152:153], s[0:1], v[50:51] op_sel_hi:[1,0,1]
	s_nop 0
	v_add_u32_e32 v142, 0xa0, v132
	v_ashrrev_i32_e32 v143, 31, v142
	v_lshlrev_b64 v[142:143], 11, v[142:143]
	v_lshl_add_u64 v[142:143], s[2:3], 0, v[142:143]
	v_lshl_add_u64 v[142:143], v[142:143], 0, v[162:163]
	s_waitcnt vmcnt(5)
	v_lshlrev_b32_e32 v144, 16, v216
	v_and_b32_e32 v145, 0xffff0000, v216
	v_lshlrev_b32_e32 v134, 16, v217
	v_and_b32_e32 v135, 0xffff0000, v217
	v_lshlrev_b32_e32 v146, 16, v218
	v_and_b32_e32 v147, 0xffff0000, v218
	v_lshlrev_b32_e32 v136, 16, v219
	v_and_b32_e32 v137, 0xffff0000, v219
	s_waitcnt vmcnt(4)
	v_lshlrev_b32_e32 v148, 16, v220
	v_and_b32_e32 v149, 0xffff0000, v220
	v_lshlrev_b32_e32 v138, 16, v221
	v_and_b32_e32 v139, 0xffff0000, v221
	v_lshlrev_b32_e32 v152, 16, v222
	v_and_b32_e32 v153, 0xffff0000, v222
	v_lshlrev_b32_e32 v140, 16, v223
	v_and_b32_e32 v141, 0xffff0000, v223
	v_pk_fma_f32 v[48:49], v[134:135], s[0:1], v[48:49] op_sel_hi:[1,0,1]
	v_pk_fma_f32 v[46:47], v[144:145], s[0:1], v[46:47] op_sel_hi:[1,0,1]
	v_pk_fma_f32 v[44:45], v[136:137], s[0:1], v[44:45] op_sel_hi:[1,0,1]
	v_pk_fma_f32 v[42:43], v[146:147], s[0:1], v[42:43] op_sel_hi:[1,0,1]
	v_pk_fma_f32 v[40:41], v[138:139], s[0:1], v[40:41] op_sel_hi:[1,0,1]
	v_pk_fma_f32 v[38:39], v[148:149], s[0:1], v[38:39] op_sel_hi:[1,0,1]
	v_pk_fma_f32 v[36:37], v[140:141], s[0:1], v[36:37] op_sel_hi:[1,0,1]
	v_pk_fma_f32 v[34:35], v[152:153], s[0:1], v[34:35] op_sel_hi:[1,0,1]
	v_mov_b32_e32 v146, v95
	v_and_b32_e32 v142, 64, v133
	v_xor_b32_e32 v143, 16, v133
	v_add_u32_e32 v158, 64, v142
	v_add_u32_e32 v142, 0xb0, v132
	v_cmp_lt_i32_e32 vcc, v143, v158
	v_mov_b32_e32 v147, v96
	v_mov_b32_e32 v148, v94
	v_cndmask_b32_e32 v132, v133, v143, vcc
	v_ashrrev_i32_e32 v143, 31, v142
	v_lshlrev_b64 v[142:143], 11, v[142:143]
	v_lshl_add_u64 v[142:143], s[2:3], 0, v[142:143]
	v_lshl_add_u64 v[142:143], v[142:143], 0, v[162:163]
	v_mov_b32_e32 v149, v97
	v_pk_add_f32 v[146:147], v[146:147], v[148:149]
	v_lshlrev_b32_e32 v132, 2, v132
	v_add_f32_e32 v146, v146, v147
	s_waitcnt vmcnt(3)
;     __device__ __forceinline__ bool run(const f32x4 (&v)[2][2][4][2], const Unit& u, int wr, int wc, int fr, int fq, PG8_LAS unsigned char* lds, int wid, int lane) const {
;     ...
;                 float s = 0.f;
; #pragma unroll
;                 for (int bj = 0; bj < 2; ++bj)
; #pragma unroll
;                     for (int n = 0; n < 2; ++n) { const f32x4 x = v[ai][bj][m][n]; s += (x[0] + x[1]) + (x[2] + x[3]); }
;                 s += __shfl_xor(s, 16); s += __shfl_xor(s, 32);
;                 const float mw = s * (1.0f / 64.0f); float q = 0.f;
; #pragma unroll
;                 for (int bj = 0; bj < 2; ++bj)
; #pragma unroll
;                     for (int n = 0; n < 2; ++n) { const f32x4 d = v[ai][bj][m][n] - mw; q += (d[0] * d[0] + d[1] * d[1]) + (d[2] * d[2] + d[3] * d[3]); }
;                 q += __shfl_xor(q, 16); q += __shfl_xor(q, 32);
;                 if (fq == 0) P[(ai * HALF + wr * 64 + m * 16 + fr) * 4 + wc] = (f32x2v){mw, q};
	v_lshlrev_b32_e32 v144, 16, v224
	v_and_b32_e32 v145, 0xffff0000, v224
	v_lshlrev_b32_e32 v134, 16, v225
	v_and_b32_e32 v135, 0xffff0000, v225
	v_lshlrev_b32_e32 v152, 16, v226
	v_and_b32_e32 v153, 0xffff0000, v226
	v_lshlrev_b32_e32 v136, 16, v227
	v_and_b32_e32 v137, 0xffff0000, v227
	s_waitcnt vmcnt(2)
	v_lshlrev_b32_e32 v154, 16, v228
	v_and_b32_e32 v155, 0xffff0000, v228
	v_lshlrev_b32_e32 v138, 16, v229
	v_and_b32_e32 v139, 0xffff0000, v229
	v_lshlrev_b32_e32 v156, 16, v230
	v_and_b32_e32 v157, 0xffff0000, v230
	v_lshlrev_b32_e32 v140, 16, v231
	v_and_b32_e32 v141, 0xffff0000, v231
	v_pk_fma_f32 v[32:33], v[134:135], s[0:1], v[32:33] op_sel_hi:[1,0,1]
	v_pk_fma_f32 v[30:31], v[144:145], s[0:1], v[30:31] op_sel_hi:[1,0,1]
	v_pk_fma_f32 v[28:29], v[136:137], s[0:1], v[28:29] op_sel_hi:[1,0,1]
	v_pk_fma_f32 v[26:27], v[152:153], s[0:1], v[26:27] op_sel_hi:[1,0,1]
	v_pk_fma_f32 v[24:25], v[138:139], s[0:1], v[24:25] op_sel_hi:[1,0,1]
	v_pk_fma_f32 v[22:23], v[154:155], s[0:1], v[22:23] op_sel_hi:[1,0,1]
	v_pk_fma_f32 v[20:21], v[140:141], s[0:1], v[20:21] op_sel_hi:[1,0,1]
	v_pk_fma_f32 v[18:19], v[156:157], s[0:1], v[18:19] op_sel_hi:[1,0,1]
	v_mov_b32_e32 v134, v103
	v_mov_b32_e32 v135, v104
	v_mov_b32_e32 v136, v102
	v_mov_b32_e32 v137, v105
	v_pk_add_f32 v[134:135], v[134:135], v[136:137]
	v_add_f32_e32 v153, v90, v91
	v_pk_add_f32 v[134:135], v[134:135], v[134:135] op_sel_hi:[0,1]
	v_add_f32_e32 v155, v92, v93
	v_mov_b32_e32 v152, v74
	v_mov_b32_e32 v154, v75
	v_mov_b32_e32 v156, v77
	v_add_f32_e32 v157, 0, v146
	v_mov_b32_e32 v134, v76
	v_pk_add_f32 v[136:137], v[152:153], v[154:155]
	v_pk_add_f32 v[134:135], v[134:135], v[156:157]
	s_nop 0
	v_pk_add_f32 v[134:135], v[136:137], v[134:135]
	v_xor_b32_e32 v136, 32, v133
	v_add_f32_e32 v134, v134, v135
	v_mov_b32_e32 v135, v134
	s_nop 1
	v_permlane16_swap_b32 v134, v135
	v_cmp_lt_i32_e32 vcc, v136, v158
	s_waitcnt lgkmcnt(0)
	v_add_f32_e32 v134, v134, v135
	v_cndmask_b32_e32 v133, v133, v136, vcc
	v_lshlrev_b32_e32 v133, 2, v133
	v_mov_b32_e32 v135, v134
	s_nop 1
	v_permlane32_swap_b32 v134, v135
	s_waitcnt lgkmcnt(0)
	v_add_f32_e32 v135, v134, v135
	v_fmamk_f32 v136, v135, 0xbc800000, v97
	v_fmamk_f32 v146, v135, 0xbc800000, v95
	v_fmamk_f32 v148, v135, 0xbc800000, v105
	v_fmamk_f32 v152, v135, 0xbc800000, v103
	v_fmamk_f32 v134, v135, 0xbc800000, v96
	v_fmamk_f32 v137, v135, 0xbc800000, v94
	v_fmamk_f32 v147, v135, 0xbc800000, v104
	v_fmamk_f32 v149, v135, 0xbc800000, v102
	v_fmamk_f32 v154, v135, 0xbc800000, v93
	v_fmamk_f32 v156, v135, 0xbc800000, v91
	v_mul_f32_e32 v146, v146, v146
	v_mul_f32_e32 v136, v136, v136
	v_mul_f32_e32 v152, v152, v152
	v_mul_f32_e32 v148, v148, v148
	v_fmamk_f32 v153, v135, 0xbc800000, v92
	v_fmamk_f32 v155, v135, 0xbc800000, v90
	v_fmamk_f32 v158, v135, 0xbc800000, v77
	v_fmamk_f32 v160, v135, 0xbc800000, v75
	v_mul_f32_e32 v156, v156, v156
	v_mul_f32_e32 v154, v154, v154
	v_fmac_f32_e32 v146, v137, v137
	v_fmac_f32_e32 v136, v134, v134
	v_fmac_f32_e32 v152, v149, v149
	v_fmac_f32_e32 v148, v147, v147
	v_fmamk_f32 v157, v135, 0xbc800000, v76
	v_fmamk_f32 v159, v135, 0xbc800000, v74
	v_mul_f32_e32 v160, v160, v160
	v_mul_f32_e32 v158, v158, v158
	v_fmac_f32_e32 v156, v155, v155
	v_fmac_f32_e32 v154, v153, v153
	v_add_f32_e32 v134, v146, v136
	v_add_f32_e32 v136, v152, v148
	v_fmac_f32_e32 v160, v159, v159
	v_fmac_f32_e32 v158, v157, v157
	v_add_f32_e32 v137, v156, v154
	v_add_f32_e32 v134, v134, v136
	v_add_f32_e32 v146, v160, v158
	v_add_f32_e32 v134, v137, v134
	v_add_f32_e32 v136, v146, v134
	v_mov_b32_e32 v137, v136
	s_nop 1
	v_permlane16_swap_b32 v136, v137
	v_and_b32_e32 v134, 63, v150
	v_cmp_gt_u32_e32 vcc, 16, v134
	s_waitcnt lgkmcnt(0)
	v_add_f32_e32 v136, v136, v137
	v_mov_b32_e32 v137, v136
	s_nop 1
	v_permlane32_swap_b32 v136, v137
	s_waitcnt vmcnt(1)
	v_lshlrev_b32_e32 v146, 16, v232
	v_and_b32_e32 v147, 0xffff0000, v232
	v_lshlrev_b32_e32 v138, 16, v233
	v_and_b32_e32 v139, 0xffff0000, v233
	v_lshlrev_b32_e32 v148, 16, v234
	v_and_b32_e32 v149, 0xffff0000, v234
	v_lshlrev_b32_e32 v140, 16, v235
	v_and_b32_e32 v141, 0xffff0000, v235
	s_waitcnt vmcnt(0)
	v_lshlrev_b32_e32 v152, 16, v236
	v_and_b32_e32 v153, 0xffff0000, v236
	v_lshlrev_b32_e32 v142, 16, v237
	v_and_b32_e32 v143, 0xffff0000, v237
	v_lshlrev_b32_e32 v154, 16, v238
	v_and_b32_e32 v155, 0xffff0000, v238
	v_lshlrev_b32_e32 v144, 16, v239
	v_and_b32_e32 v145, 0xffff0000, v239
	v_pk_fma_f32 v[16:17], v[138:139], s[0:1], v[16:17] op_sel_hi:[1,0,1]
	v_pk_fma_f32 v[14:15], v[146:147], s[0:1], v[14:15] op_sel_hi:[1,0,1]
	v_pk_fma_f32 v[12:13], v[140:141], s[0:1], v[12:13] op_sel_hi:[1,0,1]
	v_pk_fma_f32 v[10:11], v[148:149], s[0:1], v[10:11] op_sel_hi:[1,0,1]
	v_pk_fma_f32 v[8:9], v[142:143], s[0:1], v[8:9] op_sel_hi:[1,0,1]
	v_pk_fma_f32 v[6:7], v[152:153], s[0:1], v[6:7] op_sel_hi:[1,0,1]
	v_pk_fma_f32 v[4:5], v[144:145], s[0:1], v[4:5] op_sel_hi:[1,0,1]
	v_pk_fma_f32 v[2:3], v[154:155], s[0:1], v[2:3] op_sel_hi:[1,0,1]
	s_lshl_b32 s0, s13, 3
	s_add_i32 s2, s0, 0
	s_and_saveexec_b64 s[0:1], vcc
	s_cbranch_execz .LBB0_1498
	s_lshl_b32 s3, s17, 11
	s_add_i32 s3, s2, s3
	v_mul_f32_e32 v138, 0x3c800000, v135
	v_lshl_add_u32 v135, v151, 5, s3
	s_waitcnt lgkmcnt(0)
	v_add_f32_e32 v139, v136, v137
	ds_write_b64 v135, v[138:139]
;     __device__ __forceinline__ bool run(const f32x4 (&v)[2][2][4][2], const Unit& u, int wr, int wc, int fr, int fq, PG8_LAS unsigned char* lds, int wid, int lane) const {
;     ...
;                 float s = 0.f;
; #pragma unroll
;                 for (int bj = 0; bj < 2; ++bj)
; #pragma unroll
;                     for (int n = 0; n < 2; ++n) { const f32x4 x = v[ai][bj][m][n]; s += (x[0] + x[1]) + (x[2] + x[3]); }
;                 s += __shfl_xor(s, 16); s += __shfl_xor(s, 32);
;                 const float mw = s * (1.0f / 64.0f); float q = 0.f;
; #pragma unroll
;                 for (int bj = 0; bj < 2; ++bj)
; #pragma unroll
;                     for (int n = 0; n < 2; ++n) { const f32x4 d = v[ai][bj][m][n] - mw; q += (d[0] * d[0] + d[1] * d[1]) + (d[2] * d[2] + d[3] * d[3]); }
;                 q += __shfl_xor(q, 16); q += __shfl_xor(q, 32);
;                 if (fq == 0) P[(ai * HALF + wr * 64 + m * 16 + fr) * 4 + wc] = (f32x2v){mw, q};
.LBB0_1498:
	s_or_b64 exec, exec, s[0:1]
	v_mov_b32_e32 v136, v107
	s_waitcnt lgkmcnt(0)
	v_mov_b32_e32 v137, v108
	v_mov_b32_e32 v138, v106
	v_mov_b32_e32 v139, v109
	v_pk_add_f32 v[136:137], v[136:137], v[138:139]
	v_mov_b32_e32 v138, v111
	v_mov_b32_e32 v139, v112
	v_mov_b32_e32 v140, v110
	v_mov_b32_e32 v141, v113
	v_pk_add_f32 v[138:139], v[138:139], v[140:141]
	v_add_f32_e32 v135, v136, v137
	v_pk_add_f32 v[138:139], v[138:139], v[138:139] op_sel_hi:[0,1]
	v_add_f32_e32 v137, 0, v135
	v_add_f32_e32 v141, v78, v79
	v_add_f32_e32 v143, v80, v81
	v_mov_b32_e32 v140, v66
	v_mov_b32_e32 v142, v67
	v_mov_b32_e32 v138, v68
	v_mov_b32_e32 v136, v69
	v_pk_add_f32 v[140:141], v[140:141], v[142:143]
	v_pk_add_f32 v[136:137], v[138:139], v[136:137]
	s_nop 0
	v_pk_add_f32 v[136:137], v[140:141], v[136:137]
	s_nop 0
	v_add_f32_e32 v135, v136, v137
	v_mov_b32_e32 v136, v135
	s_nop 1
	v_permlane16_swap_b32 v135, v136
	s_waitcnt lgkmcnt(0)
	v_add_f32_e32 v135, v135, v136
	v_mov_b32_e32 v136, v135
	s_nop 1
	v_permlane32_swap_b32 v135, v136
	s_waitcnt lgkmcnt(0)
	v_add_f32_e32 v135, v135, v136
	v_fmamk_f32 v137, v135, 0xbc800000, v109
	v_fmamk_f32 v139, v135, 0xbc800000, v107
	v_fmamk_f32 v136, v135, 0xbc800000, v108
	v_fmamk_f32 v138, v135, 0xbc800000, v106
	v_mul_f32_e32 v139, v139, v139
	v_mul_f32_e32 v137, v137, v137
	v_fmac_f32_e32 v139, v138, v138
	v_fmac_f32_e32 v137, v136, v136
	v_fmamk_f32 v138, v135, 0xbc800000, v113
	v_fmamk_f32 v140, v135, 0xbc800000, v111
	v_add_f32_e32 v136, v139, v137
	v_fmamk_f32 v137, v135, 0xbc800000, v112
	v_fmamk_f32 v139, v135, 0xbc800000, v110
	v_mul_f32_e32 v140, v140, v140
	v_mul_f32_e32 v138, v138, v138
	v_fmac_f32_e32 v140, v139, v139
	v_fmac_f32_e32 v138, v137, v137
	v_add_f32_e32 v137, v140, v138
	v_fmamk_f32 v138, v135, 0xbc800000, v81
	v_fmamk_f32 v140, v135, 0xbc800000, v79
	v_add_f32_e32 v136, v136, v137
	v_fmamk_f32 v137, v135, 0xbc800000, v80
	v_fmamk_f32 v139, v135, 0xbc800000, v78
	v_mul_f32_e32 v140, v140, v140
	v_mul_f32_e32 v138, v138, v138
	v_fmac_f32_e32 v140, v139, v139
	v_fmac_f32_e32 v138, v137, v137
	v_add_f32_e32 v137, v140, v138
	v_fmamk_f32 v138, v135, 0xbc800000, v69
	v_fmamk_f32 v140, v135, 0xbc800000, v67
	v_add_f32_e32 v136, v137, v136
	v_fmamk_f32 v137, v135, 0xbc800000, v68
	v_fmamk_f32 v139, v135, 0xbc800000, v66
	v_mul_f32_e32 v140, v140, v140
	v_mul_f32_e32 v138, v138, v138
	v_fmac_f32_e32 v140, v139, v139
	v_fmac_f32_e32 v138, v137, v137
	v_add_f32_e32 v137, v140, v138
	v_add_f32_e32 v136, v137, v136
	v_mov_b32_e32 v137, v136
	s_nop 1
	v_permlane16_swap_b32 v136, v137
	s_waitcnt lgkmcnt(0)
	v_add_f32_e32 v136, v136, v137
	v_mov_b32_e32 v137, v136
	s_nop 1
	v_permlane32_swap_b32 v136, v137
	s_and_saveexec_b64 s[0:1], vcc
	s_cbranch_execz .LBB0_1500
	s_lshl_b32 s3, s17, 11
	s_add_i32 s3, s2, s3
	v_mul_f32_e32 v138, 0x3c800000, v135
	v_lshl_add_u32 v135, v151, 5, s3
	s_waitcnt lgkmcnt(0)
	v_add_f32_e32 v139, v136, v137
	ds_write_b64 v135, v[138:139] offset:512
.LBB0_1500:
	s_or_b64 exec, exec, s[0:1]
	v_mov_b32_e32 v136, v115
	s_waitcnt lgkmcnt(0)
	v_mov_b32_e32 v137, v116
	v_mov_b32_e32 v138, v114
	v_mov_b32_e32 v139, v117
	v_pk_add_f32 v[136:137], v[136:137], v[138:139]
	v_mov_b32_e32 v138, v123
	v_mov_b32_e32 v139, v124
	v_mov_b32_e32 v140, v122
	v_mov_b32_e32 v141, v125
	v_pk_add_f32 v[138:139], v[138:139], v[140:141]
	v_add_f32_e32 v135, v136, v137
	v_pk_add_f32 v[138:139], v[138:139], v[138:139] op_sel_hi:[0,1]
	v_add_f32_e32 v137, 0, v135
	v_add_f32_e32 v141, v98, v99
	v_add_f32_e32 v143, v100, v101
	v_mov_b32_e32 v140, v86
	v_mov_b32_e32 v142, v87
	v_mov_b32_e32 v138, v88
	v_mov_b32_e32 v136, v89
	v_pk_add_f32 v[140:141], v[140:141], v[142:143]
	v_pk_add_f32 v[136:137], v[138:139], v[136:137]
	s_nop 0
	v_pk_add_f32 v[136:137], v[140:141], v[136:137]
	s_nop 0
	v_add_f32_e32 v135, v136, v137
	v_mov_b32_e32 v136, v135
	s_nop 1
	v_permlane16_swap_b32 v135, v136
	s_waitcnt lgkmcnt(0)
	v_add_f32_e32 v135, v135, v136
	v_mov_b32_e32 v136, v135
	s_nop 1
	v_permlane32_swap_b32 v135, v136
	s_waitcnt lgkmcnt(0)
	v_add_f32_e32 v135, v135, v136
	v_fmamk_f32 v137, v135, 0xbc800000, v117
	v_fmamk_f32 v139, v135, 0xbc800000, v115
	v_fmamk_f32 v136, v135, 0xbc800000, v116
	v_fmamk_f32 v138, v135, 0xbc800000, v114
	v_mul_f32_e32 v139, v139, v139
	v_mul_f32_e32 v137, v137, v137
	v_fmac_f32_e32 v139, v138, v138
	v_fmac_f32_e32 v137, v136, v136
	v_fmamk_f32 v138, v135, 0xbc800000, v125
	v_fmamk_f32 v140, v135, 0xbc800000, v123
	v_add_f32_e32 v136, v139, v137
	v_fmamk_f32 v137, v135, 0xbc800000, v124
	v_fmamk_f32 v139, v135, 0xbc800000, v122
	v_mul_f32_e32 v140, v140, v140
	v_mul_f32_e32 v138, v138, v138
	v_fmac_f32_e32 v140, v139, v139
	v_fmac_f32_e32 v138, v137, v137
	v_add_f32_e32 v137, v140, v138
	v_fmamk_f32 v138, v135, 0xbc800000, v101
	v_fmamk_f32 v140, v135, 0xbc800000, v99
	v_add_f32_e32 v136, v136, v137
	v_fmamk_f32 v137, v135, 0xbc800000, v100
	v_fmamk_f32 v139, v135, 0xbc800000, v98
	v_mul_f32_e32 v140, v140, v140
	v_mul_f32_e32 v138, v138, v138
	v_fmac_f32_e32 v140, v139, v139
	v_fmac_f32_e32 v138, v137, v137
	v_add_f32_e32 v137, v140, v138
	v_fmamk_f32 v138, v135, 0xbc800000, v89
	v_fmamk_f32 v140, v135, 0xbc800000, v87
	v_add_f32_e32 v136, v137, v136
	v_fmamk_f32 v137, v135, 0xbc800000, v88
	v_fmamk_f32 v139, v135, 0xbc800000, v86
	v_mul_f32_e32 v140, v140, v140
	v_mul_f32_e32 v138, v138, v138
	v_fmac_f32_e32 v140, v139, v139
	v_fmac_f32_e32 v138, v137, v137
	v_add_f32_e32 v137, v140, v138
	v_add_f32_e32 v136, v137, v136
	v_mov_b32_e32 v137, v136
	s_nop 1
	v_permlane16_swap_b32 v136, v137
	s_waitcnt lgkmcnt(0)
	v_add_f32_e32 v136, v136, v137
	v_mov_b32_e32 v137, v136
	s_nop 1
	v_permlane32_swap_b32 v136, v137
	s_and_saveexec_b64 s[0:1], vcc
	s_cbranch_execz .LBB0_1502
	s_lshl_b32 s3, s17, 11
	s_add_i32 s3, s2, s3
	v_mul_f32_e32 v138, 0x3c800000, v135
	v_lshl_add_u32 v135, v151, 5, s3
	s_waitcnt lgkmcnt(0)
	v_add_f32_e32 v139, v136, v137
	ds_write_b64 v135, v[138:139] offset:1024
;     __device__ __forceinline__ bool run(const f32x4 (&v)[2][2][4][2], const Unit& u, int wr, int wc, int fr, int fq, PG8_LAS unsigned char* lds, int wid, int lane) const {
;     ...
;                 float s = 0.f;
; #pragma unroll
;                 for (int bj = 0; bj < 2; ++bj)
; #pragma unroll
;                     for (int n = 0; n < 2; ++n) { const f32x4 x = v[ai][bj][m][n]; s += (x[0] + x[1]) + (x[2] + x[3]); }
;                 s += __shfl_xor(s, 16); s += __shfl_xor(s, 32);
;                 const float mw = s * (1.0f / 64.0f); float q = 0.f;
; #pragma unroll
;                 for (int bj = 0; bj < 2; ++bj)
; #pragma unroll
;                     for (int n = 0; n < 2; ++n) { const f32x4 d = v[ai][bj][m][n] - mw; q += (d[0] * d[0] + d[1] * d[1]) + (d[2] * d[2] + d[3] * d[3]); }
;                 q += __shfl_xor(q, 16); q += __shfl_xor(q, 32);
;                 if (fq == 0) P[(ai * HALF + wr * 64 + m * 16 + fr) * 4 + wc] = (f32x2v){mw, q};
.LBB0_1502:
	s_or_b64 exec, exec, s[0:1]
	v_mov_b32_e32 v136, v127
	s_waitcnt lgkmcnt(0)
	v_mov_b32_e32 v137, v128
	v_mov_b32_e32 v138, v126
	v_mov_b32_e32 v139, v129
	v_pk_add_f32 v[136:137], v[136:137], v[138:139]
	v_mov_b32_e32 v138, v119
	v_mov_b32_e32 v139, v120
	v_mov_b32_e32 v140, v118
	v_mov_b32_e32 v141, v121
	v_pk_add_f32 v[138:139], v[138:139], v[140:141]
	v_add_f32_e32 v135, v136, v137
	v_pk_add_f32 v[138:139], v[138:139], v[138:139] op_sel_hi:[0,1]
	v_add_f32_e32 v137, 0, v135
	v_add_f32_e32 v141, v82, v83
	v_add_f32_e32 v143, v84, v85
	v_mov_b32_e32 v140, v70
	v_mov_b32_e32 v142, v71
	v_mov_b32_e32 v138, v72
	v_mov_b32_e32 v136, v73
	v_pk_add_f32 v[140:141], v[140:141], v[142:143]
	v_pk_add_f32 v[136:137], v[138:139], v[136:137]
	s_nop 0
	v_pk_add_f32 v[136:137], v[140:141], v[136:137]
	s_nop 0
	v_add_f32_e32 v135, v136, v137
	v_mov_b32_e32 v136, v135
	s_nop 1
	v_permlane16_swap_b32 v135, v136
	s_waitcnt lgkmcnt(0)
	v_add_f32_e32 v135, v135, v136
	v_mov_b32_e32 v136, v135
	s_nop 1
	v_permlane32_swap_b32 v135, v136
	s_waitcnt lgkmcnt(0)
	v_add_f32_e32 v135, v135, v136
	v_fmamk_f32 v137, v135, 0xbc800000, v129
	v_fmamk_f32 v139, v135, 0xbc800000, v127
	v_fmamk_f32 v136, v135, 0xbc800000, v128
	v_fmamk_f32 v138, v135, 0xbc800000, v126
	v_mul_f32_e32 v139, v139, v139
	v_mul_f32_e32 v137, v137, v137
	v_fmac_f32_e32 v139, v138, v138
	v_fmac_f32_e32 v137, v136, v136
	v_fmamk_f32 v138, v135, 0xbc800000, v121
	v_fmamk_f32 v140, v135, 0xbc800000, v119
	v_add_f32_e32 v136, v139, v137
	v_fmamk_f32 v137, v135, 0xbc800000, v120
	v_fmamk_f32 v139, v135, 0xbc800000, v118
	v_mul_f32_e32 v140, v140, v140
	v_mul_f32_e32 v138, v138, v138
	v_fmac_f32_e32 v140, v139, v139
	v_fmac_f32_e32 v138, v137, v137
	v_add_f32_e32 v137, v140, v138
	v_fmamk_f32 v138, v135, 0xbc800000, v85
	v_fmamk_f32 v140, v135, 0xbc800000, v83
	v_add_f32_e32 v136, v136, v137
	v_fmamk_f32 v137, v135, 0xbc800000, v84
	v_fmamk_f32 v139, v135, 0xbc800000, v82
	v_mul_f32_e32 v140, v140, v140
	v_mul_f32_e32 v138, v138, v138
	v_fmac_f32_e32 v140, v139, v139
	v_fmac_f32_e32 v138, v137, v137
	v_add_f32_e32 v137, v140, v138
	v_fmamk_f32 v138, v135, 0xbc800000, v73
	v_fmamk_f32 v140, v135, 0xbc800000, v71
	v_add_f32_e32 v136, v137, v136
	v_fmamk_f32 v137, v135, 0xbc800000, v72
	v_fmamk_f32 v139, v135, 0xbc800000, v70
	v_mul_f32_e32 v140, v140, v140
	v_mul_f32_e32 v138, v138, v138
	v_fmac_f32_e32 v140, v139, v139
	v_fmac_f32_e32 v138, v137, v137
	v_add_f32_e32 v137, v140, v138
	v_add_f32_e32 v136, v137, v136
	v_mov_b32_e32 v137, v136
	s_nop 1
	v_permlane16_swap_b32 v136, v137
	s_waitcnt lgkmcnt(0)
	v_add_f32_e32 v136, v136, v137
	v_mov_b32_e32 v137, v136
	s_nop 1
	v_permlane32_swap_b32 v136, v137
	s_and_saveexec_b64 s[0:1], vcc
	s_cbranch_execz .LBB0_1504
	s_lshl_b32 s3, s17, 11
	s_add_i32 s3, s2, s3
	v_mul_f32_e32 v138, 0x3c800000, v135
	v_lshl_add_u32 v135, v151, 5, s3
	s_waitcnt lgkmcnt(0)
	v_add_f32_e32 v139, v136, v137
	ds_write_b64 v135, v[138:139] offset:1536
.LBB0_1504:
	s_or_b64 exec, exec, s[0:1]
	v_mov_b32_e32 v136, v63
	s_waitcnt lgkmcnt(0)
	v_mov_b32_e32 v137, v64
	v_mov_b32_e32 v138, v62
	v_mov_b32_e32 v139, v65
	v_pk_add_f32 v[136:137], v[136:137], v[138:139]
	v_mov_b32_e32 v138, v59
	v_mov_b32_e32 v139, v60
	v_mov_b32_e32 v140, v58
	v_mov_b32_e32 v141, v61
	v_pk_add_f32 v[138:139], v[138:139], v[140:141]
	v_add_f32_e32 v135, v136, v137
	v_pk_add_f32 v[138:139], v[138:139], v[138:139] op_sel_hi:[0,1]
	v_add_f32_e32 v137, 0, v135
	v_add_f32_e32 v141, v54, v55
	v_add_f32_e32 v143, v56, v57
	v_mov_b32_e32 v140, v50
	v_mov_b32_e32 v142, v51
	v_mov_b32_e32 v138, v52
	v_mov_b32_e32 v136, v53
	v_pk_add_f32 v[140:141], v[140:141], v[142:143]
	v_pk_add_f32 v[136:137], v[138:139], v[136:137]
	s_nop 0
	v_pk_add_f32 v[136:137], v[140:141], v[136:137]
	s_nop 0
	v_add_f32_e32 v135, v136, v137
	v_mov_b32_e32 v136, v135
	s_nop 1
	v_permlane16_swap_b32 v135, v136
	s_waitcnt lgkmcnt(0)
	v_add_f32_e32 v135, v135, v136
	v_mov_b32_e32 v136, v135
	s_nop 1
	v_permlane32_swap_b32 v135, v136
	s_waitcnt lgkmcnt(0)
	v_add_f32_e32 v135, v135, v136
	v_fmamk_f32 v137, v135, 0xbc800000, v65
	v_fmamk_f32 v139, v135, 0xbc800000, v63
	v_fmamk_f32 v136, v135, 0xbc800000, v64
	v_fmamk_f32 v138, v135, 0xbc800000, v62
	v_mul_f32_e32 v139, v139, v139
	v_mul_f32_e32 v137, v137, v137
	v_fmac_f32_e32 v139, v138, v138
	v_fmac_f32_e32 v137, v136, v136
	v_fmamk_f32 v138, v135, 0xbc800000, v61
	v_fmamk_f32 v140, v135, 0xbc800000, v59
	v_add_f32_e32 v136, v139, v137
	v_fmamk_f32 v137, v135, 0xbc800000, v60
	v_fmamk_f32 v139, v135, 0xbc800000, v58
	v_mul_f32_e32 v140, v140, v140
	v_mul_f32_e32 v138, v138, v138
	v_fmac_f32_e32 v140, v139, v139
	v_fmac_f32_e32 v138, v137, v137
	v_add_f32_e32 v137, v140, v138
	v_fmamk_f32 v138, v135, 0xbc800000, v57
	v_fmamk_f32 v140, v135, 0xbc800000, v55
	v_add_f32_e32 v136, v136, v137
	v_fmamk_f32 v137, v135, 0xbc800000, v56
	v_fmamk_f32 v139, v135, 0xbc800000, v54
	v_mul_f32_e32 v140, v140, v140
	v_mul_f32_e32 v138, v138, v138
	v_fmac_f32_e32 v140, v139, v139
	v_fmac_f32_e32 v138, v137, v137
	v_add_f32_e32 v137, v140, v138
	v_fmamk_f32 v138, v135, 0xbc800000, v53
	v_fmamk_f32 v140, v135, 0xbc800000, v51
	v_add_f32_e32 v136, v137, v136
	v_fmamk_f32 v137, v135, 0xbc800000, v52
	v_fmamk_f32 v139, v135, 0xbc800000, v50
	v_mul_f32_e32 v140, v140, v140
	v_mul_f32_e32 v138, v138, v138
	v_fmac_f32_e32 v140, v139, v139
	v_fmac_f32_e32 v138, v137, v137
	v_add_f32_e32 v137, v140, v138
	v_add_f32_e32 v136, v137, v136
	v_mov_b32_e32 v137, v136
	s_nop 1
	v_permlane16_swap_b32 v136, v137
	s_waitcnt lgkmcnt(0)
	v_add_f32_e32 v136, v136, v137
	v_mov_b32_e32 v137, v136
	s_nop 1
	v_permlane32_swap_b32 v136, v137
	s_and_saveexec_b64 s[0:1], vcc
	s_cbranch_execz .LBB0_1506
	s_lshl_b32 s3, s17, 11
	s_add_i32 s3, s2, s3
	v_mul_f32_e32 v138, 0x3c800000, v135
	v_lshl_add_u32 v135, v151, 5, s3
	s_waitcnt lgkmcnt(0)
	v_add_f32_e32 v139, v136, v137
	ds_write_b64 v135, v[138:139] offset:4096
;     __device__ __forceinline__ bool run(const f32x4 (&v)[2][2][4][2], const Unit& u, int wr, int wc, int fr, int fq, PG8_LAS unsigned char* lds, int wid, int lane) const {
;     ...
;                 float s = 0.f;
; #pragma unroll
;                 for (int bj = 0; bj < 2; ++bj)
; #pragma unroll
;                     for (int n = 0; n < 2; ++n) { const f32x4 x = v[ai][bj][m][n]; s += (x[0] + x[1]) + (x[2] + x[3]); }
;                 s += __shfl_xor(s, 16); s += __shfl_xor(s, 32);
;                 const float mw = s * (1.0f / 64.0f); float q = 0.f;
; #pragma unroll
;                 for (int bj = 0; bj < 2; ++bj)
; #pragma unroll
;                     for (int n = 0; n < 2; ++n) { const f32x4 d = v[ai][bj][m][n] - mw; q += (d[0] * d[0] + d[1] * d[1]) + (d[2] * d[2] + d[3] * d[3]); }
;                 q += __shfl_xor(q, 16); q += __shfl_xor(q, 32);
;                 if (fq == 0) P[(ai * HALF + wr * 64 + m * 16 + fr) * 4 + wc] = (f32x2v){mw, q};
.LBB0_1506:
	s_or_b64 exec, exec, s[0:1]
	v_mov_b32_e32 v136, v47
	s_waitcnt lgkmcnt(0)
	v_mov_b32_e32 v137, v48
	v_mov_b32_e32 v138, v46
	v_mov_b32_e32 v139, v49
	v_pk_add_f32 v[136:137], v[136:137], v[138:139]
	v_mov_b32_e32 v138, v43
	v_mov_b32_e32 v139, v44
	v_mov_b32_e32 v140, v42
	v_mov_b32_e32 v141, v45
	v_pk_add_f32 v[138:139], v[138:139], v[140:141]
	v_add_f32_e32 v135, v136, v137
	v_pk_add_f32 v[138:139], v[138:139], v[138:139] op_sel_hi:[0,1]
	v_add_f32_e32 v137, 0, v135
	v_add_f32_e32 v141, v38, v39
	v_add_f32_e32 v143, v40, v41
	v_mov_b32_e32 v140, v34
	v_mov_b32_e32 v142, v35
	v_mov_b32_e32 v138, v36
	v_mov_b32_e32 v136, v37
	v_pk_add_f32 v[140:141], v[140:141], v[142:143]
	v_pk_add_f32 v[136:137], v[138:139], v[136:137]
	s_nop 0
	v_pk_add_f32 v[136:137], v[140:141], v[136:137]
	s_nop 0
	v_add_f32_e32 v135, v136, v137
	v_mov_b32_e32 v136, v135
	s_nop 1
	v_permlane16_swap_b32 v135, v136
	s_waitcnt lgkmcnt(0)
	v_add_f32_e32 v135, v135, v136
	v_mov_b32_e32 v136, v135
	s_nop 1
	v_permlane32_swap_b32 v135, v136
	s_waitcnt lgkmcnt(0)
	v_add_f32_e32 v135, v135, v136
	v_fmamk_f32 v137, v135, 0xbc800000, v49
	v_fmamk_f32 v139, v135, 0xbc800000, v47
	v_fmamk_f32 v136, v135, 0xbc800000, v48
	v_fmamk_f32 v138, v135, 0xbc800000, v46
	v_mul_f32_e32 v139, v139, v139
	v_mul_f32_e32 v137, v137, v137
	v_fmac_f32_e32 v139, v138, v138
	v_fmac_f32_e32 v137, v136, v136
	v_fmamk_f32 v138, v135, 0xbc800000, v45
	v_fmamk_f32 v140, v135, 0xbc800000, v43
	v_add_f32_e32 v136, v139, v137
	v_fmamk_f32 v137, v135, 0xbc800000, v44
	v_fmamk_f32 v139, v135, 0xbc800000, v42
	v_mul_f32_e32 v140, v140, v140
	v_mul_f32_e32 v138, v138, v138
	v_fmac_f32_e32 v140, v139, v139
	v_fmac_f32_e32 v138, v137, v137
	v_add_f32_e32 v137, v140, v138
	v_fmamk_f32 v138, v135, 0xbc800000, v41
	v_fmamk_f32 v140, v135, 0xbc800000, v39
	v_add_f32_e32 v136, v136, v137
	v_fmamk_f32 v137, v135, 0xbc800000, v40
	v_fmamk_f32 v139, v135, 0xbc800000, v38
	v_mul_f32_e32 v140, v140, v140
	v_mul_f32_e32 v138, v138, v138
	v_fmac_f32_e32 v140, v139, v139
	v_fmac_f32_e32 v138, v137, v137
	v_add_f32_e32 v137, v140, v138
	v_fmamk_f32 v138, v135, 0xbc800000, v37
	v_fmamk_f32 v140, v135, 0xbc800000, v35
	v_add_f32_e32 v136, v137, v136
	v_fmamk_f32 v137, v135, 0xbc800000, v36
	v_fmamk_f32 v139, v135, 0xbc800000, v34
	v_mul_f32_e32 v140, v140, v140
	v_mul_f32_e32 v138, v138, v138
	v_fmac_f32_e32 v140, v139, v139
	v_fmac_f32_e32 v138, v137, v137
	v_add_f32_e32 v137, v140, v138
	v_add_f32_e32 v136, v137, v136
	v_mov_b32_e32 v137, v136
	s_nop 1
	v_permlane16_swap_b32 v136, v137
	s_waitcnt lgkmcnt(0)
	v_add_f32_e32 v136, v136, v137
	v_mov_b32_e32 v137, v136
	s_nop 1
	v_permlane32_swap_b32 v136, v137
	s_and_saveexec_b64 s[0:1], vcc
	s_cbranch_execz .LBB0_1508
	s_lshl_b32 s3, s17, 11
	s_add_i32 s3, s2, s3
	v_mul_f32_e32 v138, 0x3c800000, v135
	v_lshl_add_u32 v135, v151, 5, s3
	s_waitcnt lgkmcnt(0)
	v_add_f32_e32 v139, v136, v137
	ds_write_b64 v135, v[138:139] offset:4608
;     __device__ __forceinline__ bool run(const f32x4 (&v)[2][2][4][2], const Unit& u, int wr, int wc, int fr, int fq, PG8_LAS unsigned char* lds, int wid, int lane) const {
;     ...
;                 float s = 0.f;
; #pragma unroll
;                 for (int bj = 0; bj < 2; ++bj)
; #pragma unroll
;                     for (int n = 0; n < 2; ++n) { const f32x4 x = v[ai][bj][m][n]; s += (x[0] + x[1]) + (x[2] + x[3]); }
;                 s += __shfl_xor(s, 16); s += __shfl_xor(s, 32);
;                 const float mw = s * (1.0f / 64.0f); float q = 0.f;
; #pragma unroll
;                 for (int bj = 0; bj < 2; ++bj)
; #pragma unroll
;                     for (int n = 0; n < 2; ++n) { const f32x4 d = v[ai][bj][m][n] - mw; q += (d[0] * d[0] + d[1] * d[1]) + (d[2] * d[2] + d[3] * d[3]); }
;                 q += __shfl_xor(q, 16); q += __shfl_xor(q, 32);
;                 if (fq == 0) P[(ai * HALF + wr * 64 + m * 16 + fr) * 4 + wc] = (f32x2v){mw, q};
.LBB0_1508:
	s_or_b64 exec, exec, s[0:1]
	v_mov_b32_e32 v136, v31
	s_waitcnt lgkmcnt(0)
	v_mov_b32_e32 v137, v32
	v_mov_b32_e32 v138, v30
	v_mov_b32_e32 v139, v33
	v_pk_add_f32 v[136:137], v[136:137], v[138:139]
	v_mov_b32_e32 v138, v27
	v_mov_b32_e32 v139, v28
	v_mov_b32_e32 v140, v26
	v_mov_b32_e32 v141, v29
	v_pk_add_f32 v[138:139], v[138:139], v[140:141]
	v_add_f32_e32 v135, v136, v137
	v_pk_add_f32 v[138:139], v[138:139], v[138:139] op_sel_hi:[0,1]
	v_add_f32_e32 v137, 0, v135
	v_add_f32_e32 v141, v22, v23
	v_add_f32_e32 v143, v24, v25
	v_mov_b32_e32 v140, v18
	v_mov_b32_e32 v142, v19
	v_mov_b32_e32 v138, v20
	v_mov_b32_e32 v136, v21
	v_pk_add_f32 v[140:141], v[140:141], v[142:143]
	v_pk_add_f32 v[136:137], v[138:139], v[136:137]
	s_nop 0
	v_pk_add_f32 v[136:137], v[140:141], v[136:137]
	s_nop 0
	v_add_f32_e32 v135, v136, v137
	v_mov_b32_e32 v136, v135
	s_nop 1
	v_permlane16_swap_b32 v135, v136
	s_waitcnt lgkmcnt(0)
	v_add_f32_e32 v135, v135, v136
	v_mov_b32_e32 v136, v135
	s_nop 1
	v_permlane32_swap_b32 v135, v136
	s_waitcnt lgkmcnt(0)
	v_add_f32_e32 v135, v135, v136
	v_fmamk_f32 v137, v135, 0xbc800000, v33
	v_fmamk_f32 v139, v135, 0xbc800000, v31
	v_fmamk_f32 v136, v135, 0xbc800000, v32
	v_fmamk_f32 v138, v135, 0xbc800000, v30
	v_mul_f32_e32 v139, v139, v139
	v_mul_f32_e32 v137, v137, v137
	v_fmac_f32_e32 v139, v138, v138
	v_fmac_f32_e32 v137, v136, v136
	v_fmamk_f32 v138, v135, 0xbc800000, v29
	v_fmamk_f32 v140, v135, 0xbc800000, v27
	v_add_f32_e32 v136, v139, v137
	v_fmamk_f32 v137, v135, 0xbc800000, v28
	v_fmamk_f32 v139, v135, 0xbc800000, v26
	v_mul_f32_e32 v140, v140, v140
	v_mul_f32_e32 v138, v138, v138
	v_fmac_f32_e32 v140, v139, v139
	v_fmac_f32_e32 v138, v137, v137
	v_add_f32_e32 v137, v140, v138
	v_fmamk_f32 v138, v135, 0xbc800000, v25
	v_fmamk_f32 v140, v135, 0xbc800000, v23
	v_add_f32_e32 v136, v136, v137
	v_fmamk_f32 v137, v135, 0xbc800000, v24
	v_fmamk_f32 v139, v135, 0xbc800000, v22
	v_mul_f32_e32 v140, v140, v140
	v_mul_f32_e32 v138, v138, v138
	v_fmac_f32_e32 v140, v139, v139
	v_fmac_f32_e32 v138, v137, v137
	v_add_f32_e32 v137, v140, v138
	v_fmamk_f32 v138, v135, 0xbc800000, v21
	v_fmamk_f32 v140, v135, 0xbc800000, v19
	v_add_f32_e32 v136, v137, v136
	v_fmamk_f32 v137, v135, 0xbc800000, v20
	v_fmamk_f32 v139, v135, 0xbc800000, v18
	v_mul_f32_e32 v140, v140, v140
	v_mul_f32_e32 v138, v138, v138
	v_fmac_f32_e32 v140, v139, v139
	v_fmac_f32_e32 v138, v137, v137
	v_add_f32_e32 v137, v140, v138
	v_add_f32_e32 v136, v137, v136
	v_mov_b32_e32 v137, v136
	s_nop 1
	v_permlane16_swap_b32 v136, v137
	s_waitcnt lgkmcnt(0)
	v_add_f32_e32 v136, v136, v137
	v_mov_b32_e32 v137, v136
	s_nop 1
	v_permlane32_swap_b32 v136, v137
	s_and_saveexec_b64 s[0:1], vcc
	s_cbranch_execz .LBB0_1510
	s_lshl_b32 s3, s17, 11
	s_add_i32 s3, s2, s3
	v_mul_f32_e32 v138, 0x3c800000, v135
	v_lshl_add_u32 v135, v151, 5, s3
	s_waitcnt lgkmcnt(0)
	v_add_f32_e32 v139, v136, v137
	ds_write_b64 v135, v[138:139] offset:5120
.LBB0_1510:
	s_or_b64 exec, exec, s[0:1]
	v_mov_b32_e32 v136, v15
	s_waitcnt lgkmcnt(0)
	v_mov_b32_e32 v137, v16
	v_mov_b32_e32 v138, v14
	v_mov_b32_e32 v139, v17
	v_pk_add_f32 v[136:137], v[136:137], v[138:139]
	v_mov_b32_e32 v138, v11
	v_mov_b32_e32 v139, v12
	v_mov_b32_e32 v140, v10
	v_mov_b32_e32 v141, v13
	v_pk_add_f32 v[138:139], v[138:139], v[140:141]
	v_add_f32_e32 v135, v136, v137
	v_pk_add_f32 v[138:139], v[138:139], v[138:139] op_sel_hi:[0,1]
	v_add_f32_e32 v137, 0, v135
	v_add_f32_e32 v141, v6, v7
	v_add_f32_e32 v143, v8, v9
	v_mov_b32_e32 v140, v2
	v_mov_b32_e32 v142, v3
	v_mov_b32_e32 v138, v4
	v_mov_b32_e32 v136, v5
	v_pk_add_f32 v[140:141], v[140:141], v[142:143]
	v_pk_add_f32 v[136:137], v[138:139], v[136:137]
	s_nop 0
	v_pk_add_f32 v[136:137], v[140:141], v[136:137]
	s_nop 0
	v_add_f32_e32 v135, v136, v137
	v_mov_b32_e32 v136, v135
	s_nop 1
	v_permlane16_swap_b32 v135, v136
	s_waitcnt lgkmcnt(0)
	v_add_f32_e32 v135, v135, v136
	v_mov_b32_e32 v136, v135
	s_nop 1
	v_permlane32_swap_b32 v135, v136
	s_waitcnt lgkmcnt(0)
	v_add_f32_e32 v135, v135, v136
	v_fmamk_f32 v137, v135, 0xbc800000, v17
	v_fmamk_f32 v139, v135, 0xbc800000, v15
	v_fmamk_f32 v136, v135, 0xbc800000, v16
	v_fmamk_f32 v138, v135, 0xbc800000, v14
	v_mul_f32_e32 v139, v139, v139
	v_mul_f32_e32 v137, v137, v137
	v_fmac_f32_e32 v139, v138, v138
	v_fmac_f32_e32 v137, v136, v136
	v_fmamk_f32 v138, v135, 0xbc800000, v13
	v_fmamk_f32 v140, v135, 0xbc800000, v11
	v_add_f32_e32 v136, v139, v137
	v_fmamk_f32 v137, v135, 0xbc800000, v12
	v_fmamk_f32 v139, v135, 0xbc800000, v10
	v_mul_f32_e32 v140, v140, v140
	v_mul_f32_e32 v138, v138, v138
	v_fmac_f32_e32 v140, v139, v139
	v_fmac_f32_e32 v138, v137, v137
	v_add_f32_e32 v137, v140, v138
	v_fmamk_f32 v138, v135, 0xbc800000, v9
	v_fmamk_f32 v140, v135, 0xbc800000, v7
	v_add_f32_e32 v136, v136, v137
	v_fmamk_f32 v137, v135, 0xbc800000, v8
	v_fmamk_f32 v139, v135, 0xbc800000, v6
	v_mul_f32_e32 v140, v140, v140
	v_mul_f32_e32 v138, v138, v138
	v_fmac_f32_e32 v140, v139, v139
	v_fmac_f32_e32 v138, v137, v137
	v_add_f32_e32 v137, v140, v138
	v_fmamk_f32 v138, v135, 0xbc800000, v5
	v_fmamk_f32 v140, v135, 0xbc800000, v3
	v_add_f32_e32 v136, v137, v136
	v_fmamk_f32 v137, v135, 0xbc800000, v4
	v_fmamk_f32 v139, v135, 0xbc800000, v2
	v_mul_f32_e32 v140, v140, v140
	v_mul_f32_e32 v138, v138, v138
	v_fmac_f32_e32 v140, v139, v139
	v_fmac_f32_e32 v138, v137, v137
	v_add_f32_e32 v137, v140, v138
	v_add_f32_e32 v136, v137, v136
	v_mov_b32_e32 v132, v136
	s_nop 1
	v_permlane16_swap_b32 v136, v132
	s_waitcnt lgkmcnt(0)
	v_add_f32_e32 v132, v136, v132
	v_mov_b32_e32 v133, v132
	s_nop 1
	v_permlane32_swap_b32 v132, v133
	s_and_saveexec_b64 s[0:1], vcc
	s_cbranch_execz .LBB0_1512
	s_lshl_b32 s3, s17, 11
	s_add_i32 s2, s2, s3
	v_mul_f32_e32 v136, 0x3c800000, v135
	v_lshl_add_u32 v135, v151, 5, s2
	s_waitcnt lgkmcnt(0)
	v_add_f32_e32 v137, v132, v133
	ds_write_b64 v135, v[136:137] offset:5632

;     __device__ __forceinline__ void fused(f32x4 (&acc)[2][2][4][2], const Unit& u, int wr, int wc, int fr, int fq, PG8_LAS unsigned char* lds, int wid, int lane) const {
;     ...
;             for (int m = 0; m < 4; ++m) { const size_t off = (size_t)(u.pm * BM + ai * HALF + wr * 64 + m * 16 + fr) * ldc + col0;
; #pragma unroll
;                 for (int bj = 0; bj < 2; ++bj) { f32x4 b0, b1;
;                     if (base) { b0 = *(const f32x4*)(base + off + bj * HALF); b1 = *(const f32x4*)(base + off + bj * HALF + 4); }
;                     else { const u32x4 w = *(const u32x4*)(baseb + off + bj * HALF);
;                         b0 = (f32x4){__uint_as_float(w.x << 16), __uint_as_float(w.x & 0xffff0000u), __uint_as_float(w.y << 16), __uint_as_float(w.y & 0xffff0000u)};
;                         b1 = (f32x4){__uint_as_float(w.z << 16), __uint_as_float(w.z & 0xffff0000u), __uint_as_float(w.w << 16), __uint_as_float(w.w & 0xffff0000u)}; }
;                     acc[ai][bj][m][0] = acc[ai][bj][m][0] * s + b0 * alpha; acc[ai][bj][m][1] = acc[ai][bj][m][1] * s + b1 * alpha; }
.LBB0_1713:
	s_lshl_b32 s0, s27, 5
	s_lshl_b32 s1, s12, 8
	v_lshrrev_b32_e32 v130, 1, v150
	s_or_b32 s0, s1, s0
	s_lshl_b32 s18, s25, 8
	v_and_or_b32 v130, v130, 24, s0
	s_add_i32 s0, s18, s35
	v_or_b32_e32 v132, s0, v151
	v_ashrrev_i32_e32 v133, 31, v132
	v_ashrrev_i32_e32 v131, 31, v130
	v_lshlrev_b64 v[134:135], 11, v[132:133]
	v_lshl_add_u64 v[136:137], s[10:11], 0, v[134:135]
	v_lshlrev_b64 v[134:135], 1, v[130:131]
	v_lshl_add_u64 v[140:141], v[136:137], 0, v[134:135]
	s_barrier
	s_nop 1
	v_subrev_u32_e32 v175, s10, v140
	global_load_dwordx4 v[176:179], v175, s[10:11]
	global_load_dwordx4 v[180:183], v175, s[10:11] offset:256
	s_add_u32 s100, s10, 0x8000
	s_addc_u32 s101, s11, 0
	global_load_dwordx4 v[184:187], v175, s[100:101]
	global_load_dwordx4 v[188:191], v175, s[100:101] offset:256
	s_add_u32 s98, s10, 0x10000
	s_addc_u32 s99, s11, 0
	global_load_dwordx4 v[192:195], v175, s[98:99]
	global_load_dwordx4 v[196:199], v175, s[98:99] offset:256
	s_add_u32 s100, s10, 0x18000
	s_addc_u32 s101, s11, 0
	global_load_dwordx4 v[200:203], v175, s[100:101]
	global_load_dwordx4 v[204:207], v175, s[100:101] offset:256
	s_add_u32 s98, s10, 0x40000
	s_addc_u32 s99, s11, 0
	global_load_dwordx4 v[208:211], v175, s[98:99]
	global_load_dwordx4 v[212:215], v175, s[98:99] offset:256
	s_add_u32 s100, s10, 0x48000
	s_addc_u32 s101, s11, 0
	global_load_dwordx4 v[216:219], v175, s[100:101]
	global_load_dwordx4 v[220:223], v175, s[100:101] offset:256
	s_add_u32 s98, s10, 0x50000
	s_addc_u32 s99, s11, 0
	global_load_dwordx4 v[224:227], v175, s[98:99]
	global_load_dwordx4 v[228:231], v175, s[98:99] offset:256
	s_add_u32 s100, s10, 0x58000
	s_addc_u32 s101, s11, 0
	global_load_dwordx4 v[232:235], v175, s[100:101]
	global_load_dwordx4 v[236:239], v175, s[100:101] offset:256
	s_nop 0
	v_or_b32_e32 v144, 16, v132
	v_ashrrev_i32_e32 v145, 31, v144
	s_mov_b32 s0, 0x3f9837f0
	v_lshlrev_b64 v[144:145], 11, v[144:145]
	v_lshl_add_u64 v[144:145], s[10:11], 0, v[144:145]
	v_lshl_add_u64 v[144:145], v[144:145], 0, v[134:135]
	v_mbcnt_hi_u32_b32 v156, -1, v1
	v_and_b32_e32 v133, 64, v156
	v_add_u32_e32 v157, 64, v133
	v_xor_b32_e32 v1, 16, v156
	v_cmp_lt_i32_e32 vcc, v1, v157
	s_waitcnt vmcnt(14)
	v_lshlrev_b32_e32 v146, 16, v176
	v_and_b32_e32 v147, 0xffff0000, v176
	v_lshlrev_b32_e32 v136, 16, v177
	v_and_b32_e32 v137, 0xffff0000, v177
	v_lshlrev_b32_e32 v148, 16, v178
	v_and_b32_e32 v149, 0xffff0000, v178
	v_lshlrev_b32_e32 v138, 16, v179
	v_and_b32_e32 v139, 0xffff0000, v179
	v_lshlrev_b32_e32 v152, 16, v180
	v_and_b32_e32 v153, 0xffff0000, v180
	v_lshlrev_b32_e32 v140, 16, v181
	v_and_b32_e32 v141, 0xffff0000, v181
	v_lshlrev_b32_e32 v154, 16, v182
	v_and_b32_e32 v155, 0xffff0000, v182
	v_lshlrev_b32_e32 v142, 16, v183
	v_and_b32_e32 v143, 0xffff0000, v183
	v_pk_mul_f32 v[146:147], v[146:147], s[0:1] op_sel_hi:[1,0]
	v_pk_mul_f32 v[136:137], v[136:137], s[0:1] op_sel_hi:[1,0]
	v_pk_mul_f32 v[148:149], v[148:149], s[0:1] op_sel_hi:[1,0]
	v_pk_mul_f32 v[138:139], v[138:139], s[0:1] op_sel_hi:[1,0]
	v_pk_mul_f32 v[152:153], v[152:153], s[0:1] op_sel_hi:[1,0]
	v_pk_mul_f32 v[140:141], v[140:141], s[0:1] op_sel_hi:[1,0]
	v_pk_mul_f32 v[154:155], v[154:155], s[0:1] op_sel_hi:[1,0]
	v_pk_mul_f32 v[142:143], v[142:143], s[0:1] op_sel_hi:[1,0]
	v_pk_fma_f32 v[72:73], v[72:73], 0.5, v[136:137] op_sel_hi:[1,0,1]
	v_pk_fma_f32 v[70:71], v[70:71], 0.5, v[146:147] op_sel_hi:[1,0,1]
	v_pk_fma_f32 v[80:81], v[80:81], 0.5, v[138:139] op_sel_hi:[1,0,1]
	v_pk_fma_f32 v[78:79], v[78:79], 0.5, v[148:149] op_sel_hi:[1,0,1]
	v_pk_fma_f32 v[68:69], v[68:69], 0.5, v[140:141] op_sel_hi:[1,0,1]
	v_pk_fma_f32 v[66:67], v[66:67], 0.5, v[152:153] op_sel_hi:[1,0,1]
	v_pk_fma_f32 v[76:77], v[76:77], 0.5, v[142:143] op_sel_hi:[1,0,1]
	v_pk_fma_f32 v[74:75], v[74:75], 0.5, v[154:155] op_sel_hi:[1,0,1]
	v_cndmask_b32_e32 v1, v156, v1, vcc
	v_or_b32_e32 v144, 32, v132
	v_ashrrev_i32_e32 v145, 31, v144
	v_lshlrev_b64 v[144:145], 11, v[144:145]
	v_lshl_add_u64 v[144:145], s[10:11], 0, v[144:145]
	v_lshl_add_u64 v[144:145], v[144:145], 0, v[134:135]
	v_lshlrev_b32_e32 v1, 2, v1
	s_waitcnt vmcnt(13)
	v_lshlrev_b32_e32 v146, 16, v184
	v_and_b32_e32 v147, 0xffff0000, v184
	v_lshlrev_b32_e32 v136, 16, v185
	v_and_b32_e32 v137, 0xffff0000, v185
	v_lshlrev_b32_e32 v148, 16, v186
	v_and_b32_e32 v149, 0xffff0000, v186
	v_lshlrev_b32_e32 v138, 16, v187
	v_and_b32_e32 v139, 0xffff0000, v187
	s_waitcnt vmcnt(12)
	v_lshlrev_b32_e32 v152, 16, v188
	v_and_b32_e32 v153, 0xffff0000, v188
	v_lshlrev_b32_e32 v140, 16, v189
	v_and_b32_e32 v141, 0xffff0000, v189
	v_lshlrev_b32_e32 v154, 16, v190
	v_and_b32_e32 v155, 0xffff0000, v190
	v_lshlrev_b32_e32 v142, 16, v191
	v_and_b32_e32 v143, 0xffff0000, v191
	v_pk_mul_f32 v[146:147], v[146:147], s[0:1] op_sel_hi:[1,0]
	v_pk_mul_f32 v[136:137], v[136:137], s[0:1] op_sel_hi:[1,0]
	v_pk_mul_f32 v[148:149], v[148:149], s[0:1] op_sel_hi:[1,0]
	v_pk_mul_f32 v[138:139], v[138:139], s[0:1] op_sel_hi:[1,0]
	v_pk_mul_f32 v[152:153], v[152:153], s[0:1] op_sel_hi:[1,0]
	v_pk_mul_f32 v[140:141], v[140:141], s[0:1] op_sel_hi:[1,0]
	v_pk_mul_f32 v[154:155], v[154:155], s[0:1] op_sel_hi:[1,0]
	v_pk_mul_f32 v[142:143], v[142:143], s[0:1] op_sel_hi:[1,0]
	v_pk_fma_f32 v[96:97], v[96:97], 0.5, v[136:137] op_sel_hi:[1,0,1]
	v_pk_fma_f32 v[94:95], v[94:95], 0.5, v[146:147] op_sel_hi:[1,0,1]
	v_pk_fma_f32 v[120:121], v[120:121], 0.5, v[138:139] op_sel_hi:[1,0,1]
	v_pk_fma_f32 v[118:119], v[118:119], 0.5, v[148:149] op_sel_hi:[1,0,1]
	v_pk_fma_f32 v[84:85], v[84:85], 0.5, v[140:141] op_sel_hi:[1,0,1]
	v_pk_fma_f32 v[82:83], v[82:83], 0.5, v[152:153] op_sel_hi:[1,0,1]
	v_pk_fma_f32 v[88:89], v[88:89], 0.5, v[142:143] op_sel_hi:[1,0,1]
	v_pk_fma_f32 v[86:87], v[86:87], 0.5, v[154:155] op_sel_hi:[1,0,1]
	s_nop 0
	v_or_b32_e32 v144, 48, v132
	v_ashrrev_i32_e32 v145, 31, v144
	v_lshlrev_b64 v[144:145], 11, v[144:145]
	v_lshl_add_u64 v[144:145], s[10:11], 0, v[144:145]
	v_lshl_add_u64 v[144:145], v[144:145], 0, v[134:135]
	s_waitcnt vmcnt(11)
;     __device__ __forceinline__ void fused(f32x4 (&acc)[2][2][4][2], const Unit& u, int wr, int wc, int fr, int fq, PG8_LAS unsigned char* lds, int wid, int lane) const {
;     ...
;             for (int m = 0; m < 4; ++m) { const size_t off = (size_t)(u.pm * BM + ai * HALF + wr * 64 + m * 16 + fr) * ldc + col0;
; #pragma unroll
;                 for (int bj = 0; bj < 2; ++bj) { f32x4 b0, b1;
;                     if (base) { b0 = *(const f32x4*)(base + off + bj * HALF); b1 = *(const f32x4*)(base + off + bj * HALF + 4); }
;                     else { const u32x4 w = *(const u32x4*)(baseb + off + bj * HALF);
;                         b0 = (f32x4){__uint_as_float(w.x << 16), __uint_as_float(w.x & 0xffff0000u), __uint_as_float(w.y << 16), __uint_as_float(w.y & 0xffff0000u)};
;                         b1 = (f32x4){__uint_as_float(w.z << 16), __uint_as_float(w.z & 0xffff0000u), __uint_as_float(w.w << 16), __uint_as_float(w.w & 0xffff0000u)}; }
;                     acc[ai][bj][m][0] = acc[ai][bj][m][0] * s + b0 * alpha; acc[ai][bj][m][1] = acc[ai][bj][m][1] * s + b1 * alpha; }
	v_lshlrev_b32_e32 v146, 16, v192
	v_and_b32_e32 v147, 0xffff0000, v192
	v_lshlrev_b32_e32 v136, 16, v193
	v_and_b32_e32 v137, 0xffff0000, v193
	v_lshlrev_b32_e32 v148, 16, v194
	v_and_b32_e32 v149, 0xffff0000, v194
	v_lshlrev_b32_e32 v138, 16, v195
	v_and_b32_e32 v139, 0xffff0000, v195
	s_waitcnt vmcnt(10)
	v_lshlrev_b32_e32 v152, 16, v196
	v_and_b32_e32 v153, 0xffff0000, v196
	v_lshlrev_b32_e32 v140, 16, v197
	v_and_b32_e32 v141, 0xffff0000, v197
	v_lshlrev_b32_e32 v154, 16, v198
	v_and_b32_e32 v155, 0xffff0000, v198
	v_lshlrev_b32_e32 v142, 16, v199
	v_and_b32_e32 v143, 0xffff0000, v199
	v_pk_mul_f32 v[146:147], v[146:147], s[0:1] op_sel_hi:[1,0]
	v_pk_mul_f32 v[136:137], v[136:137], s[0:1] op_sel_hi:[1,0]
	v_pk_mul_f32 v[148:149], v[148:149], s[0:1] op_sel_hi:[1,0]
	v_pk_mul_f32 v[138:139], v[138:139], s[0:1] op_sel_hi:[1,0]
	v_pk_mul_f32 v[152:153], v[152:153], s[0:1] op_sel_hi:[1,0]
	v_pk_mul_f32 v[140:141], v[140:141], s[0:1] op_sel_hi:[1,0]
	v_pk_mul_f32 v[154:155], v[154:155], s[0:1] op_sel_hi:[1,0]
	v_pk_mul_f32 v[142:143], v[142:143], s[0:1] op_sel_hi:[1,0]
	v_pk_fma_f32 v[108:109], v[108:109], 0.5, v[136:137] op_sel_hi:[1,0,1]
	v_pk_fma_f32 v[106:107], v[106:107], 0.5, v[146:147] op_sel_hi:[1,0,1]
	v_pk_fma_f32 v[116:117], v[116:117], 0.5, v[138:139] op_sel_hi:[1,0,1]
	v_pk_fma_f32 v[114:115], v[114:115], 0.5, v[148:149] op_sel_hi:[1,0,1]
	v_pk_fma_f32 v[92:93], v[92:93], 0.5, v[140:141] op_sel_hi:[1,0,1]
	v_pk_fma_f32 v[90:91], v[90:91], 0.5, v[152:153] op_sel_hi:[1,0,1]
	v_pk_fma_f32 v[100:101], v[100:101], 0.5, v[142:143] op_sel_hi:[1,0,1]
	v_pk_fma_f32 v[98:99], v[98:99], 0.5, v[154:155] op_sel_hi:[1,0,1]
	s_nop 0
	v_add_u32_e32 v144, 0x80, v132
	v_ashrrev_i32_e32 v145, 31, v144
	v_lshlrev_b64 v[144:145], 11, v[144:145]
	v_lshl_add_u64 v[144:145], s[10:11], 0, v[144:145]
	v_lshl_add_u64 v[144:145], v[144:145], 0, v[134:135]
	s_waitcnt vmcnt(9)
	v_lshlrev_b32_e32 v146, 16, v200
	v_and_b32_e32 v147, 0xffff0000, v200
	v_lshlrev_b32_e32 v136, 16, v201
	v_and_b32_e32 v137, 0xffff0000, v201
	v_lshlrev_b32_e32 v148, 16, v202
	v_and_b32_e32 v149, 0xffff0000, v202
	v_lshlrev_b32_e32 v138, 16, v203
	v_and_b32_e32 v139, 0xffff0000, v203
	s_waitcnt vmcnt(8)
	v_lshlrev_b32_e32 v152, 16, v204
	v_and_b32_e32 v153, 0xffff0000, v204
	v_lshlrev_b32_e32 v140, 16, v205
	v_and_b32_e32 v141, 0xffff0000, v205
	v_lshlrev_b32_e32 v154, 16, v206
	v_and_b32_e32 v155, 0xffff0000, v206
	v_lshlrev_b32_e32 v142, 16, v207
	v_and_b32_e32 v143, 0xffff0000, v207
	v_pk_mul_f32 v[146:147], v[146:147], s[0:1] op_sel_hi:[1,0]
	v_pk_mul_f32 v[136:137], v[136:137], s[0:1] op_sel_hi:[1,0]
	v_pk_mul_f32 v[148:149], v[148:149], s[0:1] op_sel_hi:[1,0]
	v_pk_mul_f32 v[138:139], v[138:139], s[0:1] op_sel_hi:[1,0]
	v_pk_mul_f32 v[152:153], v[152:153], s[0:1] op_sel_hi:[1,0]
	v_pk_mul_f32 v[140:141], v[140:141], s[0:1] op_sel_hi:[1,0]
	v_pk_mul_f32 v[154:155], v[154:155], s[0:1] op_sel_hi:[1,0]
	v_pk_mul_f32 v[142:143], v[142:143], s[0:1] op_sel_hi:[1,0]
	v_pk_fma_f32 v[124:125], v[124:125], 0.5, v[136:137] op_sel_hi:[1,0,1]
	v_pk_fma_f32 v[122:123], v[122:123], 0.5, v[146:147] op_sel_hi:[1,0,1]
	v_pk_fma_f32 v[128:129], v[128:129], 0.5, v[138:139] op_sel_hi:[1,0,1]
	v_pk_fma_f32 v[126:127], v[126:127], 0.5, v[148:149] op_sel_hi:[1,0,1]
	v_pk_fma_f32 v[104:105], v[104:105], 0.5, v[140:141] op_sel_hi:[1,0,1]
	v_pk_fma_f32 v[102:103], v[102:103], 0.5, v[152:153] op_sel_hi:[1,0,1]
	v_pk_fma_f32 v[112:113], v[112:113], 0.5, v[142:143] op_sel_hi:[1,0,1]
	v_pk_fma_f32 v[110:111], v[110:111], 0.5, v[154:155] op_sel_hi:[1,0,1]
	s_nop 0
	v_add_u32_e32 v144, 0x90, v132
	v_ashrrev_i32_e32 v145, 31, v144
	v_lshlrev_b64 v[144:145], 11, v[144:145]
	v_lshl_add_u64 v[144:145], s[10:11], 0, v[144:145]
	v_lshl_add_u64 v[144:145], v[144:145], 0, v[134:135]
	s_waitcnt vmcnt(7)
	v_lshlrev_b32_e32 v146, 16, v208
	v_and_b32_e32 v147, 0xffff0000, v208
	v_lshlrev_b32_e32 v136, 16, v209
	v_and_b32_e32 v137, 0xffff0000, v209
	v_lshlrev_b32_e32 v148, 16, v210
	v_and_b32_e32 v149, 0xffff0000, v210
	v_lshlrev_b32_e32 v138, 16, v211
	v_and_b32_e32 v139, 0xffff0000, v211
	s_waitcnt vmcnt(6)
	v_lshlrev_b32_e32 v152, 16, v212
	v_and_b32_e32 v153, 0xffff0000, v212
	v_lshlrev_b32_e32 v140, 16, v213
	v_and_b32_e32 v141, 0xffff0000, v213
	v_lshlrev_b32_e32 v154, 16, v214
	v_and_b32_e32 v155, 0xffff0000, v214
	v_lshlrev_b32_e32 v142, 16, v215
	v_and_b32_e32 v143, 0xffff0000, v215
	v_pk_mul_f32 v[146:147], v[146:147], s[0:1] op_sel_hi:[1,0]
	v_pk_mul_f32 v[136:137], v[136:137], s[0:1] op_sel_hi:[1,0]
	v_pk_mul_f32 v[148:149], v[148:149], s[0:1] op_sel_hi:[1,0]
	v_pk_mul_f32 v[138:139], v[138:139], s[0:1] op_sel_hi:[1,0]
	v_pk_mul_f32 v[152:153], v[152:153], s[0:1] op_sel_hi:[1,0]
	v_pk_mul_f32 v[140:141], v[140:141], s[0:1] op_sel_hi:[1,0]
	v_pk_mul_f32 v[154:155], v[154:155], s[0:1] op_sel_hi:[1,0]
	v_pk_mul_f32 v[142:143], v[142:143], s[0:1] op_sel_hi:[1,0]
	v_pk_fma_f32 v[64:65], v[64:65], 0.5, v[136:137] op_sel_hi:[1,0,1]
	v_pk_fma_f32 v[62:63], v[62:63], 0.5, v[146:147] op_sel_hi:[1,0,1]
	v_pk_fma_f32 v[60:61], v[60:61], 0.5, v[138:139] op_sel_hi:[1,0,1]
	v_pk_fma_f32 v[58:59], v[58:59], 0.5, v[148:149] op_sel_hi:[1,0,1]
	v_pk_fma_f32 v[56:57], v[56:57], 0.5, v[140:141] op_sel_hi:[1,0,1]
	v_pk_fma_f32 v[54:55], v[54:55], 0.5, v[152:153] op_sel_hi:[1,0,1]
	v_pk_fma_f32 v[52:53], v[52:53], 0.5, v[142:143] op_sel_hi:[1,0,1]
	v_pk_fma_f32 v[50:51], v[50:51], 0.5, v[154:155] op_sel_hi:[1,0,1]
	s_nop 0
	v_add_u32_e32 v144, 0xa0, v132
	v_ashrrev_i32_e32 v145, 31, v144
	v_lshlrev_b64 v[144:145], 11, v[144:145]
	v_lshl_add_u64 v[144:145], s[10:11], 0, v[144:145]
	v_lshl_add_u64 v[144:145], v[144:145], 0, v[134:135]
	v_add_u32_e32 v132, 0xb0, v132
	v_ashrrev_i32_e32 v133, 31, v132
	v_lshlrev_b64 v[132:133], 11, v[132:133]
	v_lshl_add_u64 v[132:133], s[10:11], 0, v[132:133]
	v_lshl_add_u64 v[132:133], v[132:133], 0, v[134:135]
	v_mov_b32_e32 v134, v71
	v_mov_b32_e32 v135, v72
	s_waitcnt vmcnt(5)
;     __device__ __forceinline__ bool run(const f32x4 (&v)[2][2][4][2], const Unit& u, int wr, int wc, int fr, int fq, PG8_LAS unsigned char* lds, int wid, int lane) const {
;     ...
;                 float s = 0.f;
; #pragma unroll
;                 for (int bj = 0; bj < 2; ++bj)
; #pragma unroll
;                     for (int n = 0; n < 2; ++n) { const f32x4 x = v[ai][bj][m][n]; s += (x[0] + x[1]) + (x[2] + x[3]); }
;                 s += __shfl_xor(s, 16); s += __shfl_xor(s, 32);
;                 const float mw = s * (1.0f / 64.0f); float q = 0.f;
; #pragma unroll
;                 for (int bj = 0; bj < 2; ++bj)
; #pragma unroll
;                     for (int n = 0; n < 2; ++n) { const f32x4 d = v[ai][bj][m][n] - mw; q += (d[0] * d[0] + d[1] * d[1]) + (d[2] * d[2] + d[3] * d[3]); }
;                 q += __shfl_xor(q, 16); q += __shfl_xor(q, 32);
;                 if (fq == 0) P[(ai * HALF + wr * 64 + m * 16 + fr) * 4 + wc] = (f32x2v){mw, q};
	v_lshlrev_b32_e32 v146, 16, v216
	v_and_b32_e32 v147, 0xffff0000, v216
	v_lshlrev_b32_e32 v136, 16, v217
	v_and_b32_e32 v137, 0xffff0000, v217
	v_lshlrev_b32_e32 v148, 16, v218
	v_and_b32_e32 v149, 0xffff0000, v218
	v_lshlrev_b32_e32 v138, 16, v219
	v_and_b32_e32 v139, 0xffff0000, v219
	s_waitcnt vmcnt(4)
	v_lshlrev_b32_e32 v152, 16, v220
	v_and_b32_e32 v153, 0xffff0000, v220
	v_lshlrev_b32_e32 v140, 16, v221
	v_and_b32_e32 v141, 0xffff0000, v221
	v_lshlrev_b32_e32 v154, 16, v222
	v_and_b32_e32 v155, 0xffff0000, v222
	v_lshlrev_b32_e32 v142, 16, v223
	v_and_b32_e32 v143, 0xffff0000, v223
	v_pk_mul_f32 v[146:147], v[146:147], s[0:1] op_sel_hi:[1,0]
	v_pk_mul_f32 v[136:137], v[136:137], s[0:1] op_sel_hi:[1,0]
	v_pk_mul_f32 v[148:149], v[148:149], s[0:1] op_sel_hi:[1,0]
	v_pk_mul_f32 v[138:139], v[138:139], s[0:1] op_sel_hi:[1,0]
	v_pk_mul_f32 v[152:153], v[152:153], s[0:1] op_sel_hi:[1,0]
	v_pk_mul_f32 v[140:141], v[140:141], s[0:1] op_sel_hi:[1,0]
	v_pk_mul_f32 v[154:155], v[154:155], s[0:1] op_sel_hi:[1,0]
	v_pk_mul_f32 v[142:143], v[142:143], s[0:1] op_sel_hi:[1,0]
	v_pk_fma_f32 v[48:49], v[48:49], 0.5, v[136:137] op_sel_hi:[1,0,1]
	v_pk_fma_f32 v[46:47], v[46:47], 0.5, v[146:147] op_sel_hi:[1,0,1]
	v_pk_fma_f32 v[44:45], v[44:45], 0.5, v[138:139] op_sel_hi:[1,0,1]
	v_pk_fma_f32 v[42:43], v[42:43], 0.5, v[148:149] op_sel_hi:[1,0,1]
	v_pk_fma_f32 v[40:41], v[40:41], 0.5, v[140:141] op_sel_hi:[1,0,1]
	v_pk_fma_f32 v[38:39], v[38:39], 0.5, v[152:153] op_sel_hi:[1,0,1]
	v_pk_fma_f32 v[36:37], v[36:37], 0.5, v[142:143] op_sel_hi:[1,0,1]
	v_pk_fma_f32 v[34:35], v[34:35], 0.5, v[154:155] op_sel_hi:[1,0,1]
	v_mov_b32_e32 v146, v70
	v_mov_b32_e32 v147, v73
	v_pk_add_f32 v[134:135], v[134:135], v[146:147]
	s_waitcnt vmcnt(3)
	v_lshlrev_b32_e32 v144, 16, v224
	v_and_b32_e32 v145, 0xffff0000, v224
	v_lshlrev_b32_e32 v136, 16, v225
	v_and_b32_e32 v137, 0xffff0000, v225
	v_lshlrev_b32_e32 v148, 16, v226
	v_and_b32_e32 v149, 0xffff0000, v226
	v_lshlrev_b32_e32 v138, 16, v227
	v_and_b32_e32 v139, 0xffff0000, v227
	s_waitcnt vmcnt(2)
	v_lshlrev_b32_e32 v152, 16, v228
	v_and_b32_e32 v153, 0xffff0000, v228
	v_lshlrev_b32_e32 v140, 16, v229
	v_and_b32_e32 v141, 0xffff0000, v229
	v_lshlrev_b32_e32 v154, 16, v230
	v_and_b32_e32 v155, 0xffff0000, v230
	v_lshlrev_b32_e32 v142, 16, v231
	v_and_b32_e32 v143, 0xffff0000, v231
	v_pk_mul_f32 v[144:145], v[144:145], s[0:1] op_sel_hi:[1,0]
	v_pk_mul_f32 v[136:137], v[136:137], s[0:1] op_sel_hi:[1,0]
	v_pk_mul_f32 v[148:149], v[148:149], s[0:1] op_sel_hi:[1,0]
	v_pk_mul_f32 v[138:139], v[138:139], s[0:1] op_sel_hi:[1,0]
	v_pk_mul_f32 v[152:153], v[152:153], s[0:1] op_sel_hi:[1,0]
	v_pk_mul_f32 v[140:141], v[140:141], s[0:1] op_sel_hi:[1,0]
	v_pk_mul_f32 v[154:155], v[154:155], s[0:1] op_sel_hi:[1,0]
	v_pk_mul_f32 v[142:143], v[142:143], s[0:1] op_sel_hi:[1,0]
	v_pk_fma_f32 v[32:33], v[32:33], 0.5, v[136:137] op_sel_hi:[1,0,1]
	v_pk_fma_f32 v[30:31], v[30:31], 0.5, v[144:145] op_sel_hi:[1,0,1]
	v_pk_fma_f32 v[28:29], v[28:29], 0.5, v[138:139] op_sel_hi:[1,0,1]
	v_pk_fma_f32 v[26:27], v[26:27], 0.5, v[148:149] op_sel_hi:[1,0,1]
	v_pk_fma_f32 v[24:25], v[24:25], 0.5, v[140:141] op_sel_hi:[1,0,1]
	v_pk_fma_f32 v[22:23], v[22:23], 0.5, v[152:153] op_sel_hi:[1,0,1]
	v_pk_fma_f32 v[20:21], v[20:21], 0.5, v[142:143] op_sel_hi:[1,0,1]
	v_pk_fma_f32 v[18:19], v[18:19], 0.5, v[154:155] op_sel_hi:[1,0,1]
	v_mov_b32_e32 v136, v79
	v_mov_b32_e32 v137, v80
	v_mov_b32_e32 v148, v78
	v_mov_b32_e32 v149, v81
	v_pk_add_f32 v[136:137], v[136:137], v[148:149]
	v_add_f32_e32 v133, v134, v135
	v_pk_add_f32 v[134:135], v[136:137], v[136:137] op_sel_hi:[0,1]
	v_add_f32_e32 v153, v66, v67
	v_add_f32_e32 v155, v68, v69
	v_mov_b32_e32 v152, v74
	v_mov_b32_e32 v154, v75
	v_mov_b32_e32 v132, v77
	v_add_f32_e32 v133, 0, v133
	v_mov_b32_e32 v134, v76
	v_pk_add_f32 v[146:147], v[152:153], v[154:155]
	v_pk_add_f32 v[132:133], v[134:135], v[132:133]
	s_nop 0
	v_pk_add_f32 v[132:133], v[146:147], v[132:133]
	s_nop 0
	v_add_f32_e32 v133, v132, v133
	v_mov_b32_e32 v134, v133
	s_nop 1
	v_permlane16_swap_b32 v133, v134
	v_xor_b32_e32 v132, 32, v156
	v_cmp_lt_i32_e32 vcc, v132, v157
	s_waitcnt lgkmcnt(0)
	v_add_f32_e32 v133, v133, v134
	v_cndmask_b32_e32 v132, v156, v132, vcc
	v_lshlrev_b32_e32 v132, 2, v132
	v_mov_b32_e32 v134, v133
	s_nop 1
	v_permlane32_swap_b32 v133, v134
	s_waitcnt lgkmcnt(0)
	v_add_f32_e32 v133, v133, v134
	v_fmamk_f32 v135, v133, 0xbc800000, v73
	v_fmamk_f32 v137, v133, 0xbc800000, v71
	v_fmamk_f32 v147, v133, 0xbc800000, v81
	v_fmamk_f32 v149, v133, 0xbc800000, v79
	v_fmamk_f32 v134, v133, 0xbc800000, v72
	v_fmamk_f32 v136, v133, 0xbc800000, v70
	v_fmamk_f32 v146, v133, 0xbc800000, v80
	v_fmamk_f32 v148, v133, 0xbc800000, v78
	v_fmamk_f32 v153, v133, 0xbc800000, v69
	v_fmamk_f32 v155, v133, 0xbc800000, v67
	v_mul_f32_e32 v137, v137, v137
	v_mul_f32_e32 v135, v135, v135
	v_mul_f32_e32 v149, v149, v149
	v_mul_f32_e32 v147, v147, v147
	v_fmamk_f32 v152, v133, 0xbc800000, v68
	v_fmamk_f32 v154, v133, 0xbc800000, v66
	v_fmamk_f32 v157, v133, 0xbc800000, v77
	v_fmamk_f32 v159, v133, 0xbc800000, v75
	v_mul_f32_e32 v155, v155, v155
	v_mul_f32_e32 v153, v153, v153
	v_fmac_f32_e32 v137, v136, v136
	v_fmac_f32_e32 v135, v134, v134
	v_fmac_f32_e32 v149, v148, v148
	v_fmac_f32_e32 v147, v146, v146
	v_fmamk_f32 v156, v133, 0xbc800000, v76
	v_fmamk_f32 v158, v133, 0xbc800000, v74
	v_mul_f32_e32 v159, v159, v159
	v_mul_f32_e32 v157, v157, v157
	v_fmac_f32_e32 v155, v154, v154
	v_fmac_f32_e32 v153, v152, v152
	v_add_f32_e32 v134, v137, v135
	v_add_f32_e32 v135, v149, v147
	v_fmac_f32_e32 v159, v158, v158
	v_fmac_f32_e32 v157, v156, v156
	v_add_f32_e32 v136, v155, v153
	v_add_f32_e32 v134, v134, v135
	v_add_f32_e32 v137, v159, v157
	v_add_f32_e32 v134, v136, v134
	v_add_f32_e32 v135, v137, v134
	v_mov_b32_e32 v136, v135
	s_nop 1
	v_permlane16_swap_b32 v135, v136
	v_and_b32_e32 v134, 63, v150
	v_cmp_gt_u32_e32 vcc, 16, v134
	s_waitcnt lgkmcnt(0)
;     __device__ __forceinline__ bool run(const f32x4 (&v)[2][2][4][2], const Unit& u, int wr, int wc, int fr, int fq, PG8_LAS unsigned char* lds, int wid, int lane) const {
;     ...
;                     for (int n = 0; n < 2; ++n) { const f32x4 x = v[ai][bj][m][n]; s += (x[0] + x[1]) + (x[2] + x[3]); }
;                 s += __shfl_xor(s, 16); s += __shfl_xor(s, 32);
;                 const float mw = s * (1.0f / 64.0f); float q = 0.f;
; #pragma unroll
;                 for (int bj = 0; bj < 2; ++bj)
; #pragma unroll
;                     for (int n = 0; n < 2; ++n) { const f32x4 d = v[ai][bj][m][n] - mw; q += (d[0] * d[0] + d[1] * d[1]) + (d[2] * d[2] + d[3] * d[3]); }
;                 q += __shfl_xor(q, 16); q += __shfl_xor(q, 32);
;                 if (fq == 0) P[(ai * HALF + wr * 64 + m * 16 + fr) * 4 + wc] = (f32x2v){mw, q};
;     __device__ __forceinline__ void fused(f32x4 (&acc)[2][2][4][2], const Unit& u, int wr, int wc, int fr, int fq, PG8_LAS unsigned char* lds, int wid, int lane) const {
;     ...
;             for (int m = 0; m < 4; ++m) { const size_t off = (size_t)(u.pm * BM + ai * HALF + wr * 64 + m * 16 + fr) * ldc + col0;
; #pragma unroll
;                 for (int bj = 0; bj < 2; ++bj) { f32x4 b0, b1;
;                     if (base) { b0 = *(const f32x4*)(base + off + bj * HALF); b1 = *(const f32x4*)(base + off + bj * HALF + 4); }
;                     else { const u32x4 w = *(const u32x4*)(baseb + off + bj * HALF);
;                         b0 = (f32x4){__uint_as_float(w.x << 16), __uint_as_float(w.x & 0xffff0000u), __uint_as_float(w.y << 16), __uint_as_float(w.y & 0xffff0000u)};
;                         b1 = (f32x4){__uint_as_float(w.z << 16), __uint_as_float(w.z & 0xffff0000u), __uint_as_float(w.w << 16), __uint_as_float(w.w & 0xffff0000u)}; }
;                     acc[ai][bj][m][0] = acc[ai][bj][m][0] * s + b0 * alpha; acc[ai][bj][m][1] = acc[ai][bj][m][1] * s + b1 * alpha; }
	v_add_f32_e32 v135, v135, v136
	s_waitcnt vmcnt(1)
	v_lshlrev_b32_e32 v146, 16, v232
	v_and_b32_e32 v147, 0xffff0000, v232
	v_lshlrev_b32_e32 v138, 16, v233
	v_and_b32_e32 v139, 0xffff0000, v233
	v_lshlrev_b32_e32 v148, 16, v234
	v_and_b32_e32 v149, 0xffff0000, v234
	v_lshlrev_b32_e32 v140, 16, v235
	v_and_b32_e32 v141, 0xffff0000, v235
	s_waitcnt vmcnt(0)
	v_lshlrev_b32_e32 v152, 16, v236
	v_and_b32_e32 v153, 0xffff0000, v236
	v_lshlrev_b32_e32 v142, 16, v237
	v_and_b32_e32 v143, 0xffff0000, v237
	v_lshlrev_b32_e32 v154, 16, v238
	v_and_b32_e32 v155, 0xffff0000, v238
	v_lshlrev_b32_e32 v144, 16, v239
	v_and_b32_e32 v145, 0xffff0000, v239
	v_mov_b32_e32 v136, v135
	s_nop 1
	v_permlane32_swap_b32 v135, v136
	v_pk_mul_f32 v[146:147], v[146:147], s[0:1] op_sel_hi:[1,0]
	v_pk_mul_f32 v[138:139], v[138:139], s[0:1] op_sel_hi:[1,0]
	v_pk_mul_f32 v[148:149], v[148:149], s[0:1] op_sel_hi:[1,0]
	v_pk_mul_f32 v[140:141], v[140:141], s[0:1] op_sel_hi:[1,0]
	v_pk_mul_f32 v[152:153], v[152:153], s[0:1] op_sel_hi:[1,0]
	v_pk_mul_f32 v[142:143], v[142:143], s[0:1] op_sel_hi:[1,0]
	v_pk_mul_f32 v[154:155], v[154:155], s[0:1] op_sel_hi:[1,0]
	v_pk_mul_f32 v[144:145], v[144:145], s[0:1] op_sel_hi:[1,0]
	v_pk_fma_f32 v[16:17], v[16:17], 0.5, v[138:139] op_sel_hi:[1,0,1]
	v_pk_fma_f32 v[14:15], v[14:15], 0.5, v[146:147] op_sel_hi:[1,0,1]
	v_pk_fma_f32 v[12:13], v[12:13], 0.5, v[140:141] op_sel_hi:[1,0,1]
	v_pk_fma_f32 v[10:11], v[10:11], 0.5, v[148:149] op_sel_hi:[1,0,1]
	v_pk_fma_f32 v[8:9], v[8:9], 0.5, v[142:143] op_sel_hi:[1,0,1]
	v_pk_fma_f32 v[6:7], v[6:7], 0.5, v[152:153] op_sel_hi:[1,0,1]
	v_pk_fma_f32 v[4:5], v[4:5], 0.5, v[144:145] op_sel_hi:[1,0,1]
	v_pk_fma_f32 v[2:3], v[2:3], 0.5, v[154:155] op_sel_hi:[1,0,1]
	s_lshl_b32 s0, s27, 3
	s_add_i32 s2, s0, 0
	s_and_saveexec_b64 s[0:1], vcc
	s_cbranch_execz .LBB0_1715
	s_lshl_b32 s3, s26, 11
	s_add_i32 s3, s2, s3
	v_mul_f32_e32 v138, 0x3c800000, v133
	v_lshl_add_u32 v133, v151, 5, s3
	s_waitcnt lgkmcnt(0)
	v_add_f32_e32 v139, v135, v136
	ds_write_b64 v133, v[138:139]
.LBB0_1715:
	s_or_b64 exec, exec, s[0:1]
	s_waitcnt lgkmcnt(0)
	v_mov_b32_e32 v136, v95
	v_mov_b32_e32 v137, v96
	v_mov_b32_e32 v138, v94
	v_mov_b32_e32 v139, v97
	v_pk_add_f32 v[136:137], v[136:137], v[138:139]
	v_mov_b32_e32 v138, v119
	v_mov_b32_e32 v139, v120
	v_mov_b32_e32 v140, v118
	v_mov_b32_e32 v141, v121
	v_pk_add_f32 v[138:139], v[138:139], v[140:141]
	v_add_f32_e32 v133, v136, v137
	v_pk_add_f32 v[138:139], v[138:139], v[138:139] op_sel_hi:[0,1]
	v_add_f32_e32 v137, 0, v133
	v_add_f32_e32 v141, v82, v83
	v_add_f32_e32 v143, v84, v85
	v_mov_b32_e32 v140, v86
	v_mov_b32_e32 v142, v87
	v_mov_b32_e32 v138, v88
	v_mov_b32_e32 v136, v89
	v_pk_add_f32 v[140:141], v[140:141], v[142:143]
	v_pk_add_f32 v[136:137], v[138:139], v[136:137]
	s_nop 0
	v_pk_add_f32 v[136:137], v[140:141], v[136:137]
	s_nop 0
	v_add_f32_e32 v133, v136, v137
	v_mov_b32_e32 v135, v133
	s_nop 1
	v_permlane16_swap_b32 v133, v135
	s_waitcnt lgkmcnt(0)
	v_add_f32_e32 v133, v133, v135
	v_mov_b32_e32 v135, v133
	s_nop 1
	v_permlane32_swap_b32 v133, v135
	s_waitcnt lgkmcnt(0)
	v_add_f32_e32 v133, v133, v135
	v_fmamk_f32 v136, v133, 0xbc800000, v97
	v_fmamk_f32 v138, v133, 0xbc800000, v95
	v_fmamk_f32 v135, v133, 0xbc800000, v96
	v_fmamk_f32 v137, v133, 0xbc800000, v94
	v_mul_f32_e32 v138, v138, v138
	v_mul_f32_e32 v136, v136, v136
	v_fmac_f32_e32 v138, v137, v137
	v_fmac_f32_e32 v136, v135, v135
	v_fmamk_f32 v137, v133, 0xbc800000, v121
	v_fmamk_f32 v139, v133, 0xbc800000, v119
	v_add_f32_e32 v135, v138, v136
	v_fmamk_f32 v136, v133, 0xbc800000, v120
	v_fmamk_f32 v138, v133, 0xbc800000, v118
	v_mul_f32_e32 v139, v139, v139
	v_mul_f32_e32 v137, v137, v137
	v_fmac_f32_e32 v139, v138, v138
	v_fmac_f32_e32 v137, v136, v136
	v_add_f32_e32 v136, v139, v137
	v_fmamk_f32 v137, v133, 0xbc800000, v85
	v_fmamk_f32 v139, v133, 0xbc800000, v83
	v_add_f32_e32 v135, v135, v136
	v_fmamk_f32 v136, v133, 0xbc800000, v84
	v_fmamk_f32 v138, v133, 0xbc800000, v82
	v_mul_f32_e32 v139, v139, v139
	v_mul_f32_e32 v137, v137, v137
	v_fmac_f32_e32 v139, v138, v138
	v_fmac_f32_e32 v137, v136, v136
	v_add_f32_e32 v136, v139, v137
	v_fmamk_f32 v137, v133, 0xbc800000, v89
	v_fmamk_f32 v139, v133, 0xbc800000, v87
	v_add_f32_e32 v135, v136, v135
	v_fmamk_f32 v136, v133, 0xbc800000, v88
	v_fmamk_f32 v138, v133, 0xbc800000, v86
	v_mul_f32_e32 v139, v139, v139
	v_mul_f32_e32 v137, v137, v137
	v_fmac_f32_e32 v139, v138, v138
	v_fmac_f32_e32 v137, v136, v136
	v_add_f32_e32 v136, v139, v137
	v_add_f32_e32 v135, v136, v135
	v_mov_b32_e32 v136, v135
	s_nop 1
	v_permlane16_swap_b32 v135, v136
	s_waitcnt lgkmcnt(0)
	v_add_f32_e32 v135, v135, v136
	v_mov_b32_e32 v136, v135
	s_nop 1
	v_permlane32_swap_b32 v135, v136
	s_and_saveexec_b64 s[0:1], vcc
	s_cbranch_execz .LBB0_1717
	s_lshl_b32 s3, s26, 11
	s_add_i32 s3, s2, s3
	v_mul_f32_e32 v138, 0x3c800000, v133
	v_lshl_add_u32 v133, v151, 5, s3
	s_waitcnt lgkmcnt(0)
	v_add_f32_e32 v139, v135, v136
	ds_write_b64 v133, v[138:139] offset:512
;     __device__ __forceinline__ bool run(const f32x4 (&v)[2][2][4][2], const Unit& u, int wr, int wc, int fr, int fq, PG8_LAS unsigned char* lds, int wid, int lane) const {
;     ...
;                 float s = 0.f;
; #pragma unroll
;                 for (int bj = 0; bj < 2; ++bj)
; #pragma unroll
;                     for (int n = 0; n < 2; ++n) { const f32x4 x = v[ai][bj][m][n]; s += (x[0] + x[1]) + (x[2] + x[3]); }
;                 s += __shfl_xor(s, 16); s += __shfl_xor(s, 32);
;                 const float mw = s * (1.0f / 64.0f); float q = 0.f;
; #pragma unroll
;                 for (int bj = 0; bj < 2; ++bj)
; #pragma unroll
;                     for (int n = 0; n < 2; ++n) { const f32x4 d = v[ai][bj][m][n] - mw; q += (d[0] * d[0] + d[1] * d[1]) + (d[2] * d[2] + d[3] * d[3]); }
;                 q += __shfl_xor(q, 16); q += __shfl_xor(q, 32);
;                 if (fq == 0) P[(ai * HALF + wr * 64 + m * 16 + fr) * 4 + wc] = (f32x2v){mw, q};
.LBB0_1717:
	s_or_b64 exec, exec, s[0:1]
	s_waitcnt lgkmcnt(0)
	v_mov_b32_e32 v136, v107
	v_mov_b32_e32 v137, v108
	v_mov_b32_e32 v138, v106
	v_mov_b32_e32 v139, v109
	v_pk_add_f32 v[136:137], v[136:137], v[138:139]
	v_mov_b32_e32 v138, v115
	v_mov_b32_e32 v139, v116
	v_mov_b32_e32 v140, v114
	v_mov_b32_e32 v141, v117
	v_pk_add_f32 v[138:139], v[138:139], v[140:141]
	v_add_f32_e32 v133, v136, v137
	v_pk_add_f32 v[138:139], v[138:139], v[138:139] op_sel_hi:[0,1]
	v_add_f32_e32 v137, 0, v133
	v_add_f32_e32 v141, v90, v91
	v_add_f32_e32 v143, v92, v93
	v_mov_b32_e32 v140, v98
	v_mov_b32_e32 v142, v99
	v_mov_b32_e32 v138, v100
	v_mov_b32_e32 v136, v101
	v_pk_add_f32 v[140:141], v[140:141], v[142:143]
	v_pk_add_f32 v[136:137], v[138:139], v[136:137]
	s_nop 0
	v_pk_add_f32 v[136:137], v[140:141], v[136:137]
	s_nop 0
	v_add_f32_e32 v133, v136, v137
	v_mov_b32_e32 v135, v133
	s_nop 1
	v_permlane16_swap_b32 v133, v135
	s_waitcnt lgkmcnt(0)
	v_add_f32_e32 v133, v133, v135
	v_mov_b32_e32 v135, v133
	s_nop 1
	v_permlane32_swap_b32 v133, v135
	s_waitcnt lgkmcnt(0)
	v_add_f32_e32 v133, v133, v135
	v_fmamk_f32 v136, v133, 0xbc800000, v109
	v_fmamk_f32 v138, v133, 0xbc800000, v107
	v_fmamk_f32 v135, v133, 0xbc800000, v108
	v_fmamk_f32 v137, v133, 0xbc800000, v106
	v_mul_f32_e32 v138, v138, v138
	v_mul_f32_e32 v136, v136, v136
	v_fmac_f32_e32 v138, v137, v137
	v_fmac_f32_e32 v136, v135, v135
	v_fmamk_f32 v137, v133, 0xbc800000, v117
	v_fmamk_f32 v139, v133, 0xbc800000, v115
	v_add_f32_e32 v135, v138, v136
	v_fmamk_f32 v136, v133, 0xbc800000, v116
	v_fmamk_f32 v138, v133, 0xbc800000, v114
	v_mul_f32_e32 v139, v139, v139
	v_mul_f32_e32 v137, v137, v137
	v_fmac_f32_e32 v139, v138, v138
	v_fmac_f32_e32 v137, v136, v136
	v_add_f32_e32 v136, v139, v137
	v_fmamk_f32 v137, v133, 0xbc800000, v93
	v_fmamk_f32 v139, v133, 0xbc800000, v91
	v_add_f32_e32 v135, v135, v136
	v_fmamk_f32 v136, v133, 0xbc800000, v92
	v_fmamk_f32 v138, v133, 0xbc800000, v90
	v_mul_f32_e32 v139, v139, v139
	v_mul_f32_e32 v137, v137, v137
	v_fmac_f32_e32 v139, v138, v138
	v_fmac_f32_e32 v137, v136, v136
	v_add_f32_e32 v136, v139, v137
	v_fmamk_f32 v137, v133, 0xbc800000, v101
	v_fmamk_f32 v139, v133, 0xbc800000, v99
	v_add_f32_e32 v135, v136, v135
	v_fmamk_f32 v136, v133, 0xbc800000, v100
	v_fmamk_f32 v138, v133, 0xbc800000, v98
	v_mul_f32_e32 v139, v139, v139
	v_mul_f32_e32 v137, v137, v137
	v_fmac_f32_e32 v139, v138, v138
	v_fmac_f32_e32 v137, v136, v136
	v_add_f32_e32 v136, v139, v137
	v_add_f32_e32 v135, v136, v135
	v_mov_b32_e32 v136, v135
	s_nop 1
	v_permlane16_swap_b32 v135, v136
	s_waitcnt lgkmcnt(0)
	v_add_f32_e32 v135, v135, v136
	v_mov_b32_e32 v136, v135
	s_nop 1
	v_permlane32_swap_b32 v135, v136
	s_and_saveexec_b64 s[0:1], vcc
	s_cbranch_execz .LBB0_1719
	s_lshl_b32 s3, s26, 11
	s_add_i32 s3, s2, s3
	v_mul_f32_e32 v138, 0x3c800000, v133
	v_lshl_add_u32 v133, v151, 5, s3
	s_waitcnt lgkmcnt(0)
	v_add_f32_e32 v139, v135, v136
	ds_write_b64 v133, v[138:139] offset:1024
.LBB0_1719:
	s_or_b64 exec, exec, s[0:1]
	s_waitcnt lgkmcnt(0)
	v_mov_b32_e32 v136, v123
	v_mov_b32_e32 v137, v124
	v_mov_b32_e32 v138, v122
	v_mov_b32_e32 v139, v125
	v_pk_add_f32 v[136:137], v[136:137], v[138:139]
	v_mov_b32_e32 v138, v127
	v_mov_b32_e32 v139, v128
	v_mov_b32_e32 v140, v126
	v_mov_b32_e32 v141, v129
	v_pk_add_f32 v[138:139], v[138:139], v[140:141]
	v_add_f32_e32 v133, v136, v137
	v_pk_add_f32 v[138:139], v[138:139], v[138:139] op_sel_hi:[0,1]
	v_add_f32_e32 v137, 0, v133
	v_add_f32_e32 v141, v102, v103
	v_add_f32_e32 v143, v104, v105
	v_mov_b32_e32 v140, v110
	v_mov_b32_e32 v142, v111
	v_mov_b32_e32 v138, v112
	v_mov_b32_e32 v136, v113
	v_pk_add_f32 v[140:141], v[140:141], v[142:143]
	v_pk_add_f32 v[136:137], v[138:139], v[136:137]
	s_nop 0
	v_pk_add_f32 v[136:137], v[140:141], v[136:137]
	s_nop 0
	v_add_f32_e32 v133, v136, v137
	v_mov_b32_e32 v135, v133
	s_nop 1
	v_permlane16_swap_b32 v133, v135
	s_waitcnt lgkmcnt(0)
	v_add_f32_e32 v133, v133, v135
	v_mov_b32_e32 v135, v133
	s_nop 1
	v_permlane32_swap_b32 v133, v135
	s_waitcnt lgkmcnt(0)
	v_add_f32_e32 v133, v133, v135
	v_fmamk_f32 v136, v133, 0xbc800000, v125
	v_fmamk_f32 v138, v133, 0xbc800000, v123
	v_fmamk_f32 v135, v133, 0xbc800000, v124
	v_fmamk_f32 v137, v133, 0xbc800000, v122
	v_mul_f32_e32 v138, v138, v138
	v_mul_f32_e32 v136, v136, v136
	v_fmac_f32_e32 v138, v137, v137
	v_fmac_f32_e32 v136, v135, v135
	v_fmamk_f32 v137, v133, 0xbc800000, v129
	v_fmamk_f32 v139, v133, 0xbc800000, v127
	v_add_f32_e32 v135, v138, v136
	v_fmamk_f32 v136, v133, 0xbc800000, v128
	v_fmamk_f32 v138, v133, 0xbc800000, v126
	v_mul_f32_e32 v139, v139, v139
	v_mul_f32_e32 v137, v137, v137
	v_fmac_f32_e32 v139, v138, v138
	v_fmac_f32_e32 v137, v136, v136
	v_add_f32_e32 v136, v139, v137
	v_fmamk_f32 v137, v133, 0xbc800000, v105
	v_fmamk_f32 v139, v133, 0xbc800000, v103
	v_add_f32_e32 v135, v135, v136
	v_fmamk_f32 v136, v133, 0xbc800000, v104
	v_fmamk_f32 v138, v133, 0xbc800000, v102
	v_mul_f32_e32 v139, v139, v139
	v_mul_f32_e32 v137, v137, v137
	v_fmac_f32_e32 v139, v138, v138
	v_fmac_f32_e32 v137, v136, v136
	v_add_f32_e32 v136, v139, v137
	v_fmamk_f32 v137, v133, 0xbc800000, v113
	v_fmamk_f32 v139, v133, 0xbc800000, v111
	v_add_f32_e32 v135, v136, v135
	v_fmamk_f32 v136, v133, 0xbc800000, v112
	v_fmamk_f32 v138, v133, 0xbc800000, v110
	v_mul_f32_e32 v139, v139, v139
	v_mul_f32_e32 v137, v137, v137
	v_fmac_f32_e32 v139, v138, v138
	v_fmac_f32_e32 v137, v136, v136
	v_add_f32_e32 v136, v139, v137
	v_add_f32_e32 v135, v136, v135
	v_mov_b32_e32 v136, v135
	s_nop 1
	v_permlane16_swap_b32 v135, v136
	s_waitcnt lgkmcnt(0)
	v_add_f32_e32 v135, v135, v136
	v_mov_b32_e32 v136, v135
	s_nop 1
	v_permlane32_swap_b32 v135, v136
	s_and_saveexec_b64 s[0:1], vcc
	s_cbranch_execz .LBB0_1721
	s_lshl_b32 s3, s26, 11
	s_add_i32 s3, s2, s3
	v_mul_f32_e32 v138, 0x3c800000, v133
	v_lshl_add_u32 v133, v151, 5, s3
	s_waitcnt lgkmcnt(0)
	v_add_f32_e32 v139, v135, v136
	ds_write_b64 v133, v[138:139] offset:1536
;     __device__ __forceinline__ bool run(const f32x4 (&v)[2][2][4][2], const Unit& u, int wr, int wc, int fr, int fq, PG8_LAS unsigned char* lds, int wid, int lane) const {
;     ...
;                 float s = 0.f;
; #pragma unroll
;                 for (int bj = 0; bj < 2; ++bj)
; #pragma unroll
;                     for (int n = 0; n < 2; ++n) { const f32x4 x = v[ai][bj][m][n]; s += (x[0] + x[1]) + (x[2] + x[3]); }
;                 s += __shfl_xor(s, 16); s += __shfl_xor(s, 32);
;                 const float mw = s * (1.0f / 64.0f); float q = 0.f;
; #pragma unroll
;                 for (int bj = 0; bj < 2; ++bj)
; #pragma unroll
;                     for (int n = 0; n < 2; ++n) { const f32x4 d = v[ai][bj][m][n] - mw; q += (d[0] * d[0] + d[1] * d[1]) + (d[2] * d[2] + d[3] * d[3]); }
;                 q += __shfl_xor(q, 16); q += __shfl_xor(q, 32);
;                 if (fq == 0) P[(ai * HALF + wr * 64 + m * 16 + fr) * 4 + wc] = (f32x2v){mw, q};
.LBB0_1721:
	s_or_b64 exec, exec, s[0:1]
	s_waitcnt lgkmcnt(0)
	v_mov_b32_e32 v136, v63
	v_mov_b32_e32 v137, v64
	v_mov_b32_e32 v138, v62
	v_mov_b32_e32 v139, v65
	v_pk_add_f32 v[136:137], v[136:137], v[138:139]
	v_mov_b32_e32 v138, v59
	v_mov_b32_e32 v139, v60
	v_mov_b32_e32 v140, v58
	v_mov_b32_e32 v141, v61
	v_pk_add_f32 v[138:139], v[138:139], v[140:141]
	v_add_f32_e32 v133, v136, v137
	v_pk_add_f32 v[138:139], v[138:139], v[138:139] op_sel_hi:[0,1]
	v_add_f32_e32 v137, 0, v133
	v_add_f32_e32 v141, v54, v55
	v_add_f32_e32 v143, v56, v57
	v_mov_b32_e32 v140, v50
	v_mov_b32_e32 v142, v51
	v_mov_b32_e32 v138, v52
	v_mov_b32_e32 v136, v53
	v_pk_add_f32 v[140:141], v[140:141], v[142:143]
	v_pk_add_f32 v[136:137], v[138:139], v[136:137]
	s_nop 0
	v_pk_add_f32 v[136:137], v[140:141], v[136:137]
	s_nop 0
	v_add_f32_e32 v133, v136, v137
	v_mov_b32_e32 v135, v133
	s_nop 1
	v_permlane16_swap_b32 v133, v135
	s_waitcnt lgkmcnt(0)
	v_add_f32_e32 v133, v133, v135
	v_mov_b32_e32 v135, v133
	s_nop 1
	v_permlane32_swap_b32 v133, v135
	s_waitcnt lgkmcnt(0)
	v_add_f32_e32 v133, v133, v135
	v_fmamk_f32 v136, v133, 0xbc800000, v65
	v_fmamk_f32 v138, v133, 0xbc800000, v63
	v_fmamk_f32 v135, v133, 0xbc800000, v64
	v_fmamk_f32 v137, v133, 0xbc800000, v62
	v_mul_f32_e32 v138, v138, v138
	v_mul_f32_e32 v136, v136, v136
	v_fmac_f32_e32 v138, v137, v137
	v_fmac_f32_e32 v136, v135, v135
	v_fmamk_f32 v137, v133, 0xbc800000, v61
	v_fmamk_f32 v139, v133, 0xbc800000, v59
	v_add_f32_e32 v135, v138, v136
	v_fmamk_f32 v136, v133, 0xbc800000, v60
	v_fmamk_f32 v138, v133, 0xbc800000, v58
	v_mul_f32_e32 v139, v139, v139
	v_mul_f32_e32 v137, v137, v137
	v_fmac_f32_e32 v139, v138, v138
	v_fmac_f32_e32 v137, v136, v136
	v_add_f32_e32 v136, v139, v137
	v_fmamk_f32 v137, v133, 0xbc800000, v57
	v_fmamk_f32 v139, v133, 0xbc800000, v55
	v_add_f32_e32 v135, v135, v136
	v_fmamk_f32 v136, v133, 0xbc800000, v56
	v_fmamk_f32 v138, v133, 0xbc800000, v54
	v_mul_f32_e32 v139, v139, v139
	v_mul_f32_e32 v137, v137, v137
	v_fmac_f32_e32 v139, v138, v138
	v_fmac_f32_e32 v137, v136, v136
	v_add_f32_e32 v136, v139, v137
	v_fmamk_f32 v137, v133, 0xbc800000, v53
	v_fmamk_f32 v139, v133, 0xbc800000, v51
	v_add_f32_e32 v135, v136, v135
	v_fmamk_f32 v136, v133, 0xbc800000, v52
	v_fmamk_f32 v138, v133, 0xbc800000, v50
	v_mul_f32_e32 v139, v139, v139
	v_mul_f32_e32 v137, v137, v137
	v_fmac_f32_e32 v139, v138, v138
	v_fmac_f32_e32 v137, v136, v136
	v_add_f32_e32 v136, v139, v137
	v_add_f32_e32 v135, v136, v135
	v_mov_b32_e32 v136, v135
	s_nop 1
	v_permlane16_swap_b32 v135, v136
	s_waitcnt lgkmcnt(0)
	v_add_f32_e32 v135, v135, v136
	v_mov_b32_e32 v136, v135
	s_nop 1
	v_permlane32_swap_b32 v135, v136
	s_and_saveexec_b64 s[0:1], vcc
	s_cbranch_execz .LBB0_1723
	s_lshl_b32 s3, s26, 11
	s_add_i32 s3, s2, s3
	v_mul_f32_e32 v138, 0x3c800000, v133
	v_lshl_add_u32 v133, v151, 5, s3
	s_waitcnt lgkmcnt(0)
	v_add_f32_e32 v139, v135, v136
	ds_write_b64 v133, v[138:139] offset:4096
.LBB0_1723:
	s_or_b64 exec, exec, s[0:1]
	s_waitcnt lgkmcnt(0)
	v_mov_b32_e32 v136, v47
	v_mov_b32_e32 v137, v48
	v_mov_b32_e32 v138, v46
	v_mov_b32_e32 v139, v49
	v_pk_add_f32 v[136:137], v[136:137], v[138:139]
	v_mov_b32_e32 v138, v43
	v_mov_b32_e32 v139, v44
	v_mov_b32_e32 v140, v42
	v_mov_b32_e32 v141, v45
	v_pk_add_f32 v[138:139], v[138:139], v[140:141]
	v_add_f32_e32 v133, v136, v137
	v_pk_add_f32 v[138:139], v[138:139], v[138:139] op_sel_hi:[0,1]
	v_add_f32_e32 v137, 0, v133
	v_add_f32_e32 v141, v38, v39
	v_add_f32_e32 v143, v40, v41
	v_mov_b32_e32 v140, v34
	v_mov_b32_e32 v142, v35
	v_mov_b32_e32 v138, v36
	v_mov_b32_e32 v136, v37
	v_pk_add_f32 v[140:141], v[140:141], v[142:143]
	v_pk_add_f32 v[136:137], v[138:139], v[136:137]
	s_nop 0
	v_pk_add_f32 v[136:137], v[140:141], v[136:137]
	s_nop 0
	v_add_f32_e32 v133, v136, v137
	v_mov_b32_e32 v135, v133
	s_nop 1
	v_permlane16_swap_b32 v133, v135
	s_waitcnt lgkmcnt(0)
	v_add_f32_e32 v133, v133, v135
	v_mov_b32_e32 v135, v133
	s_nop 1
	v_permlane32_swap_b32 v133, v135
	s_waitcnt lgkmcnt(0)
	v_add_f32_e32 v133, v133, v135
	v_fmamk_f32 v136, v133, 0xbc800000, v49
	v_fmamk_f32 v138, v133, 0xbc800000, v47
	v_fmamk_f32 v135, v133, 0xbc800000, v48
	v_fmamk_f32 v137, v133, 0xbc800000, v46
	v_mul_f32_e32 v138, v138, v138
	v_mul_f32_e32 v136, v136, v136
	v_fmac_f32_e32 v138, v137, v137
	v_fmac_f32_e32 v136, v135, v135
	v_fmamk_f32 v137, v133, 0xbc800000, v45
	v_fmamk_f32 v139, v133, 0xbc800000, v43
	v_add_f32_e32 v135, v138, v136
	v_fmamk_f32 v136, v133, 0xbc800000, v44
	v_fmamk_f32 v138, v133, 0xbc800000, v42
	v_mul_f32_e32 v139, v139, v139
	v_mul_f32_e32 v137, v137, v137
	v_fmac_f32_e32 v139, v138, v138
	v_fmac_f32_e32 v137, v136, v136
	v_add_f32_e32 v136, v139, v137
	v_fmamk_f32 v137, v133, 0xbc800000, v41
	v_fmamk_f32 v139, v133, 0xbc800000, v39
	v_add_f32_e32 v135, v135, v136
	v_fmamk_f32 v136, v133, 0xbc800000, v40
	v_fmamk_f32 v138, v133, 0xbc800000, v38
	v_mul_f32_e32 v139, v139, v139
	v_mul_f32_e32 v137, v137, v137
	v_fmac_f32_e32 v139, v138, v138
	v_fmac_f32_e32 v137, v136, v136
	v_add_f32_e32 v136, v139, v137
	v_fmamk_f32 v137, v133, 0xbc800000, v37
	v_fmamk_f32 v139, v133, 0xbc800000, v35
	v_add_f32_e32 v135, v136, v135
	v_fmamk_f32 v136, v133, 0xbc800000, v36
	v_fmamk_f32 v138, v133, 0xbc800000, v34
	v_mul_f32_e32 v139, v139, v139
	v_mul_f32_e32 v137, v137, v137
	v_fmac_f32_e32 v139, v138, v138
	v_fmac_f32_e32 v137, v136, v136
	v_add_f32_e32 v136, v139, v137
	v_add_f32_e32 v135, v136, v135
	v_mov_b32_e32 v136, v135
	s_nop 1
	v_permlane16_swap_b32 v135, v136
	s_waitcnt lgkmcnt(0)
	v_add_f32_e32 v135, v135, v136
	v_mov_b32_e32 v136, v135
	s_nop 1
	v_permlane32_swap_b32 v135, v136
	s_and_saveexec_b64 s[0:1], vcc
	s_cbranch_execz .LBB0_1725
	s_lshl_b32 s3, s26, 11
	s_add_i32 s3, s2, s3
	v_mul_f32_e32 v138, 0x3c800000, v133
	v_lshl_add_u32 v133, v151, 5, s3
	s_waitcnt lgkmcnt(0)
	v_add_f32_e32 v139, v135, v136
	ds_write_b64 v133, v[138:139] offset:4608
;     __device__ __forceinline__ bool run(const f32x4 (&v)[2][2][4][2], const Unit& u, int wr, int wc, int fr, int fq, PG8_LAS unsigned char* lds, int wid, int lane) const {
;     ...
;                 float s = 0.f;
; #pragma unroll
;                 for (int bj = 0; bj < 2; ++bj)
; #pragma unroll
;                     for (int n = 0; n < 2; ++n) { const f32x4 x = v[ai][bj][m][n]; s += (x[0] + x[1]) + (x[2] + x[3]); }
;                 s += __shfl_xor(s, 16); s += __shfl_xor(s, 32);
;                 const float mw = s * (1.0f / 64.0f); float q = 0.f;
; #pragma unroll
;                 for (int bj = 0; bj < 2; ++bj)
; #pragma unroll
;                     for (int n = 0; n < 2; ++n) { const f32x4 d = v[ai][bj][m][n] - mw; q += (d[0] * d[0] + d[1] * d[1]) + (d[2] * d[2] + d[3] * d[3]); }
;                 q += __shfl_xor(q, 16); q += __shfl_xor(q, 32);
;                 if (fq == 0) P[(ai * HALF + wr * 64 + m * 16 + fr) * 4 + wc] = (f32x2v){mw, q};
.LBB0_1725:
	s_or_b64 exec, exec, s[0:1]
	s_waitcnt lgkmcnt(0)
	v_mov_b32_e32 v136, v31
	v_mov_b32_e32 v137, v32
	v_mov_b32_e32 v138, v30
	v_mov_b32_e32 v139, v33
	v_pk_add_f32 v[136:137], v[136:137], v[138:139]
	v_mov_b32_e32 v138, v27
	v_mov_b32_e32 v139, v28
	v_mov_b32_e32 v140, v26
	v_mov_b32_e32 v141, v29
	v_pk_add_f32 v[138:139], v[138:139], v[140:141]
	v_add_f32_e32 v133, v136, v137
	v_pk_add_f32 v[138:139], v[138:139], v[138:139] op_sel_hi:[0,1]
	v_add_f32_e32 v137, 0, v133
	v_add_f32_e32 v141, v22, v23
	v_add_f32_e32 v143, v24, v25
	v_mov_b32_e32 v140, v18
	v_mov_b32_e32 v142, v19
	v_mov_b32_e32 v138, v20
	v_mov_b32_e32 v136, v21
	v_pk_add_f32 v[140:141], v[140:141], v[142:143]
	v_pk_add_f32 v[136:137], v[138:139], v[136:137]
	s_nop 0
	v_pk_add_f32 v[136:137], v[140:141], v[136:137]
	s_nop 0
	v_add_f32_e32 v133, v136, v137
	v_mov_b32_e32 v135, v133
	s_nop 1
	v_permlane16_swap_b32 v133, v135
	s_waitcnt lgkmcnt(0)
	v_add_f32_e32 v133, v133, v135
	v_mov_b32_e32 v135, v133
	s_nop 1
	v_permlane32_swap_b32 v133, v135
	s_waitcnt lgkmcnt(0)
	v_add_f32_e32 v133, v133, v135
	v_fmamk_f32 v136, v133, 0xbc800000, v33
	v_fmamk_f32 v138, v133, 0xbc800000, v31
	v_fmamk_f32 v135, v133, 0xbc800000, v32
	v_fmamk_f32 v137, v133, 0xbc800000, v30
	v_mul_f32_e32 v138, v138, v138
	v_mul_f32_e32 v136, v136, v136
	v_fmac_f32_e32 v138, v137, v137
	v_fmac_f32_e32 v136, v135, v135
	v_fmamk_f32 v137, v133, 0xbc800000, v29
	v_fmamk_f32 v139, v133, 0xbc800000, v27
	v_add_f32_e32 v135, v138, v136
	v_fmamk_f32 v136, v133, 0xbc800000, v28
	v_fmamk_f32 v138, v133, 0xbc800000, v26
	v_mul_f32_e32 v139, v139, v139
	v_mul_f32_e32 v137, v137, v137
	v_fmac_f32_e32 v139, v138, v138
	v_fmac_f32_e32 v137, v136, v136
	v_add_f32_e32 v136, v139, v137
	v_fmamk_f32 v137, v133, 0xbc800000, v25
	v_fmamk_f32 v139, v133, 0xbc800000, v23
	v_add_f32_e32 v135, v135, v136
	v_fmamk_f32 v136, v133, 0xbc800000, v24
	v_fmamk_f32 v138, v133, 0xbc800000, v22
	v_mul_f32_e32 v139, v139, v139
	v_mul_f32_e32 v137, v137, v137
	v_fmac_f32_e32 v139, v138, v138
	v_fmac_f32_e32 v137, v136, v136
	v_add_f32_e32 v136, v139, v137
	v_fmamk_f32 v137, v133, 0xbc800000, v21
	v_fmamk_f32 v139, v133, 0xbc800000, v19
	v_add_f32_e32 v135, v136, v135
	v_fmamk_f32 v136, v133, 0xbc800000, v20
	v_fmamk_f32 v138, v133, 0xbc800000, v18
	v_mul_f32_e32 v139, v139, v139
	v_mul_f32_e32 v137, v137, v137
	v_fmac_f32_e32 v139, v138, v138
	v_fmac_f32_e32 v137, v136, v136
	v_add_f32_e32 v136, v139, v137
	v_add_f32_e32 v135, v136, v135
	v_mov_b32_e32 v136, v135
	s_nop 1
	v_permlane16_swap_b32 v135, v136
	s_waitcnt lgkmcnt(0)
	v_add_f32_e32 v135, v135, v136
	v_mov_b32_e32 v136, v135
	s_nop 1
	v_permlane32_swap_b32 v135, v136
	s_and_saveexec_b64 s[0:1], vcc
	s_cbranch_execz .LBB0_1727
	s_lshl_b32 s3, s26, 11
	s_add_i32 s3, s2, s3
	v_mul_f32_e32 v138, 0x3c800000, v133
	v_lshl_add_u32 v133, v151, 5, s3
	s_waitcnt lgkmcnt(0)
	v_add_f32_e32 v139, v135, v136
	ds_write_b64 v133, v[138:139] offset:5120
.LBB0_1727:
	s_or_b64 exec, exec, s[0:1]
	s_waitcnt lgkmcnt(0)
	v_mov_b32_e32 v136, v15
	v_mov_b32_e32 v137, v16
	v_mov_b32_e32 v138, v14
	v_mov_b32_e32 v139, v17
	v_pk_add_f32 v[136:137], v[136:137], v[138:139]
	v_mov_b32_e32 v138, v11
	v_mov_b32_e32 v139, v12
	v_mov_b32_e32 v140, v10
	v_mov_b32_e32 v141, v13
	v_pk_add_f32 v[138:139], v[138:139], v[140:141]
	v_add_f32_e32 v133, v136, v137
	v_pk_add_f32 v[138:139], v[138:139], v[138:139] op_sel_hi:[0,1]
	v_add_f32_e32 v137, 0, v133
	v_add_f32_e32 v141, v6, v7
	v_add_f32_e32 v143, v8, v9
	v_mov_b32_e32 v140, v2
	v_mov_b32_e32 v142, v3
	v_mov_b32_e32 v138, v4
	v_mov_b32_e32 v136, v5
	v_pk_add_f32 v[140:141], v[140:141], v[142:143]
	v_pk_add_f32 v[136:137], v[138:139], v[136:137]
	s_nop 0
	v_pk_add_f32 v[136:137], v[140:141], v[136:137]
	s_nop 0
	v_add_f32_e32 v133, v136, v137
	v_mov_b32_e32 v135, v133
	s_nop 1
	v_permlane16_swap_b32 v133, v135
	s_waitcnt lgkmcnt(0)
	v_add_f32_e32 v133, v133, v135
	v_mov_b32_e32 v135, v133
	s_nop 1
	v_permlane32_swap_b32 v133, v135
	s_waitcnt lgkmcnt(0)
	v_add_f32_e32 v133, v133, v135
	v_fmamk_f32 v136, v133, 0xbc800000, v17
	v_fmamk_f32 v138, v133, 0xbc800000, v15
	v_fmamk_f32 v135, v133, 0xbc800000, v16
	v_fmamk_f32 v137, v133, 0xbc800000, v14
	v_mul_f32_e32 v138, v138, v138
	v_mul_f32_e32 v136, v136, v136
	v_fmac_f32_e32 v138, v137, v137
	v_fmac_f32_e32 v136, v135, v135
	v_fmamk_f32 v137, v133, 0xbc800000, v13
	v_fmamk_f32 v139, v133, 0xbc800000, v11
	v_add_f32_e32 v135, v138, v136
	v_fmamk_f32 v136, v133, 0xbc800000, v12
	v_fmamk_f32 v138, v133, 0xbc800000, v10
	v_mul_f32_e32 v139, v139, v139
	v_mul_f32_e32 v137, v137, v137
	v_fmac_f32_e32 v139, v138, v138
	v_fmac_f32_e32 v137, v136, v136
	v_add_f32_e32 v136, v139, v137
	v_fmamk_f32 v137, v133, 0xbc800000, v9
	v_fmamk_f32 v139, v133, 0xbc800000, v7
	v_add_f32_e32 v135, v135, v136
	v_fmamk_f32 v136, v133, 0xbc800000, v8
	v_fmamk_f32 v138, v133, 0xbc800000, v6
	v_mul_f32_e32 v139, v139, v139
	v_mul_f32_e32 v137, v137, v137
	v_fmac_f32_e32 v139, v138, v138
	v_fmac_f32_e32 v137, v136, v136
	v_add_f32_e32 v136, v139, v137
	v_fmamk_f32 v137, v133, 0xbc800000, v5
	v_fmamk_f32 v139, v133, 0xbc800000, v3
	v_add_f32_e32 v135, v136, v135
	v_fmamk_f32 v136, v133, 0xbc800000, v4
	v_fmamk_f32 v138, v133, 0xbc800000, v2
	v_mul_f32_e32 v139, v139, v139
	v_mul_f32_e32 v137, v137, v137
	v_fmac_f32_e32 v139, v138, v138
	v_fmac_f32_e32 v137, v136, v136
	v_add_f32_e32 v136, v139, v137
	v_add_f32_e32 v135, v136, v135
	v_mov_b32_e32 v1, v135
	s_nop 1
	v_permlane16_swap_b32 v135, v1
	s_waitcnt lgkmcnt(0)
	v_add_f32_e32 v1, v135, v1
	v_mov_b32_e32 v132, v1
	s_nop 1
	v_permlane32_swap_b32 v1, v132
	s_and_saveexec_b64 s[0:1], vcc
	s_cbranch_execz .LBB0_1729
	s_lshl_b32 s3, s26, 11
	s_add_i32 s2, s2, s3
	v_mul_f32_e32 v136, 0x3c800000, v133
	v_lshl_add_u32 v133, v151, 5, s2
	s_waitcnt lgkmcnt(0)
	v_add_f32_e32 v137, v1, v132
	ds_write_b64 v133, v[136:137] offset:5632
